# hints (sc1 GEMM1 stores, nt read-once inputs) + PE GEMM of WGs>=128 moved from phase 3 to the start of their phase 4
# speedup vs baseline: 1.0112x; 1.0112x over previous
_Z10hybrid_fwd6Params:
	s_mov_b32 s98, 0
	s_mov_b32 s96, s2
	s_load_dwordx16 s[64:79], s[0:1], 0x80
	s_load_dwordx2 s[26:27], s[0:1], 0xc0
	s_add_u32 s2, s0, 0xc8
	s_addc_u32 s3, s1, 0
	v_writelane_b32 v254, s2, 0
	s_waitcnt lgkmcnt(0)
	s_add_u32 s4, s78, 0xe810000
	v_writelane_b32 v254, s3, 1
	s_load_dword s3, s[0:1], 0xc8
	s_addc_u32 s5, s79, 0
	v_writelane_b32 v254, s4, 2
	s_sub_i32 s2, s27, s26
	s_cmp_lt_i32 s2, 2
	v_writelane_b32 v254, s5, 3
	s_mov_b32 s2, 0
	v_writelane_b32 v254, s2, 4
	s_cbranch_scc1 .LBB0_7
	v_and_b32_e32 v1, 0x3ff, v0
	v_cmp_gt_u32_e32 vcc, 4, v1
	s_and_saveexec_b64 s[4:5], vcc
	v_lshl_add_u32 v2, v1, 2, 0
	v_add_u32_e32 v2, 0x20000, v2
	v_mov_b32_e32 v3, 0
	ds_write_b32 v2, v3
	s_or_b64 exec, exec, s[4:5]
	s_waitcnt lgkmcnt(0)
	s_barrier
	s_getreg_b32 s2, hwreg(HW_REG_XCC_ID, 0, 4)
	s_and_b32 s2, s2, 15
	v_cmp_eq_u32_e32 vcc, 0, v1
	v_writelane_b32 v254, s2, 4
	s_and_saveexec_b64 s[4:5], vcc
	s_cbranch_execz .LBB0_6
	s_mov_b64 s[6:7], exec
	v_mbcnt_lo_u32_b32 v1, s6, 0
	v_mbcnt_hi_u32_b32 v1, s7, v1
	v_cmp_eq_u32_e32 vcc, 0, v1
	s_and_b64 s[8:9], exec, vcc
	s_mov_b64 exec, s[8:9]
	s_cbranch_execz .LBB0_6
	v_readlane_b32 s2, v254, 4
	s_bcnt1_i32_b64 s6, s[6:7]
	s_lshl_b32 s2, s2, 8
	v_mov_b32_e32 v2, s6
	v_readlane_b32 s6, v254, 2
	v_mov_b32_e32 v1, s2
	v_readlane_b32 s7, v254, 3
	s_nop 4
	global_atomic_add v1, v2, s[6:7] offset:1024

.LBB0_22:
	s_add_i32 s4, s90, 0x100
	s_cmpk_lt_i32 s90, 0x240
	s_cselect_b32 s26, s90, s4
	s_cmpk_gt_i32 s26, 0x7f
	s_mov_b64 s[4:5], -1
	s_cbranch_scc0 .LBB0_33
	s_cmpk_gt_u32 s26, 0x33f
	s_cbranch_scc0 .LBB0_25
	v_lshl_add_u32 v66, s26, 5, v86
	v_lshlrev_b64 v[2:3], 12, v[66:67]
	v_lshl_add_u64 v[2:3], v[68:69], 0, v[2:3]
	global_load_dwordx4 v[30:33], v[2:3], off nt
	global_load_dwordx4 v[18:21], v[2:3], off offset:1024 nt
	global_load_dwordx4 v[6:9], v[2:3], off offset:3072 nt
	global_load_dwordx4 v[10:13], v[2:3], off offset:2048 nt
	v_mov_b32_e32 v83, v67
	v_or_b32_e32 v82, 1, v66
	v_lshlrev_b64 v[2:3], 12, v[82:83]
	v_lshl_add_u64 v[14:15], v[68:69], 0, v[2:3]
	global_load_dwordx4 v[26:29], v[14:15], off nt
	global_load_dwordx4 v[22:25], v[14:15], off offset:1024 nt
	global_load_dwordx4 v[2:5], v[14:15], off offset:3072 nt
	s_nop 0
	global_load_dwordx4 v[14:17], v[14:15], off offset:2048 nt
	v_cmp_lt_i32_e32 vcc, v112, v111
	v_mov_b32_e32 v81, v67
	v_mov_b32_e32 v85, v67
	v_cndmask_b32_e32 v34, v110, v112, vcc
	v_or_b32_e32 v80, 2, v66
	v_or_b32_e32 v84, 3, v66
	v_lshlrev_b32_e32 v77, 2, v34
	v_lshlrev_b64 v[34:35], 12, v[80:81]
	v_lshlrev_b64 v[36:37], 12, v[84:85]
	v_lshl_add_u64 v[34:35], v[68:69], 0, v[34:35]
	v_lshl_add_u64 v[54:55], v[68:69], 0, v[36:37]
	global_load_dwordx4 v[58:61], v[34:35], off nt
	global_load_dwordx4 v[46:49], v[34:35], off offset:1024 nt
	global_load_dwordx4 v[38:41], v[34:35], off offset:2048 nt
	s_nop 0
	global_load_dwordx4 v[34:37], v[34:35], off offset:3072 nt
	s_nop 0
	global_load_dwordx4 v[50:53], v[54:55], off nt
	global_load_dwordx4 v[62:65], v[54:55], off offset:1024 nt
	global_load_dwordx4 v[42:45], v[54:55], off offset:3072 nt
	s_nop 0
	global_load_dwordx4 v[54:57], v[54:55], off offset:2048 nt
	v_cmp_lt_i32_e32 vcc, v113, v111
	s_mov_b32 s4, 0x358637bd
	s_waitcnt vmcnt(15)
	v_pk_mul_f32 v[122:123], v[32:33], v[32:33]
	v_pk_mul_f32 v[124:125], v[30:31], v[30:31]
	s_waitcnt vmcnt(14)
	v_pk_mul_f32 v[126:127], v[20:21], v[20:21]
	v_pk_mul_f32 v[128:129], v[18:19], v[18:19]
	s_waitcnt vmcnt(12)
	v_mul_f32_e32 v130, v11, v11
	v_mul_f32_e32 v132, v13, v13
	v_mul_f32_e32 v145, v8, v8
	v_mul_f32_e32 v146, v9, v9
	v_pk_mov_b32 v[134:135], v[124:125], v[122:123] op_sel:[1,0]
	v_mov_b32_e32 v125, v123
	v_pk_mov_b32 v[122:123], v[128:129], v[126:127] op_sel:[1,0]
	v_mov_b32_e32 v129, v127
	v_pk_fma_f32 v[126:127], v[10:11], v[10:11], v[130:131] op_sel_hi:[1,1,0]
	v_pk_fma_f32 v[130:131], v[12:13], v[12:13], v[132:133] op_sel_hi:[1,1,0]
	s_waitcnt vmcnt(11)
	v_pk_mul_f32 v[132:133], v[28:29], v[28:29]
	v_pk_mul_f32 v[136:137], v[26:27], v[26:27]
	s_waitcnt vmcnt(10)
	v_pk_mul_f32 v[138:139], v[24:25], v[24:25]
	v_pk_mul_f32 v[140:141], v[22:23], v[22:23]
	v_pk_add_f32 v[122:123], v[122:123], v[128:129]
	v_mov_b32_e32 v127, v145
	v_pk_mov_b32 v[128:129], v[136:137], v[132:133] op_sel:[1,0]
	v_mov_b32_e32 v137, v133
	v_pk_mov_b32 v[132:133], v[140:141], v[138:139] op_sel:[1,0]
	v_mov_b32_e32 v141, v139
	v_mov_b32_e32 v131, v146
	v_mul_f32_e32 v143, v7, v7
	s_waitcnt vmcnt(8)
	v_mul_f32_e32 v142, v15, v15
	v_mul_f32_e32 v144, v17, v17
	v_pk_add_f32 v[124:125], v[134:135], v[124:125]
	v_pk_add_f32 v[126:127], v[126:127], v[130:131]
	v_pk_add_f32 v[128:129], v[128:129], v[136:137]
	v_pk_add_f32 v[130:131], v[132:133], v[140:141]
	v_mul_f32_e32 v79, v6, v6
	v_mul_f32_e32 v147, v2, v2
	v_mul_f32_e32 v148, v3, v3
	v_mul_f32_e32 v149, v4, v4
	v_mul_f32_e32 v150, v5, v5
	v_pk_fma_f32 v[134:135], v[14:15], v[14:15], v[142:143] op_sel_hi:[1,1,0]
	v_pk_fma_f32 v[138:139], v[16:17], v[16:17], v[144:145] op_sel_hi:[1,1,0]
	v_pk_add_f32 v[124:125], v[124:125], v[124:125] op_sel:[0,1] op_sel_hi:[1,0]
	v_pk_add_f32 v[122:123], v[122:123], v[122:123] op_sel:[0,1] op_sel_hi:[1,0]
	v_pk_add_f32 v[128:129], v[128:129], v[128:129] op_sel:[0,1] op_sel_hi:[1,0]
	v_pk_add_f32 v[130:131], v[130:131], v[130:131] op_sel:[0,1] op_sel_hi:[1,0]
	v_mov_b32_e32 v135, v149
	v_mov_b32_e32 v139, v150
	v_mov_b32_e32 v125, v79
	v_mov_b32_e32 v123, v143
	v_mov_b32_e32 v129, v147
	v_mov_b32_e32 v131, v148
	v_pk_add_f32 v[132:133], v[134:135], v[138:139]
	v_pk_add_f32 v[122:123], v[124:125], v[122:123]
	v_pk_add_f32 v[124:125], v[128:129], v[130:131]
	v_pk_add_f32 v[122:123], v[122:123], v[126:127]
	v_pk_add_f32 v[124:125], v[124:125], v[132:133]
	v_mov_b32_e32 v127, v122
	v_mov_b32_e32 v126, v124
	v_mov_b32_e32 v122, v125
	v_pk_add_f32 v[122:123], v[126:127], v[122:123]
	ds_bpermute_b32 v125, v77, v123
	ds_bpermute_b32 v124, v77, v122
	v_cndmask_b32_e32 v79, v110, v113, vcc
	v_lshlrev_b32_e32 v79, 2, v79
	v_xor_b32_e32 v130, 4, v110
	v_cmp_lt_i32_e32 vcc, v117, v111
	s_waitcnt lgkmcnt(0)
	v_pk_add_f32 v[122:123], v[122:123], v[124:125]
	ds_bpermute_b32 v125, v79, v123
	ds_bpermute_b32 v124, v79, v122
	v_cndmask_b32_e32 v126, v110, v117, vcc
	v_cmp_lt_i32_e32 vcc, v130, v111
	v_lshlrev_b32_e32 v140, 2, v126
	s_waitcnt vmcnt(2)
	v_pk_mul_f32 v[134:135], v[64:65], v[64:65]
	s_waitcnt lgkmcnt(0)
	v_pk_add_f32 v[126:127], v[122:123], v[124:125]
	v_cndmask_b32_e32 v122, v110, v130, vcc
	v_lshlrev_b32_e32 v142, 2, v122
	v_pk_mul_f32 v[122:123], v[60:61], v[60:61]
	v_pk_mul_f32 v[124:125], v[58:59], v[58:59]
	v_pk_mul_f32 v[136:137], v[62:63], v[62:63]
	v_pk_mov_b32 v[130:131], v[124:125], v[122:123] op_sel:[1,0]
	v_mov_b32_e32 v125, v123
	v_pk_add_f32 v[122:123], v[130:131], v[124:125]
	v_pk_mul_f32 v[124:125], v[48:49], v[48:49]
	v_pk_mul_f32 v[130:131], v[46:47], v[46:47]
	v_pk_add_f32 v[122:123], v[122:123], v[122:123] op_sel:[0,1] op_sel_hi:[1,0]
	v_pk_mov_b32 v[132:133], v[130:131], v[124:125] op_sel:[1,0]
	v_mov_b32_e32 v131, v125
	v_pk_add_f32 v[124:125], v[132:133], v[130:131]
	v_mul_f32_e32 v130, v34, v34
	v_mul_f32_e32 v131, v35, v35
	v_pk_add_f32 v[124:125], v[124:125], v[124:125] op_sel:[0,1] op_sel_hi:[1,0]
	v_mov_b32_e32 v123, v130
	v_mov_b32_e32 v125, v131
	v_pk_add_f32 v[122:123], v[122:123], v[124:125]
	v_mul_f32_e32 v124, v39, v39
	v_mul_f32_e32 v130, v41, v41
	v_mul_f32_e32 v132, v36, v36
	v_mul_f32_e32 v133, v37, v37
	v_pk_fma_f32 v[124:125], v[38:39], v[38:39], v[124:125] op_sel_hi:[1,1,0]
	v_pk_fma_f32 v[130:131], v[40:41], v[40:41], v[130:131] op_sel_hi:[1,1,0]
	v_mov_b32_e32 v125, v132
	v_mov_b32_e32 v131, v133
	v_pk_add_f32 v[124:125], v[124:125], v[130:131]
	v_pk_mov_b32 v[138:139], v[136:137], v[134:135] op_sel:[1,0]
	v_pk_add_f32 v[130:131], v[122:123], v[124:125]
	v_pk_mul_f32 v[122:123], v[52:53], v[52:53]
	v_pk_mul_f32 v[124:125], v[50:51], v[50:51]
	v_mov_b32_e32 v137, v135
	v_pk_mov_b32 v[132:133], v[124:125], v[122:123] op_sel:[1,0]
	v_mov_b32_e32 v125, v123
	v_pk_add_f32 v[132:133], v[132:133], v[124:125]
	global_load_dwordx4 v[122:125], v[70:71], off nt
	v_pk_add_f32 v[134:135], v[138:139], v[136:137]
	v_pk_add_f32 v[132:133], v[132:133], v[132:133] op_sel:[0,1] op_sel_hi:[1,0]
	v_pk_add_f32 v[134:135], v[134:135], v[134:135] op_sel:[0,1] op_sel_hi:[1,0]
	s_waitcnt vmcnt(2)
	v_mul_f32_e32 v133, v42, v42
	v_mul_f32_e32 v135, v43, v43
	v_pk_add_f32 v[132:133], v[132:133], v[134:135]
	s_waitcnt vmcnt(1)
	v_mul_f32_e32 v134, v55, v55
	v_mul_f32_e32 v136, v57, v57
	v_pk_fma_f32 v[134:135], v[54:55], v[54:55], v[134:135] op_sel_hi:[1,1,0]
	v_pk_fma_f32 v[136:137], v[56:57], v[56:57], v[136:137] op_sel_hi:[1,1,0]
	v_mul_f32_e32 v135, v44, v44
	v_mul_f32_e32 v137, v45, v45
	v_pk_add_f32 v[134:135], v[134:135], v[136:137]
	ds_bpermute_b32 v129, v140, v127
	v_pk_add_f32 v[132:133], v[132:133], v[134:135]
	v_mov_b32_e32 v135, v130
	v_mov_b32_e32 v134, v132
	v_mov_b32_e32 v130, v133
	v_pk_add_f32 v[130:131], v[134:135], v[130:131]
	ds_bpermute_b32 v133, v77, v131
	ds_bpermute_b32 v132, v77, v130
	ds_bpermute_b32 v128, v140, v126
	v_xor_b32_e32 v141, 2, v110
	v_cmp_lt_i32_e32 vcc, v141, v111
	v_xor_b32_e32 v77, 1, v110
	s_waitcnt lgkmcnt(1)
	v_pk_add_f32 v[130:131], v[130:131], v[132:133]
	ds_bpermute_b32 v133, v79, v131
	ds_bpermute_b32 v132, v79, v130
	s_waitcnt lgkmcnt(2)
	v_pk_add_f32 v[126:127], v[126:127], v[128:129]
	ds_bpermute_b32 v129, v142, v127
	ds_bpermute_b32 v128, v142, v126
	v_cndmask_b32_e32 v79, v110, v141, vcc
	s_waitcnt lgkmcnt(2)
	v_pk_add_f32 v[130:131], v[130:131], v[132:133]
	ds_bpermute_b32 v133, v140, v131
	ds_bpermute_b32 v132, v140, v130
	v_lshlrev_b32_e32 v79, 2, v79
	s_waitcnt lgkmcnt(2)
	v_pk_add_f32 v[126:127], v[126:127], v[128:129]
	ds_bpermute_b32 v129, v79, v127
	ds_bpermute_b32 v128, v79, v126
	s_waitcnt lgkmcnt(2)
	v_pk_add_f32 v[130:131], v[130:131], v[132:133]
	ds_bpermute_b32 v133, v142, v131
	ds_bpermute_b32 v132, v142, v130
	v_cmp_lt_i32_e32 vcc, v77, v111
	s_waitcnt lgkmcnt(2)
	v_pk_add_f32 v[126:127], v[126:127], v[128:129]
	v_mov_b64_e32 v[134:135], s[4:5]
	v_cndmask_b32_e32 v77, v110, v77, vcc
	v_lshlrev_b32_e32 v77, 2, v77
	ds_bpermute_b32 v129, v77, v127
	ds_bpermute_b32 v128, v77, v126
	s_waitcnt lgkmcnt(2)
	v_pk_add_f32 v[130:131], v[130:131], v[132:133]
	ds_bpermute_b32 v133, v79, v131
	ds_bpermute_b32 v132, v79, v130
	s_waitcnt lgkmcnt(2)
	v_pk_add_f32 v[126:127], v[126:127], v[128:129]
	s_nop 0
	v_pk_fma_f32 v[126:127], v[126:127], s[54:55], v[134:135] op_sel_hi:[1,0,0]
	s_waitcnt lgkmcnt(0)
	v_pk_add_f32 v[128:129], v[130:131], v[132:133]
	v_mul_f32_e32 v79, 0x4b800000, v127
	v_cmp_gt_f32_e32 vcc, s2, v127
	ds_bpermute_b32 v131, v77, v129
	ds_bpermute_b32 v130, v77, v128
	v_cndmask_b32_e32 v77, v127, v79, vcc
	v_rsq_f32_e32 v77, v77
	v_mul_f32_e32 v136, 0x4b800000, v126
	v_cmp_gt_f32_e64 s[4:5], s2, v126
	s_nop 1
	v_cndmask_b32_e64 v79, v126, v136, s[4:5]
	s_waitcnt lgkmcnt(0)
	v_pk_add_f32 v[126:127], v[128:129], v[130:131]
	v_mul_f32_e32 v128, 0x45800000, v77
	v_cndmask_b32_e32 v128, v77, v128, vcc
	v_pk_mul_f32 v[30:31], v[30:31], v[128:129] op_sel_hi:[1,0]
	v_pk_mul_f32 v[32:33], v[32:33], v[128:129] op_sel_hi:[1,0]
	v_rsq_f32_e32 v79, v79
	v_pk_fma_f32 v[126:127], v[126:127], s[54:55], v[134:135] op_sel_hi:[1,0,0]
	v_pk_mul_f32 v[18:19], v[18:19], v[128:129] op_sel_hi:[1,0]
	v_mul_f32_e32 v77, 0x4b800000, v127
	v_cmp_gt_f32_e32 vcc, s2, v127
	v_cmp_gt_f32_e64 s[6:7], s2, v126
	s_waitcnt vmcnt(0)
	v_pk_mul_f32 v[32:33], v[32:33], v[124:125]
	v_pk_mul_f32 v[30:31], v[30:31], v[122:123]
	v_cndmask_b32_e32 v77, v127, v77, vcc
	v_cvt_pk_bf16_f32 v30, v30, v31
	v_cvt_pk_bf16_f32 v31, v32, v33
	v_lshlrev_b64 v[32:33], 11, v[66:67]
	v_lshl_add_u64 v[32:33], v[74:75], 0, v[32:33]
	global_store_dwordx2 v[32:33], v[30:31], off
	v_mul_f32_e32 v30, 0x45800000, v79
	v_mul_f32_e32 v127, 0x4b800000, v126
	v_cndmask_b32_e64 v30, v79, v30, s[4:5]
	v_cndmask_b32_e64 v126, v126, v127, s[6:7]
	v_pk_mul_f32 v[26:27], v[26:27], v[30:31] op_sel_hi:[1,0]
	v_pk_mul_f32 v[28:29], v[28:29], v[30:31] op_sel_hi:[1,0]
	v_rsq_f32_e32 v31, v77
	v_rsq_f32_e32 v77, v126
	v_pk_mul_f32 v[28:29], v[28:29], v[124:125]
	v_pk_mul_f32 v[26:27], v[26:27], v[122:123]
	v_pk_mul_f32 v[20:21], v[20:21], v[128:129] op_sel_hi:[1,0]
	v_cvt_pk_bf16_f32 v26, v26, v27
	v_cvt_pk_bf16_f32 v27, v28, v29
	v_mul_f32_e32 v28, 0x45800000, v31
	v_cndmask_b32_e32 v66, v31, v28, vcc
	v_mul_f32_e32 v28, 0x45800000, v77
	v_cndmask_b32_e64 v126, v77, v28, s[6:7]
	v_lshlrev_b64 v[28:29], 11, v[82:83]
	v_lshl_add_u64 v[82:83], v[74:75], 0, v[28:29]
	global_store_dwordx2 v[82:83], v[26:27], off
	v_pk_mul_f32 v[26:27], v[58:59], v[66:67] op_sel_hi:[1,0]
	v_pk_mul_f32 v[28:29], v[60:61], v[66:67] op_sel_hi:[1,0]
	v_pk_mul_f32 v[26:27], v[122:123], v[26:27]
	v_pk_mul_f32 v[28:29], v[124:125], v[28:29]
	v_cvt_pk_bf16_f32 v26, v26, v27
	v_cvt_pk_bf16_f32 v27, v28, v29
	v_lshlrev_b64 v[28:29], 11, v[80:81]
	v_lshl_add_u64 v[58:59], v[74:75], 0, v[28:29]
	global_store_dwordx2 v[58:59], v[26:27], off
	v_pk_mul_f32 v[26:27], v[50:51], v[126:127] op_sel_hi:[1,0]
	v_pk_mul_f32 v[28:29], v[52:53], v[126:127] op_sel_hi:[1,0]
	v_pk_mul_f32 v[26:27], v[122:123], v[26:27]
	v_pk_mul_f32 v[28:29], v[124:125], v[28:29]
	v_cvt_pk_bf16_f32 v26, v26, v27
	v_cvt_pk_bf16_f32 v27, v28, v29
	v_lshlrev_b64 v[28:29], 11, v[84:85]
	v_lshl_add_u64 v[50:51], v[74:75], 0, v[28:29]
	global_store_dwordx2 v[50:51], v[26:27], off
	global_load_dwordx4 v[26:29], v[70:71], off offset:1024 nt
	v_pk_mul_f32 v[10:11], v[10:11], v[128:129] op_sel_hi:[1,0]
	v_pk_mul_f32 v[12:13], v[12:13], v[128:129] op_sel_hi:[1,0]
	v_pk_mul_f32 v[14:15], v[14:15], v[30:31] op_sel_hi:[1,0]
	v_pk_mul_f32 v[16:17], v[16:17], v[30:31] op_sel_hi:[1,0]
	v_pk_mul_f32 v[6:7], v[6:7], v[128:129] op_sel_hi:[1,0]
	v_pk_mul_f32 v[8:9], v[8:9], v[128:129] op_sel_hi:[1,0]
	v_pk_mul_f32 v[2:3], v[2:3], v[30:31] op_sel_hi:[1,0]
	v_pk_mul_f32 v[4:5], v[4:5], v[30:31] op_sel_hi:[1,0]
	s_mov_b64 s[4:5], 0
	s_waitcnt vmcnt(0)
	v_pk_mul_f32 v[20:21], v[20:21], v[28:29]
	v_pk_mul_f32 v[18:19], v[18:19], v[26:27]
	s_nop 0
	v_cvt_pk_bf16_f32 v18, v18, v19
	v_cvt_pk_bf16_f32 v19, v20, v21
	global_store_dwordx2 v[32:33], v[18:19], off offset:512
	v_pk_mul_f32 v[18:19], v[22:23], v[30:31] op_sel_hi:[1,0]
	v_pk_mul_f32 v[20:21], v[24:25], v[30:31] op_sel_hi:[1,0]
	v_pk_mul_f32 v[18:19], v[18:19], v[26:27]
	v_pk_mul_f32 v[20:21], v[20:21], v[28:29]
	v_cvt_pk_bf16_f32 v18, v18, v19
	v_cvt_pk_bf16_f32 v19, v20, v21
	global_store_dwordx2 v[82:83], v[18:19], off offset:512
	v_pk_mul_f32 v[18:19], v[46:47], v[66:67] op_sel_hi:[1,0]
	v_pk_mul_f32 v[20:21], v[48:49], v[66:67] op_sel_hi:[1,0]
	v_pk_mul_f32 v[18:19], v[26:27], v[18:19]
	v_pk_mul_f32 v[20:21], v[28:29], v[20:21]
	v_cvt_pk_bf16_f32 v18, v18, v19
	v_cvt_pk_bf16_f32 v19, v20, v21
	global_store_dwordx2 v[58:59], v[18:19], off offset:512
	v_pk_mul_f32 v[18:19], v[62:63], v[126:127] op_sel_hi:[1,0]
	v_pk_mul_f32 v[20:21], v[64:65], v[126:127] op_sel_hi:[1,0]
	v_pk_mul_f32 v[18:19], v[26:27], v[18:19]
	v_pk_mul_f32 v[20:21], v[28:29], v[20:21]
	v_cvt_pk_bf16_f32 v18, v18, v19
	v_cvt_pk_bf16_f32 v19, v20, v21
	global_store_dwordx2 v[50:51], v[18:19], off offset:512
	global_load_dwordx4 v[18:21], v[70:71], off offset:2048 nt
	s_waitcnt vmcnt(0)
	v_pk_mul_f32 v[12:13], v[12:13], v[20:21]
	v_pk_mul_f32 v[10:11], v[10:11], v[18:19]
	v_pk_mul_f32 v[16:17], v[16:17], v[20:21]
	v_cvt_pk_bf16_f32 v10, v10, v11
	v_cvt_pk_bf16_f32 v11, v12, v13
	global_store_dwordx2 v[32:33], v[10:11], off offset:1024
	v_pk_mul_f32 v[10:11], v[14:15], v[18:19]
	v_pk_mul_f32 v[12:13], v[40:41], v[66:67] op_sel_hi:[1,0]
	v_cvt_pk_bf16_f32 v10, v10, v11
	v_cvt_pk_bf16_f32 v11, v16, v17
	global_store_dwordx2 v[82:83], v[10:11], off offset:1024
	v_pk_mul_f32 v[10:11], v[38:39], v[66:67] op_sel_hi:[1,0]
	v_pk_mul_f32 v[12:13], v[12:13], v[20:21]
	v_pk_mul_f32 v[10:11], v[10:11], v[18:19]
	v_pk_mul_f32 v[14:15], v[34:35], v[66:67] op_sel_hi:[1,0]
	v_cvt_pk_bf16_f32 v10, v10, v11
	v_cvt_pk_bf16_f32 v11, v12, v13
	global_store_dwordx2 v[58:59], v[10:11], off offset:1024
	v_pk_mul_f32 v[10:11], v[54:55], v[126:127] op_sel_hi:[1,0]
	v_pk_mul_f32 v[12:13], v[56:57], v[126:127] op_sel_hi:[1,0]
	v_pk_mul_f32 v[10:11], v[18:19], v[10:11]
	v_pk_mul_f32 v[12:13], v[20:21], v[12:13]
	v_cvt_pk_bf16_f32 v10, v10, v11
	v_cvt_pk_bf16_f32 v11, v12, v13
	global_store_dwordx2 v[50:51], v[10:11], off offset:1024
	global_load_dwordx4 v[10:13], v[70:71], off offset:3072 nt
	v_pk_mul_f32 v[16:17], v[36:37], v[66:67] op_sel_hi:[1,0]
	v_pk_mul_f32 v[18:19], v[42:43], v[126:127] op_sel_hi:[1,0]
	v_pk_mul_f32 v[20:21], v[44:45], v[126:127] op_sel_hi:[1,0]
	s_waitcnt vmcnt(0)
	v_pk_mul_f32 v[8:9], v[8:9], v[12:13]
	v_pk_mul_f32 v[6:7], v[6:7], v[10:11]
	v_pk_mul_f32 v[4:5], v[4:5], v[12:13]
	v_pk_mul_f32 v[2:3], v[2:3], v[10:11]
	v_pk_mul_f32 v[16:17], v[16:17], v[12:13]
	v_pk_mul_f32 v[14:15], v[14:15], v[10:11]
	v_pk_mul_f32 v[12:13], v[20:21], v[12:13]
	v_pk_mul_f32 v[10:11], v[18:19], v[10:11]
	v_cvt_pk_bf16_f32 v6, v6, v7
	v_cvt_pk_bf16_f32 v7, v8, v9
	v_cvt_pk_bf16_f32 v2, v2, v3
	v_cvt_pk_bf16_f32 v3, v4, v5
	v_cvt_pk_bf16_f32 v4, v14, v15
	v_cvt_pk_bf16_f32 v5, v16, v17
	v_cvt_pk_bf16_f32 v8, v10, v11
	v_cvt_pk_bf16_f32 v9, v12, v13
	global_store_dwordx2 v[32:33], v[6:7], off offset:1536
	global_store_dwordx2 v[82:83], v[2:3], off offset:1536
	global_store_dwordx2 v[58:59], v[4:5], off offset:1536
	global_store_dwordx2 v[50:51], v[8:9], off offset:1536

.LBB0_65:
	global_load_dword v6, v[2:3], off nt
	v_lshl_add_u64 v[2:3], v[2:3], 0, s[12:13]
	v_lshl_add_u64 v[4:5], v[2:3], 0, s[12:13]
	global_load_dword v7, v[2:3], off nt
	global_load_dword v8, v[4:5], off nt
	v_lshl_add_u64 v[2:3], v[4:5], 0, s[12:13]
	v_lshl_add_u64 v[4:5], v[2:3], 0, s[12:13]
	global_load_dword v9, v[2:3], off nt
	global_load_dword v10, v[4:5], off nt
	v_lshl_add_u64 v[2:3], v[4:5], 0, s[12:13]
	v_lshl_add_u64 v[4:5], v[2:3], 0, s[12:13]
	global_load_dword v11, v[2:3], off nt
	global_load_dword v12, v[4:5], off nt
	v_lshl_add_u64 v[2:3], v[4:5], 0, s[12:13]
	v_lshl_add_u64 v[4:5], v[2:3], 0, s[12:13]
	global_load_dword v13, v[2:3], off nt
	global_load_dword v14, v[4:5], off nt
	v_lshl_add_u64 v[2:3], v[4:5], 0, s[12:13]
	v_lshl_add_u64 v[4:5], v[2:3], 0, s[12:13]
	global_load_dword v15, v[2:3], off nt
	global_load_dword v16, v[4:5], off nt
	v_lshl_add_u64 v[2:3], v[4:5], 0, s[12:13]
	global_load_dword v4, v[2:3], off nt
	v_lshl_add_u64 v[2:3], v[2:3], 0, s[12:13]
	global_load_dword v5, v[2:3], off nt
	v_lshl_add_u64 v[2:3], v[2:3], 0, s[12:13]
	global_load_dword v17, v[2:3], off nt
	v_lshl_add_u64 v[2:3], v[2:3], 0, s[12:13]
	global_load_dword v18, v[2:3], off nt
	v_lshl_add_u64 v[2:3], v[2:3], 0, s[12:13]
	global_load_dword v19, v[2:3], off nt
	v_or_b32_e32 v20, s9, v87
	s_movk_i32 s19, 0x104
	s_movk_i32 s9, 0x80
	s_and_b64 vcc, exec, s[6:7]
	s_mov_b64 s[6:7], 0
	v_mad_u32_u24 v20, v20, s19, v88
	v_lshl_add_u64 v[2:3], v[2:3], 0, s[12:13]
	s_waitcnt vmcnt(15)
	ds_write_b32 v20, v6
	s_waitcnt vmcnt(14)
	ds_write_b32 v20, v7 offset:2080
	s_waitcnt vmcnt(13)
	ds_write_b32 v20, v8 offset:4160
	s_waitcnt vmcnt(12)
	ds_write_b32 v20, v9 offset:6240
	s_waitcnt vmcnt(11)
	ds_write_b32 v20, v10 offset:8320
	s_waitcnt vmcnt(10)
	ds_write_b32 v20, v11 offset:10400
	s_waitcnt vmcnt(9)
	ds_write_b32 v20, v12 offset:12480
	s_waitcnt vmcnt(8)
	ds_write_b32 v20, v13 offset:14560
	s_waitcnt vmcnt(7)
	ds_write_b32 v20, v14 offset:16640
	s_waitcnt vmcnt(6)
	ds_write_b32 v20, v15 offset:18720
	s_waitcnt vmcnt(5)
	ds_write_b32 v20, v16 offset:20800
	s_waitcnt vmcnt(4)
	ds_write_b32 v20, v4 offset:22880
	s_waitcnt vmcnt(3)
	ds_write_b32 v20, v5 offset:24960
	s_waitcnt vmcnt(2)
	ds_write_b32 v20, v17 offset:27040
	s_waitcnt vmcnt(1)
	ds_write_b32 v20, v18 offset:29120
	s_waitcnt vmcnt(0)
	ds_write_b32 v20, v19 offset:31200
	s_cbranch_vccnz .LBB0_65
	s_waitcnt lgkmcnt(0)
	s_barrier
	ds_read2_b32 v[6:7], v90 offset1:32
	v_add_u32_e32 v2, 0x400, v91
	ds_read2_b32 v[8:9], v2 offset0:4 offset1:36
	ds_read2_b32 v[10:11], v90 offset0:65 offset1:97
	ds_read2_b32 v[12:13], v2 offset0:69 offset1:101
	ds_read2_b32 v[14:15], v90 offset0:130 offset1:162
	ds_read2_b32 v[16:17], v90 offset0:195 offset1:227
	ds_read2_b32 v[18:19], v2 offset0:134 offset1:166
	ds_read2_b32 v[20:21], v2 offset0:199 offset1:231
	s_lshl_b32 s6, s8, 1
	ds_read2_b32 v[26:27], v93 offset1:65
	s_waitcnt lgkmcnt(6)
	v_cvt_pk_bf16_f32 v2, v6, v10
	v_or_b32_e32 v6, s18, v89
	v_mul_u32_u24_e32 v66, s27, v6
	v_add_u32_e32 v6, 0x400, v94
	ds_read2_b32 v[28:29], v93 offset0:130 offset1:195
	ds_read2_b32 v[30:31], v6 offset0:4 offset1:69
	ds_read2_b32 v[32:33], v6 offset0:134 offset1:199
	s_add_u32 s4, s4, s6
	s_addc_u32 s5, s5, 0
	v_mov_b32_e32 v79, v67
	v_lshl_add_u64 v[22:23], s[4:5], 0, v[78:79]
	v_or_b32_e32 v6, s18, v92
	s_waitcnt lgkmcnt(6)
	v_cvt_pk_bf16_f32 v3, v14, v16
	v_cvt_pk_bf16_f32 v4, v8, v12
	s_waitcnt lgkmcnt(4)
	v_cvt_pk_bf16_f32 v5, v18, v20
	v_lshl_add_u64 v[24:25], v[66:67], 1, v[22:23]
	v_mul_u32_u24_e32 v66, s27, v6
	global_store_dwordx4 v[24:25], v[2:5], off
	v_lshl_add_u64 v[24:25], v[66:67], 1, v[22:23]
	v_add_u32_e32 v14, 0x400, v98
	s_waitcnt lgkmcnt(3)
	v_cvt_pk_bf16_f32 v2, v26, v27
	s_waitcnt lgkmcnt(2)
	v_cvt_pk_bf16_f32 v3, v28, v29
	s_waitcnt lgkmcnt(1)
	v_cvt_pk_bf16_f32 v4, v30, v31
	s_waitcnt lgkmcnt(0)
	v_cvt_pk_bf16_f32 v5, v32, v33
	global_store_dwordx4 v[24:25], v[2:5], off
	v_or_b32_e32 v6, s18, v95
	v_mul_u32_u24_e32 v66, s27, v6
	v_cvt_pk_bf16_f32 v2, v7, v11
	v_cvt_pk_bf16_f32 v3, v15, v17
	v_cvt_pk_bf16_f32 v4, v9, v13
	ds_read2_b32 v[8:9], v97 offset1:65
	ds_read2_b32 v[10:11], v97 offset0:130 offset1:195
	ds_read2_b32 v[12:13], v14 offset0:4 offset1:69
	ds_read2_b32 v[14:15], v14 offset0:134 offset1:199
	v_cvt_pk_bf16_f32 v5, v19, v21
	v_lshl_add_u64 v[6:7], v[66:67], 1, v[22:23]
	global_store_dwordx4 v[6:7], v[2:5], off
	v_add_u32_e32 v6, s18, v96
	v_mul_hi_u32_u24_e32 v7, s27, v6
	v_mul_u32_u24_e32 v6, s27, v6
	s_waitcnt lgkmcnt(3)
	v_cvt_pk_bf16_f32 v2, v8, v9
	s_waitcnt lgkmcnt(2)
	v_cvt_pk_bf16_f32 v3, v10, v11
	s_waitcnt lgkmcnt(1)
	v_cvt_pk_bf16_f32 v4, v12, v13
	s_waitcnt lgkmcnt(0)
	v_cvt_pk_bf16_f32 v5, v14, v15
	v_lshl_add_u64 v[6:7], v[6:7], 1, v[22:23]
	global_store_dwordx4 v[6:7], v[2:5], off
	s_barrier

.LBB0_68:
	s_ashr_i32 s58, s26, 2
	s_and_b32 s12, s26, 3
	s_and_saveexec_b64 s[60:61], s[0:1]
	s_cbranch_execz .LBB0_83
	s_ashr_i32 s59, s58, 31
	v_readlane_b32 s16, v254, 5
	s_lshl_b64 s[4:5], s[58:59], 2
	v_readlane_b32 s28, v254, 17
	v_readlane_b32 s29, v254, 18
	s_add_u32 s4, s28, s4
	s_addc_u32 s5, s29, s5
	global_load_dword v8, v67, s[4:5] nt
	v_lshl_or_b32 v2, s58, 6, v1
	v_ashrrev_i32_e32 v3, 31, v2
	v_readlane_b32 s26, v254, 15
	v_readlane_b32 s27, v254, 16
	v_lshlrev_b64 v[6:7], 2, v[2:3]
	v_readlane_b32 s24, v254, 13
	v_lshl_add_u64 v[4:5], s[26:27], 0, v[6:7]
	global_load_dword v4, v[4:5], off nt
	v_readlane_b32 s25, v254, 14
	s_brev_b32 s4, 18
	v_readlane_b32 s17, v254, 6
	v_lshl_add_u64 v[6:7], s[24:25], 0, v[6:7]
	global_load_dword v6, v[6:7], off nt
	v_readlane_b32 s18, v254, 7
	v_readlane_b32 s19, v254, 8
	v_readlane_b32 s20, v254, 9
	v_readlane_b32 s21, v254, 10
	v_readlane_b32 s22, v254, 11
	v_readlane_b32 s23, v254, 12
	v_readlane_b32 s30, v254, 19
	v_readlane_b32 s31, v254, 20
	s_waitcnt vmcnt(2)
	v_mul_f32_e32 v5, 0x3fb8aa3b, v8
	v_fma_f32 v7, v8, s91, -v5
	v_rndne_f32_e32 v9, v5
	v_fmac_f32_e32 v7, 0x32a5705f, v8
	v_sub_f32_e32 v5, v5, v9
	v_add_f32_e32 v5, v5, v7
	v_cvt_i32_f32_e32 v9, v9
	v_exp_f32_e32 v5, v5
	v_cmp_ngt_f32_e32 vcc, s82, v8
	v_ldexp_f32 v5, v5, v9
	s_nop 0
	v_cndmask_b32_e32 v5, 0, v5, vcc
	v_cmp_nlt_f32_e32 vcc, s55, v8
	s_nop 1
	v_cndmask_b32_e32 v8, v118, v5, vcc
	s_waitcnt vmcnt(1)
	v_mul_f32_e32 v5, v8, v4
	v_and_b32_e32 v7, 0x7fffffff, v5
	v_lshrrev_b32_e32 v9, 23, v7
	v_and_b32_e32 v10, 0x7fffff, v7
	v_cmp_nlt_f32_e64 s[62:63], |v5|, s4
	v_add_u32_e32 v12, 0xffffff88, v9
	v_or_b32_e32 v11, 0x800000, v10
	s_and_saveexec_b64 s[4:5], s[62:63]
	s_xor_b64 s[26:27], exec, s[4:5]
	s_cbranch_execz .LBB0_71
	s_mov_b32 s8, 0xfe5163ab
	v_mad_u64_u32 v[14:15], s[8:9], v11, s8, 0
	v_mov_b32_e32 v66, v15
	s_mov_b32 s8, 0x3c439041
	v_mad_u64_u32 v[16:17], s[8:9], v11, s8, v[66:67]
	v_mov_b32_e32 v66, v17
	v_mad_u64_u32 v[18:19], s[8:9], v11, s83, v[66:67]
	v_cmp_lt_u32_e32 vcc, 63, v12
	v_mov_b32_e32 v66, v19
	v_mad_u64_u32 v[20:21], s[8:9], v11, s84, v[66:67]
	v_cndmask_b32_e32 v9, 0, v119, vcc
	v_add_u32_e32 v9, v9, v12
	v_mov_b32_e32 v66, v21
	v_cmp_lt_u32_e64 s[4:5], 31, v9
	v_mad_u64_u32 v[22:23], s[8:9], v11, s85, v[66:67]
	s_nop 0
	v_cndmask_b32_e64 v10, 0, v120, s[4:5]
	v_mov_b32_e32 v66, v23
	v_add_u32_e32 v9, v10, v9
	v_mad_u64_u32 v[24:25], s[8:9], v11, s86, v[66:67]
	v_cmp_lt_u32_e64 s[6:7], 31, v9
	v_mov_b32_e32 v66, v25
	v_mad_u64_u32 v[26:27], s[8:9], v11, s87, v[66:67]
	v_cndmask_b32_e64 v10, 0, v120, s[6:7]
	v_add_u32_e32 v9, v10, v9
	v_cndmask_b32_e32 v10, v24, v20, vcc
	v_cndmask_b32_e32 v13, v26, v22, vcc
	v_cndmask_b32_e32 v17, v27, v24, vcc
	v_cndmask_b32_e64 v15, v13, v10, s[4:5]
	v_cndmask_b32_e64 v13, v17, v13, s[4:5]
	v_cndmask_b32_e32 v17, v22, v18, vcc
	v_cndmask_b32_e64 v10, v10, v17, s[4:5]
	v_cndmask_b32_e64 v13, v13, v15, s[6:7]
	v_cndmask_b32_e64 v15, v15, v10, s[6:7]
	v_sub_u32_e32 v19, 32, v9
	v_alignbit_b32 v21, v13, v15, v19
	v_cmp_eq_u32_e64 s[8:9], 0, v9
	v_cndmask_b32_e32 v14, v18, v14, vcc
	s_nop 0
	v_cndmask_b32_e64 v9, v21, v13, s[8:9]
	v_cndmask_b32_e32 v13, v20, v16, vcc
	v_cndmask_b32_e64 v16, v17, v13, s[4:5]
	v_cndmask_b32_e64 v10, v10, v16, s[6:7]
	v_alignbit_b32 v17, v15, v10, v19
	v_cndmask_b32_e64 v13, v13, v14, s[4:5]
	v_cndmask_b32_e64 v15, v17, v15, s[8:9]
	v_bfe_u32 v21, v9, 29, 1
	v_cndmask_b32_e64 v13, v16, v13, s[6:7]
	v_alignbit_b32 v17, v9, v15, 30
	v_sub_u32_e32 v22, 0, v21
	v_alignbit_b32 v14, v10, v13, v19
	v_xor_b32_e32 v17, v17, v22
	v_cndmask_b32_e64 v10, v14, v10, s[8:9]
	v_alignbit_b32 v14, v15, v10, 30
	v_ffbh_u32_e32 v15, v17
	v_min_u32_e32 v15, 32, v15
	v_alignbit_b32 v10, v10, v13, 30
	v_xor_b32_e32 v14, v14, v22
	v_sub_u32_e32 v16, 31, v15
	v_xor_b32_e32 v10, v10, v22
	v_alignbit_b32 v17, v17, v14, v16
	v_alignbit_b32 v10, v14, v10, v16
	v_alignbit_b32 v13, v17, v10, 9
	v_ffbh_u32_e32 v14, v13
	v_min_u32_e32 v14, 32, v14
	v_lshrrev_b32_e32 v20, 29, v9
	v_not_b32_e32 v16, v14
	v_alignbit_b32 v10, v13, v10, v16
	v_lshlrev_b32_e32 v13, 31, v20
	v_or_b32_e32 v16, 0x33000000, v13
	v_add_lshl_u32 v14, v14, v15, 23
	v_lshrrev_b32_e32 v10, 9, v10
	v_sub_u32_e32 v14, v16, v14
	v_or_b32_e32 v13, 0.5, v13
	v_lshlrev_b32_e32 v15, 23, v15
	v_or_b32_e32 v10, v14, v10
	v_lshrrev_b32_e32 v14, 9, v17
	v_sub_u32_e32 v13, v13, v15
	v_or_b32_e32 v13, v14, v13
	v_mul_f32_e32 v14, 0x3fc90fda, v13
	v_fma_f32 v15, v13, s88, -v14
	v_fmac_f32_e32 v15, 0x33a22168, v13
	v_fmac_f32_e32 v15, 0x3fc90fda, v10
	v_lshrrev_b32_e32 v9, 30, v9
	v_add_f32_e32 v10, v14, v15
	v_add_u32_e32 v9, v21, v9

.LBB0_84:
	global_load_dword v8, v[2:3], off nt
	global_load_dword v9, v[4:5], off nt
	v_add_co_u32_e32 v6, vcc, 0x200, v6
	s_xor_b64 s[6:7], vcc, -1
	s_and_b64 s[6:7], exec, s[6:7]
	v_lshl_add_u64 v[2:3], v[2:3], 0, s[56:57]
	v_lshl_add_u64 v[4:5], v[4:5], 0, s[56:57]
	s_or_b64 s[4:5], s[6:7], s[4:5]
	s_waitcnt vmcnt(0)
	ds_write_b64 v7, v[8:9]
	v_add_u32_e32 v7, 0x1000, v7
	s_andn2_b64 exec, exec, s[4:5]
	s_cbranch_execnz .LBB0_84
	s_or_b64 exec, exec, s[4:5]
	s_lshl_b32 s8, s12, 2
	v_or_b32_e32 v2, s8, v100
	v_cmp_eq_u32_e32 vcc, v2, v228
	v_lshl_or_b32 v2, s58, 4, v2
	v_readlane_b32 s16, v254, 21
	v_ashrrev_i32_e32 v3, 31, v2
	v_readlane_b32 s22, v254, 27
	v_readlane_b32 s23, v254, 28
	v_lshl_add_u32 v4, s12, 11, v107
	s_mov_b32 s6, 0
	v_lshl_add_u64 v[2:3], v[2:3], 2, s[22:23]
	v_mov_b32_e32 v5, v109
	s_waitcnt lgkmcnt(0)
	s_barrier
	v_readlane_b32 s17, v254, 22
	v_readlane_b32 s18, v254, 23
	v_readlane_b32 s19, v254, 24
	v_readlane_b32 s20, v254, 25
	v_readlane_b32 s21, v254, 26
	v_readlane_b32 s24, v254, 29
	v_readlane_b32 s25, v254, 30
	v_readlane_b32 s26, v254, 31
	v_readlane_b32 s27, v254, 32
	v_readlane_b32 s28, v254, 33
	v_readlane_b32 s29, v254, 34
	v_readlane_b32 s30, v254, 35
	v_readlane_b32 s31, v254, 36
	s_branch .LBB0_87

.LBB0_88:
	v_add_u32_e32 v9, s4, v4
	ds_read2_b64 v[10:13], v7 offset1:33
	ds_read2_b64 v[14:17], v8 offset1:16
	ds_read2_b64 v[18:21], v7 offset0:66 offset1:99
	ds_read2_b64 v[22:25], v8 offset0:32 offset1:48
	ds_read_b128 v[26:29], v9
	ds_read_b128 v[30:33], v9 offset:16
	s_add_i32 s4, s4, 32
	v_add_u32_e32 v8, 0x200, v8
	v_add_u32_e32 v7, 0x420, v7
	s_waitcnt lgkmcnt(1)
	v_pk_mul_f32 v[34:35], v[26:27], v[10:11] op_sel:[1,1] op_sel_hi:[0,1]
	v_pk_mul_f32 v[36:37], v[28:29], v[12:13] op_sel:[1,1] op_sel_hi:[0,1]
	v_pk_fma_f32 v[42:43], v[26:27], v[10:11], v[34:35] neg_lo:[0,0,1] neg_hi:[0,0,1]
	v_pk_fma_f32 v[10:11], v[26:27], v[10:11], v[34:35] op_sel_hi:[1,0,1]
	s_waitcnt lgkmcnt(0)
	v_pk_mul_f32 v[38:39], v[30:31], v[18:19] op_sel:[1,1] op_sel_hi:[0,1]
	v_pk_fma_f32 v[26:27], v[28:29], v[12:13], v[36:37] neg_lo:[0,0,1] neg_hi:[0,0,1]
	v_pk_fma_f32 v[12:13], v[28:29], v[12:13], v[36:37] op_sel_hi:[1,0,1]
	v_mov_b32_e32 v43, v11
	v_pk_mul_f32 v[40:41], v[32:33], v[20:21] op_sel:[1,1] op_sel_hi:[0,1]
	v_pk_fma_f32 v[28:29], v[30:31], v[18:19], v[38:39] neg_lo:[0,0,1] neg_hi:[0,0,1]
	v_pk_fma_f32 v[18:19], v[30:31], v[18:19], v[38:39] op_sel_hi:[1,0,1]
	v_mov_b32_e32 v27, v13
	v_pk_mul_f32 v[10:11], v[14:15], v[42:43]
	v_pk_fma_f32 v[30:31], v[32:33], v[20:21], v[40:41] neg_lo:[0,0,1] neg_hi:[0,0,1]
	v_pk_fma_f32 v[20:21], v[32:33], v[20:21], v[40:41] op_sel_hi:[1,0,1]
	v_mov_b32_e32 v29, v19
	v_pk_mul_f32 v[12:13], v[16:17], v[26:27]
	v_sub_f32_e32 v9, v10, v11
	v_mov_b32_e32 v31, v21
	v_pk_mul_f32 v[14:15], v[22:23], v[28:29]
	v_sub_f32_e32 v10, v12, v13
	v_add_f32_e32 v6, v6, v9
	v_pk_mul_f32 v[16:17], v[24:25], v[30:31]
	v_sub_f32_e32 v11, v14, v15
	v_add_f32_e32 v6, v6, v10
	v_sub_f32_e32 v12, v16, v17
	v_add_f32_e32 v6, v6, v11
	s_cmpk_eq_i32 s4, 0x200
	v_add_f32_e32 v6, v6, v12
	s_cbranch_scc0 .LBB0_88
	v_lshl_add_u32 v7, s6, 9, v1
	v_cmp_gt_u32_e64 s[4:5], 64, v7
	s_and_b64 s[18:19], vcc, s[4:5]
	s_and_saveexec_b64 s[4:5], s[18:19]
	s_cbranch_execz .LBB0_86
	global_load_dword v8, v[2:3], off nt
	s_waitcnt vmcnt(0)
	v_add_f32_e32 v6, v6, v8
	s_branch .LBB0_86

.LBB0_166:
	s_lshl_b32 s17, s89, 8
	s_add_i32 s17, s17, s61
	v_or_b32_e32 v152, s17, v1
	s_cmp_gt_i32 s88, 1
	s_mov_b64 s[18:19], -1
	s_cbranch_scc0 .LBB0_181
	s_cmp_gt_u32 s88, 3
	s_cbranch_scc0 .LBB0_177
	s_cmp_gt_u32 s88, 11
	s_cbranch_scc0 .LBB0_174
	s_cmp_gt_u32 s88, 19
	s_cbranch_scc0 .LBB0_171
	s_cmp_lt_u32 s88, 24
	s_cselect_b64 s[18:19], -1, 0
	s_and_b64 s[18:19], s[18:19], exec
	s_movk_i32 s18, 0xffec
	s_cselect_b32 s21, s18, 0xffffffe8
	s_mov_b32 s18, 0x8600000
	s_cselect_b32 s18, s18, 0xa600000
	s_add_u32 s18, s78, s18
	s_addc_u32 s19, s79, 0
	s_add_i32 s21, s21, s88
	v_lshl_or_b32 v166, s21, 8, v159
	v_ashrrev_i32_e32 v153, 31, v152
	v_lshlrev_b64 v[154:155], 11, v[152:153]
	v_ashrrev_i32_e32 v167, 31, v166
	v_lshl_add_u64 v[168:169], s[18:19], 0, v[154:155]
	v_lshlrev_b64 v[166:167], 1, v[166:167]
	v_cvt_pk_bf16_f32 v154, v126, v127
	v_cvt_pk_bf16_f32 v155, v128, v129
	v_cvt_pk_bf16_f32 v156, v122, v123
	v_cvt_pk_bf16_f32 v157, v124, v125
	v_lshl_add_u64 v[168:169], v[168:169], 0, v[166:167]
	global_store_dwordx4 v[168:169], v[154:157], off sc1
	s_nop 1
	v_cvt_pk_bf16_f32 v154, v110, v111
	v_cvt_pk_bf16_f32 v155, v112, v113
	v_cvt_pk_bf16_f32 v156, v106, v107
	v_cvt_pk_bf16_f32 v157, v108, v109
	global_store_dwordx4 v[168:169], v[154:157], off offset:256 sc1
	s_nop 1
	v_or_b32_e32 v154, 16, v152
	v_ashrrev_i32_e32 v155, 31, v154
	v_lshlrev_b64 v[154:155], 11, v[154:155]
	v_lshl_add_u64 v[170:171], s[18:19], 0, v[154:155]
	v_cvt_pk_bf16_f32 v154, v118, v119
	v_cvt_pk_bf16_f32 v155, v120, v121
	v_cvt_pk_bf16_f32 v156, v114, v115
	v_cvt_pk_bf16_f32 v157, v116, v117
	v_lshl_add_u64 v[170:171], v[170:171], 0, v[166:167]
	global_store_dwordx4 v[170:171], v[154:157], off sc1
	s_nop 1
	v_cvt_pk_bf16_f32 v154, v94, v95
	v_cvt_pk_bf16_f32 v155, v96, v97
	v_cvt_pk_bf16_f32 v156, v90, v91
	v_cvt_pk_bf16_f32 v157, v92, v93
	global_store_dwordx4 v[170:171], v[154:157], off offset:256 sc1
	s_nop 1
	v_or_b32_e32 v154, 32, v152
	v_ashrrev_i32_e32 v155, 31, v154
	v_lshlrev_b64 v[154:155], 11, v[154:155]
	v_lshl_add_u64 v[170:171], s[18:19], 0, v[154:155]
	v_cvt_pk_bf16_f32 v154, v102, v103
	v_cvt_pk_bf16_f32 v155, v104, v105
	v_cvt_pk_bf16_f32 v156, v98, v99
	v_cvt_pk_bf16_f32 v157, v100, v101
	v_lshl_add_u64 v[170:171], v[170:171], 0, v[166:167]
	global_store_dwordx4 v[170:171], v[154:157], off sc1
	s_nop 1
	v_cvt_pk_bf16_f32 v154, v78, v79
	v_cvt_pk_bf16_f32 v155, v80, v81
	v_cvt_pk_bf16_f32 v156, v74, v75
	v_cvt_pk_bf16_f32 v157, v76, v77
	global_store_dwordx4 v[170:171], v[154:157], off offset:256 sc1
	s_nop 1
	v_or_b32_e32 v154, 48, v152
	v_ashrrev_i32_e32 v155, 31, v154
	v_lshlrev_b64 v[154:155], 11, v[154:155]
	v_lshl_add_u64 v[170:171], s[18:19], 0, v[154:155]
	v_cvt_pk_bf16_f32 v154, v86, v87
	v_cvt_pk_bf16_f32 v155, v88, v89
	v_cvt_pk_bf16_f32 v156, v82, v83
	v_cvt_pk_bf16_f32 v157, v84, v85
	v_lshl_add_u64 v[166:167], v[170:171], 0, v[166:167]
	global_store_dwordx4 v[166:167], v[154:157], off sc1
	v_add_co_u32_e32 v170, vcc, s84, v168
	s_nop 0
	v_cvt_pk_bf16_f32 v154, v70, v71
	v_cvt_pk_bf16_f32 v155, v72, v73
	v_cvt_pk_bf16_f32 v156, v66, v67
	v_cvt_pk_bf16_f32 v157, v68, v69
	global_store_dwordx4 v[166:167], v[154:157], off offset:256 sc1
	s_mov_b64 s[18:19], 0x40000
	v_addc_co_u32_e32 v171, vcc, 0, v169, vcc
	v_cvt_pk_bf16_f32 v154, v62, v63
	v_cvt_pk_bf16_f32 v155, v64, v65
	v_cvt_pk_bf16_f32 v156, v58, v59
	v_cvt_pk_bf16_f32 v157, v60, v61
	v_lshl_add_u64 v[166:167], v[168:169], 0, s[18:19]
	global_store_dwordx4 v[170:171], v[154:157], off sc1
	v_add_co_u32_e32 v170, vcc, s85, v168
	s_nop 0
	v_cvt_pk_bf16_f32 v154, v46, v47
	v_cvt_pk_bf16_f32 v155, v48, v49
	v_cvt_pk_bf16_f32 v156, v42, v43
	v_cvt_pk_bf16_f32 v157, v44, v45
	global_store_dwordx4 v[166:167], v[154:157], off offset:256 sc1
	s_mov_b64 s[18:19], 0x48000
	v_addc_co_u32_e32 v171, vcc, 0, v169, vcc
	v_cvt_pk_bf16_f32 v154, v54, v55
	v_cvt_pk_bf16_f32 v155, v56, v57
	v_cvt_pk_bf16_f32 v156, v50, v51
	v_cvt_pk_bf16_f32 v157, v52, v53
	v_lshl_add_u64 v[166:167], v[168:169], 0, s[18:19]
	global_store_dwordx4 v[170:171], v[154:157], off sc1
	v_add_co_u32_e32 v170, vcc, s86, v168
	s_nop 0
	v_cvt_pk_bf16_f32 v154, v30, v31
	v_cvt_pk_bf16_f32 v155, v32, v33
	v_cvt_pk_bf16_f32 v156, v26, v27
	v_cvt_pk_bf16_f32 v157, v28, v29
	global_store_dwordx4 v[166:167], v[154:157], off offset:256 sc1
	s_mov_b64 s[18:19], 0x50000
	v_addc_co_u32_e32 v171, vcc, 0, v169, vcc
	v_cvt_pk_bf16_f32 v154, v38, v39
	v_cvt_pk_bf16_f32 v155, v40, v41
	v_cvt_pk_bf16_f32 v156, v34, v35
	v_cvt_pk_bf16_f32 v157, v36, v37
	v_lshl_add_u64 v[166:167], v[168:169], 0, s[18:19]
	global_store_dwordx4 v[170:171], v[154:157], off sc1
	s_mov_b64 s[18:19], 0x58000
	s_nop 0
	v_cvt_pk_bf16_f32 v154, v14, v15
	v_cvt_pk_bf16_f32 v155, v16, v17
	v_cvt_pk_bf16_f32 v156, v10, v11
	v_cvt_pk_bf16_f32 v157, v12, v13
	global_store_dwordx4 v[166:167], v[154:157], off offset:256 sc1
	v_lshl_add_u64 v[166:167], v[168:169], 0, s[18:19]
	s_mov_b32 s18, 0x58000
	v_add_co_u32_e32 v168, vcc, s18, v168
	v_cvt_pk_bf16_f32 v154, v22, v23
	v_cvt_pk_bf16_f32 v155, v24, v25
	v_cvt_pk_bf16_f32 v156, v18, v19
	v_cvt_pk_bf16_f32 v157, v20, v21
	v_addc_co_u32_e32 v169, vcc, 0, v169, vcc
	global_store_dwordx4 v[168:169], v[154:157], off sc1
	s_mov_b64 s[18:19], 0
	s_nop 0
	v_cvt_pk_bf16_f32 v154, v6, v7
	v_cvt_pk_bf16_f32 v155, v8, v9
	v_cvt_pk_bf16_f32 v156, v2, v3
	v_cvt_pk_bf16_f32 v157, v4, v5
	global_store_dwordx4 v[166:167], v[154:157], off offset:256 sc1
.LBB0_171:
	s_andn2_b64 vcc, exec, s[18:19]
	s_cbranch_vccnz .LBB0_173
	v_mul_f32_e32 v138, 0xbfb8aa3b, v110
	v_exp_f32_e32 v151, v138
	v_mul_f32_e32 v138, 0xbfb8aa3b, v111
	v_exp_f32_e32 v153, v138
	v_mul_f32_e32 v155, 0xbfb8aa3b, v113
	v_add_f32_e32 v151, 1.0, v151
	v_rcp_f32_e32 v154, v151
	v_add_f32_e32 v151, 1.0, v153
	v_mul_f32_e32 v153, 0xbfb8aa3b, v112
	v_exp_f32_e32 v153, v153
	v_exp_f32_e32 v157, v155
	v_rcp_f32_e32 v155, v151
	v_mul_f32_e32 v167, 0xbfb8aa3b, v109
	v_add_f32_e32 v151, 1.0, v153
	v_rcp_f32_e32 v156, v151
	v_add_f32_e32 v151, 1.0, v157
	v_rcp_f32_e32 v157, v151
	v_mul_f32_e32 v151, 0xbfb8aa3b, v106
	v_exp_f32_e32 v151, v151
	v_mul_f32_e32 v153, 0xbfb8aa3b, v107
	v_exp_f32_e32 v153, v153
	v_exp_f32_e32 v169, v167
	v_add_f32_e32 v151, 1.0, v151
	v_rcp_f32_e32 v166, v151
	v_add_f32_e32 v151, 1.0, v153
	v_mul_f32_e32 v153, 0xbfb8aa3b, v108
	v_exp_f32_e32 v153, v153
	v_rcp_f32_e32 v167, v151
	v_pk_mul_f32 v[156:157], v[112:113], v[156:157]
	v_lshl_add_u32 v138, s88, 7, v160
	v_add_f32_e32 v151, 1.0, v153
	v_rcp_f32_e32 v168, v151
	v_add_f32_e32 v151, 1.0, v169
	v_rcp_f32_e32 v169, v151
	v_pk_mul_f32 v[156:157], v[128:129], v[156:157]
	v_pk_mul_f32 v[166:167], v[106:107], v[166:167]
	v_pk_mul_f32 v[154:155], v[110:111], v[154:155]
	v_pk_mul_f32 v[168:169], v[108:109], v[168:169]
	v_mul_f32_e32 v151, 0xbfb8aa3b, v95
	v_pk_mul_f32 v[170:171], v[124:125], v[168:169]
	v_pk_mul_f32 v[168:169], v[122:123], v[166:167]
	v_cvt_pk_bf16_f32 v167, v156, v157
	v_lshlrev_b64 v[156:157], 1, v[138:139]
	v_mul_f32_e32 v138, 0xbfb8aa3b, v94
	v_exp_f32_e32 v138, v138
	v_pk_mul_f32 v[154:155], v[126:127], v[154:155]
	v_ashrrev_i32_e32 v153, 31, v152
	v_exp_f32_e32 v151, v151
	v_cvt_pk_bf16_f32 v166, v154, v155
	v_lshlrev_b64 v[154:155], 11, v[152:153]
	v_lshl_add_u64 v[154:155], s[10:11], 0, v[154:155]
	v_cvt_pk_bf16_f32 v168, v168, v169
	v_cvt_pk_bf16_f32 v169, v170, v171
	v_lshl_add_u64 v[154:155], v[154:155], 0, v[156:157]
	v_add_f32_e32 v138, 1.0, v138
	global_store_dwordx4 v[154:155], v[166:169], off sc1
	v_mul_f32_e32 v153, 0xbfb8aa3b, v97
	v_exp_f32_e32 v153, v153
	v_rcp_f32_e32 v166, v138
	v_add_f32_e32 v138, 1.0, v151
	v_mul_f32_e32 v151, 0xbfb8aa3b, v96
	v_exp_f32_e32 v151, v151
	v_rcp_f32_e32 v167, v138
	v_or_b32_e32 v170, 16, v152
	v_ashrrev_i32_e32 v171, 31, v170
	v_add_f32_e32 v138, 1.0, v151
	v_rcp_f32_e32 v168, v138
	v_add_f32_e32 v138, 1.0, v153
	v_rcp_f32_e32 v169, v138
	v_mul_f32_e32 v138, 0xbfb8aa3b, v90
	v_exp_f32_e32 v138, v138
	v_mul_f32_e32 v151, 0xbfb8aa3b, v91
	v_exp_f32_e32 v151, v151
	v_mul_f32_e32 v153, 0xbfb8aa3b, v93
	v_add_f32_e32 v138, 1.0, v138
	v_rcp_f32_e32 v172, v138
	v_add_f32_e32 v138, 1.0, v151
	v_mul_f32_e32 v151, 0xbfb8aa3b, v92
	v_exp_f32_e32 v151, v151
	v_exp_f32_e32 v153, v153
	v_rcp_f32_e32 v173, v138
	v_pk_mul_f32 v[166:167], v[94:95], v[166:167]
	v_add_f32_e32 v138, 1.0, v151
	v_rcp_f32_e32 v174, v138
	v_add_f32_e32 v138, 1.0, v153
	v_rcp_f32_e32 v175, v138
	v_mul_f32_e32 v138, 0xbfb8aa3b, v78
	v_exp_f32_e32 v138, v138
	v_mul_f32_e32 v151, 0xbfb8aa3b, v79
	v_exp_f32_e32 v151, v151
	v_pk_mul_f32 v[168:169], v[96:97], v[168:169]
	v_pk_mul_f32 v[172:173], v[90:91], v[172:173]
	v_pk_mul_f32 v[174:175], v[92:93], v[174:175]
	v_lshlrev_b64 v[170:171], 11, v[170:171]
	v_pk_mul_f32 v[168:169], v[120:121], v[168:169]
	v_pk_mul_f32 v[166:167], v[118:119], v[166:167]
	v_pk_mul_f32 v[174:175], v[116:117], v[174:175]
	v_pk_mul_f32 v[172:173], v[114:115], v[172:173]
	v_lshl_add_u64 v[170:171], s[10:11], 0, v[170:171]
	v_cvt_pk_bf16_f32 v166, v166, v167
	v_cvt_pk_bf16_f32 v167, v168, v169
	v_cvt_pk_bf16_f32 v168, v172, v173
	v_cvt_pk_bf16_f32 v169, v174, v175
	v_lshl_add_u64 v[170:171], v[170:171], 0, v[156:157]
	v_add_f32_e32 v138, 1.0, v138
	global_store_dwordx4 v[170:171], v[166:169], off sc1
	v_mul_f32_e32 v153, 0xbfb8aa3b, v81
	v_exp_f32_e32 v153, v153
	v_rcp_f32_e32 v166, v138
	v_add_f32_e32 v138, 1.0, v151
	v_mul_f32_e32 v151, 0xbfb8aa3b, v80
	v_exp_f32_e32 v151, v151
	v_rcp_f32_e32 v167, v138
	v_or_b32_e32 v170, 32, v152
	v_ashrrev_i32_e32 v171, 31, v170
	v_add_f32_e32 v138, 1.0, v151
	v_rcp_f32_e32 v168, v138
	v_add_f32_e32 v138, 1.0, v153
	v_rcp_f32_e32 v169, v138
	v_mul_f32_e32 v138, 0xbfb8aa3b, v74
	v_exp_f32_e32 v138, v138
	v_mul_f32_e32 v151, 0xbfb8aa3b, v75
	v_exp_f32_e32 v151, v151
	v_mul_f32_e32 v153, 0xbfb8aa3b, v77
	v_add_f32_e32 v138, 1.0, v138
	v_rcp_f32_e32 v172, v138
	v_add_f32_e32 v138, 1.0, v151
	v_mul_f32_e32 v151, 0xbfb8aa3b, v76
	v_exp_f32_e32 v151, v151
	v_exp_f32_e32 v153, v153
	v_rcp_f32_e32 v173, v138
	v_pk_mul_f32 v[166:167], v[78:79], v[166:167]
	v_add_f32_e32 v138, 1.0, v151
	v_rcp_f32_e32 v174, v138
	v_add_f32_e32 v138, 1.0, v153
	v_rcp_f32_e32 v175, v138
	v_mul_f32_e32 v138, 0xbfb8aa3b, v70
	v_exp_f32_e32 v138, v138
	v_mul_f32_e32 v151, 0xbfb8aa3b, v71
	v_exp_f32_e32 v151, v151
	v_pk_mul_f32 v[168:169], v[80:81], v[168:169]
	v_pk_mul_f32 v[172:173], v[74:75], v[172:173]
	v_pk_mul_f32 v[174:175], v[76:77], v[174:175]
	v_lshlrev_b64 v[170:171], 11, v[170:171]
	v_pk_mul_f32 v[168:169], v[104:105], v[168:169]
	v_pk_mul_f32 v[166:167], v[102:103], v[166:167]
	v_pk_mul_f32 v[174:175], v[100:101], v[174:175]
	v_pk_mul_f32 v[172:173], v[98:99], v[172:173]
	v_lshl_add_u64 v[170:171], s[10:11], 0, v[170:171]
	v_cvt_pk_bf16_f32 v166, v166, v167
	v_cvt_pk_bf16_f32 v167, v168, v169
	v_cvt_pk_bf16_f32 v168, v172, v173
	v_cvt_pk_bf16_f32 v169, v174, v175
	v_lshl_add_u64 v[170:171], v[170:171], 0, v[156:157]
	v_add_f32_e32 v138, 1.0, v138
	global_store_dwordx4 v[170:171], v[166:169], off sc1
	v_mul_f32_e32 v153, 0xbfb8aa3b, v73
	v_exp_f32_e32 v153, v153
	v_rcp_f32_e32 v166, v138
	v_add_f32_e32 v138, 1.0, v151
	v_mul_f32_e32 v151, 0xbfb8aa3b, v72
	v_exp_f32_e32 v151, v151
	v_rcp_f32_e32 v167, v138
	v_or_b32_e32 v170, 48, v152
	v_ashrrev_i32_e32 v171, 31, v170
	v_add_f32_e32 v138, 1.0, v151
	v_rcp_f32_e32 v168, v138
	v_add_f32_e32 v138, 1.0, v153
	v_rcp_f32_e32 v169, v138
	v_mul_f32_e32 v138, 0xbfb8aa3b, v66
	v_exp_f32_e32 v138, v138
	v_mul_f32_e32 v151, 0xbfb8aa3b, v67
	v_exp_f32_e32 v151, v151
	v_mul_f32_e32 v153, 0xbfb8aa3b, v69
	v_add_f32_e32 v138, 1.0, v138
	v_rcp_f32_e32 v172, v138
	v_add_f32_e32 v138, 1.0, v151
	v_mul_f32_e32 v151, 0xbfb8aa3b, v68
	v_exp_f32_e32 v151, v151
	v_exp_f32_e32 v153, v153
	v_rcp_f32_e32 v173, v138
	v_pk_mul_f32 v[166:167], v[70:71], v[166:167]
	v_add_f32_e32 v138, 1.0, v151
	v_rcp_f32_e32 v174, v138
	v_add_f32_e32 v138, 1.0, v153
	v_rcp_f32_e32 v175, v138
	v_mul_f32_e32 v138, 0xbfb8aa3b, v46
	v_exp_f32_e32 v138, v138
	v_mul_f32_e32 v151, 0xbfb8aa3b, v47
	v_exp_f32_e32 v151, v151
	v_pk_mul_f32 v[168:169], v[72:73], v[168:169]
	v_pk_mul_f32 v[172:173], v[66:67], v[172:173]
	v_pk_mul_f32 v[174:175], v[68:69], v[174:175]
	v_lshlrev_b64 v[170:171], 11, v[170:171]
	v_pk_mul_f32 v[168:169], v[88:89], v[168:169]
	v_pk_mul_f32 v[166:167], v[86:87], v[166:167]
	v_pk_mul_f32 v[174:175], v[84:85], v[174:175]
	v_pk_mul_f32 v[172:173], v[82:83], v[172:173]
	v_lshl_add_u64 v[170:171], s[10:11], 0, v[170:171]
	v_cvt_pk_bf16_f32 v166, v166, v167
	v_cvt_pk_bf16_f32 v167, v168, v169
	v_cvt_pk_bf16_f32 v168, v172, v173
	v_cvt_pk_bf16_f32 v169, v174, v175
	v_lshl_add_u64 v[156:157], v[170:171], 0, v[156:157]
	v_add_f32_e32 v138, 1.0, v138
	global_store_dwordx4 v[156:157], v[166:169], off sc1
	v_rcp_f32_e32 v156, v138
	v_add_f32_e32 v138, 1.0, v151
	v_mul_f32_e32 v151, 0xbfb8aa3b, v48
	v_exp_f32_e32 v151, v151
	v_mul_f32_e32 v153, 0xbfb8aa3b, v49
	v_exp_f32_e32 v153, v153
	v_rcp_f32_e32 v157, v138
	v_add_f32_e32 v138, 1.0, v151
	v_rcp_f32_e32 v166, v138
	v_add_f32_e32 v138, 1.0, v153
	v_rcp_f32_e32 v167, v138
	v_mul_f32_e32 v138, 0xbfb8aa3b, v42
	v_exp_f32_e32 v138, v138
	v_mul_f32_e32 v151, 0xbfb8aa3b, v43
	v_exp_f32_e32 v151, v151
	v_mul_f32_e32 v153, 0xbfb8aa3b, v45
	v_add_f32_e32 v138, 1.0, v138
	v_rcp_f32_e32 v168, v138
	v_add_f32_e32 v138, 1.0, v151
	v_mul_f32_e32 v151, 0xbfb8aa3b, v44
	v_exp_f32_e32 v151, v151
	v_exp_f32_e32 v153, v153
	v_rcp_f32_e32 v169, v138
	v_pk_mul_f32 v[156:157], v[46:47], v[156:157]
	v_add_f32_e32 v138, 1.0, v151
	v_rcp_f32_e32 v170, v138
	v_add_f32_e32 v138, 1.0, v153
	v_rcp_f32_e32 v171, v138
	v_mul_f32_e32 v138, 0xbfb8aa3b, v30
	v_exp_f32_e32 v138, v138
	v_mul_f32_e32 v151, 0xbfb8aa3b, v31
	v_pk_mul_f32 v[166:167], v[48:49], v[166:167]
	v_exp_f32_e32 v151, v151
	v_pk_mul_f32 v[172:173], v[64:65], v[166:167]
	v_pk_mul_f32 v[156:157], v[62:63], v[156:157]
	v_pk_mul_f32 v[166:167], v[42:43], v[168:169]
	v_pk_mul_f32 v[168:169], v[44:45], v[170:171]
	v_add_f32_e32 v138, 1.0, v138
	v_pk_mul_f32 v[170:171], v[60:61], v[168:169]
	v_pk_mul_f32 v[168:169], v[58:59], v[166:167]
	v_cvt_pk_bf16_f32 v166, v156, v157
	v_add_co_u32_e32 v156, vcc, s84, v154
	v_cvt_pk_bf16_f32 v167, v172, v173
	v_cvt_pk_bf16_f32 v168, v168, v169
	v_cvt_pk_bf16_f32 v169, v170, v171
	v_addc_co_u32_e32 v157, vcc, 0, v155, vcc
	global_store_dwordx4 v[156:157], v[166:169], off sc1
	v_rcp_f32_e32 v156, v138
	v_add_f32_e32 v138, 1.0, v151
	v_mul_f32_e32 v151, 0xbfb8aa3b, v32
	v_exp_f32_e32 v151, v151
	v_mul_f32_e32 v153, 0xbfb8aa3b, v33
	v_exp_f32_e32 v153, v153
	v_rcp_f32_e32 v157, v138
	v_add_f32_e32 v138, 1.0, v151
	v_rcp_f32_e32 v166, v138
	v_add_f32_e32 v138, 1.0, v153
	v_rcp_f32_e32 v167, v138
	v_mul_f32_e32 v138, 0xbfb8aa3b, v26
	v_exp_f32_e32 v138, v138
	v_mul_f32_e32 v151, 0xbfb8aa3b, v27
	v_exp_f32_e32 v151, v151
	v_mul_f32_e32 v153, 0xbfb8aa3b, v29
	v_add_f32_e32 v138, 1.0, v138
	v_rcp_f32_e32 v168, v138
	v_add_f32_e32 v138, 1.0, v151
	v_mul_f32_e32 v151, 0xbfb8aa3b, v28
	v_exp_f32_e32 v151, v151
	v_exp_f32_e32 v153, v153
	v_rcp_f32_e32 v169, v138
	v_pk_mul_f32 v[156:157], v[30:31], v[156:157]
	v_add_f32_e32 v138, 1.0, v151
	v_rcp_f32_e32 v170, v138
	v_add_f32_e32 v138, 1.0, v153
	v_rcp_f32_e32 v171, v138
	v_mul_f32_e32 v138, 0xbfb8aa3b, v14
	v_exp_f32_e32 v138, v138
	v_mul_f32_e32 v151, 0xbfb8aa3b, v15
	v_pk_mul_f32 v[166:167], v[32:33], v[166:167]
	v_exp_f32_e32 v151, v151
	v_pk_mul_f32 v[172:173], v[56:57], v[166:167]
	v_pk_mul_f32 v[156:157], v[54:55], v[156:157]
	v_pk_mul_f32 v[166:167], v[26:27], v[168:169]
	v_pk_mul_f32 v[168:169], v[28:29], v[170:171]
	v_add_f32_e32 v138, 1.0, v138
	v_pk_mul_f32 v[170:171], v[52:53], v[168:169]
	v_pk_mul_f32 v[168:169], v[50:51], v[166:167]
	v_cvt_pk_bf16_f32 v166, v156, v157
	v_add_co_u32_e32 v156, vcc, s85, v154
	v_cvt_pk_bf16_f32 v167, v172, v173
	v_cvt_pk_bf16_f32 v168, v168, v169
	v_cvt_pk_bf16_f32 v169, v170, v171
	v_addc_co_u32_e32 v157, vcc, 0, v155, vcc
	global_store_dwordx4 v[156:157], v[166:169], off sc1
	v_rcp_f32_e32 v156, v138
	v_add_f32_e32 v138, 1.0, v151
	v_mul_f32_e32 v151, 0xbfb8aa3b, v16
	v_exp_f32_e32 v151, v151
	v_mul_f32_e32 v153, 0xbfb8aa3b, v17
	v_exp_f32_e32 v153, v153
	v_rcp_f32_e32 v157, v138
	v_add_f32_e32 v138, 1.0, v151
	v_rcp_f32_e32 v166, v138
	v_add_f32_e32 v138, 1.0, v153
	v_rcp_f32_e32 v167, v138
	v_mul_f32_e32 v138, 0xbfb8aa3b, v10
	v_exp_f32_e32 v138, v138
	v_mul_f32_e32 v151, 0xbfb8aa3b, v11
	v_exp_f32_e32 v151, v151
	v_mul_f32_e32 v153, 0xbfb8aa3b, v13
	v_add_f32_e32 v138, 1.0, v138
	v_rcp_f32_e32 v168, v138
	v_add_f32_e32 v138, 1.0, v151
	v_mul_f32_e32 v151, 0xbfb8aa3b, v12
	v_exp_f32_e32 v151, v151
	v_exp_f32_e32 v153, v153
	v_rcp_f32_e32 v169, v138
	v_pk_mul_f32 v[156:157], v[14:15], v[156:157]
	v_add_f32_e32 v138, 1.0, v151
	v_rcp_f32_e32 v170, v138
	v_add_f32_e32 v138, 1.0, v153
	v_rcp_f32_e32 v171, v138
	v_mul_f32_e32 v138, 0xbfb8aa3b, v6
	v_exp_f32_e32 v138, v138
	v_mul_f32_e32 v151, 0xbfb8aa3b, v7
	v_pk_mul_f32 v[166:167], v[16:17], v[166:167]
	v_exp_f32_e32 v151, v151
	v_pk_mul_f32 v[172:173], v[40:41], v[166:167]
	v_pk_mul_f32 v[156:157], v[38:39], v[156:157]
	v_pk_mul_f32 v[166:167], v[10:11], v[168:169]
	v_pk_mul_f32 v[168:169], v[12:13], v[170:171]
	v_add_f32_e32 v138, 1.0, v138
	v_pk_mul_f32 v[170:171], v[36:37], v[168:169]
	v_pk_mul_f32 v[168:169], v[34:35], v[166:167]
	v_cvt_pk_bf16_f32 v166, v156, v157
	v_add_co_u32_e32 v156, vcc, s86, v154
	v_cvt_pk_bf16_f32 v167, v172, v173
	v_cvt_pk_bf16_f32 v168, v168, v169
	v_cvt_pk_bf16_f32 v169, v170, v171
	v_addc_co_u32_e32 v157, vcc, 0, v155, vcc
	global_store_dwordx4 v[156:157], v[166:169], off sc1
	v_rcp_f32_e32 v156, v138
	v_add_f32_e32 v138, 1.0, v151
	v_mul_f32_e32 v151, 0xbfb8aa3b, v8
	v_exp_f32_e32 v151, v151
	v_mul_f32_e32 v153, 0xbfb8aa3b, v9
	v_exp_f32_e32 v153, v153
	v_rcp_f32_e32 v157, v138
	v_add_f32_e32 v138, 1.0, v151
	v_rcp_f32_e32 v166, v138
	v_add_f32_e32 v138, 1.0, v153
	v_rcp_f32_e32 v167, v138
	v_mul_f32_e32 v138, 0xbfb8aa3b, v2
	v_exp_f32_e32 v138, v138
	v_mul_f32_e32 v151, 0xbfb8aa3b, v3
	v_exp_f32_e32 v151, v151
	v_mul_f32_e32 v153, 0xbfb8aa3b, v5
	v_add_f32_e32 v138, 1.0, v138
	v_rcp_f32_e32 v168, v138
	v_add_f32_e32 v138, 1.0, v151
	v_mul_f32_e32 v151, 0xbfb8aa3b, v4
	v_exp_f32_e32 v151, v151
	v_exp_f32_e32 v153, v153
	v_rcp_f32_e32 v169, v138
	v_pk_mul_f32 v[166:167], v[8:9], v[166:167]
	v_add_f32_e32 v138, 1.0, v151
	v_rcp_f32_e32 v170, v138
	v_add_f32_e32 v138, 1.0, v153
	v_rcp_f32_e32 v171, v138
	v_pk_mul_f32 v[156:157], v[6:7], v[156:157]
	v_pk_mul_f32 v[172:173], v[24:25], v[166:167]
	v_pk_mul_f32 v[166:167], v[2:3], v[168:169]
	v_pk_mul_f32 v[168:169], v[4:5], v[170:171]
	v_pk_mul_f32 v[156:157], v[22:23], v[156:157]
	v_pk_mul_f32 v[170:171], v[20:21], v[168:169]
	v_pk_mul_f32 v[168:169], v[18:19], v[166:167]
	v_add_co_u32_e32 v154, vcc, 0x58000, v154
	v_cvt_pk_bf16_f32 v166, v156, v157
	v_cvt_pk_bf16_f32 v167, v172, v173
	v_cvt_pk_bf16_f32 v168, v168, v169
	v_cvt_pk_bf16_f32 v169, v170, v171
	v_addc_co_u32_e32 v155, vcc, 0, v155, vcc
	global_store_dwordx4 v[154:155], v[166:169], off sc1

.LBB0_174:
	s_andn2_b64 vcc, exec, s[18:19]
	s_cbranch_vccnz .LBB0_176
	v_pk_mul_f32 v[156:157], v[128:129], v[112:113]
	v_pk_mul_f32 v[154:155], v[126:127], v[110:111]
	v_pk_mul_f32 v[166:167], v[124:125], v[108:109]
	v_ashrrev_i32_e32 v153, 31, v152
	v_lshl_add_u32 v138, s88, 7, v161
	v_pk_mul_f32 v[168:169], v[122:123], v[106:107]
	v_cvt_pk_bf16_f32 v154, v154, v155
	v_cvt_pk_bf16_f32 v155, v156, v157
	v_cvt_pk_bf16_f32 v157, v166, v167
	v_lshlrev_b64 v[166:167], 11, v[152:153]
	v_or_b32_e32 v170, 16, v152
	v_cvt_pk_bf16_f32 v156, v168, v169
	v_lshl_add_u64 v[166:167], s[34:35], 0, v[166:167]
	v_lshlrev_b64 v[168:169], 1, v[138:139]
	v_ashrrev_i32_e32 v171, 31, v170
	v_lshl_add_u64 v[166:167], v[166:167], 0, v[168:169]
	v_lshlrev_b64 v[170:171], 11, v[170:171]
	global_store_dwordx4 v[166:167], v[154:157], off sc1
	v_pk_mul_f32 v[172:173], v[116:117], v[92:93]
	v_pk_mul_f32 v[174:175], v[114:115], v[90:91]
	v_pk_mul_f32 v[156:157], v[120:121], v[96:97]
	v_pk_mul_f32 v[154:155], v[118:119], v[94:95]
	v_lshl_add_u64 v[170:171], s[34:35], 0, v[170:171]
	v_cvt_pk_bf16_f32 v154, v154, v155
	v_cvt_pk_bf16_f32 v155, v156, v157
	v_cvt_pk_bf16_f32 v156, v174, v175
	v_cvt_pk_bf16_f32 v157, v172, v173
	v_lshl_add_u64 v[170:171], v[170:171], 0, v[168:169]
	global_store_dwordx4 v[170:171], v[154:157], off sc1
	v_or_b32_e32 v170, 32, v152
	v_ashrrev_i32_e32 v171, 31, v170
	v_lshlrev_b64 v[170:171], 11, v[170:171]
	v_pk_mul_f32 v[156:157], v[104:105], v[80:81]
	v_pk_mul_f32 v[154:155], v[102:103], v[78:79]
	v_pk_mul_f32 v[172:173], v[100:101], v[76:77]
	v_pk_mul_f32 v[174:175], v[98:99], v[74:75]
	v_lshl_add_u64 v[170:171], s[34:35], 0, v[170:171]
	v_cvt_pk_bf16_f32 v154, v154, v155
	v_cvt_pk_bf16_f32 v155, v156, v157
	v_cvt_pk_bf16_f32 v156, v174, v175
	v_cvt_pk_bf16_f32 v157, v172, v173
	v_lshl_add_u64 v[170:171], v[170:171], 0, v[168:169]
	global_store_dwordx4 v[170:171], v[154:157], off sc1
	v_or_b32_e32 v170, 48, v152
	v_ashrrev_i32_e32 v171, 31, v170
	v_lshlrev_b64 v[170:171], 11, v[170:171]
	v_pk_mul_f32 v[156:157], v[88:89], v[72:73]
	v_pk_mul_f32 v[154:155], v[86:87], v[70:71]
	v_pk_mul_f32 v[172:173], v[84:85], v[68:69]
	v_pk_mul_f32 v[174:175], v[82:83], v[66:67]
	v_lshl_add_u64 v[170:171], s[34:35], 0, v[170:171]
	v_cvt_pk_bf16_f32 v154, v154, v155
	v_cvt_pk_bf16_f32 v155, v156, v157
	v_cvt_pk_bf16_f32 v156, v174, v175
	v_cvt_pk_bf16_f32 v157, v172, v173
	v_lshl_add_u64 v[168:169], v[170:171], 0, v[168:169]
	global_store_dwordx4 v[168:169], v[154:157], off sc1
	v_pk_mul_f32 v[168:169], v[60:61], v[44:45]
	v_pk_mul_f32 v[170:171], v[58:59], v[42:43]
	v_pk_mul_f32 v[156:157], v[64:65], v[48:49]
	v_pk_mul_f32 v[154:155], v[62:63], v[46:47]
	s_nop 0
	v_cvt_pk_bf16_f32 v154, v154, v155
	v_cvt_pk_bf16_f32 v155, v156, v157
	v_cvt_pk_bf16_f32 v157, v168, v169
	v_add_co_u32_e32 v168, vcc, s84, v166
	v_cvt_pk_bf16_f32 v156, v170, v171
	s_nop 0
	v_addc_co_u32_e32 v169, vcc, 0, v167, vcc
	global_store_dwordx4 v[168:169], v[154:157], off sc1
	v_pk_mul_f32 v[168:169], v[52:53], v[28:29]
	v_pk_mul_f32 v[170:171], v[50:51], v[26:27]
	v_pk_mul_f32 v[156:157], v[56:57], v[32:33]
	v_pk_mul_f32 v[154:155], v[54:55], v[30:31]
	s_nop 0
	v_cvt_pk_bf16_f32 v154, v154, v155
	v_cvt_pk_bf16_f32 v155, v156, v157
	v_cvt_pk_bf16_f32 v157, v168, v169
	v_add_co_u32_e32 v168, vcc, s85, v166
	v_cvt_pk_bf16_f32 v156, v170, v171
	s_nop 0
	v_addc_co_u32_e32 v169, vcc, 0, v167, vcc
	global_store_dwordx4 v[168:169], v[154:157], off sc1
	v_pk_mul_f32 v[168:169], v[36:37], v[12:13]
	v_pk_mul_f32 v[170:171], v[34:35], v[10:11]
	v_pk_mul_f32 v[156:157], v[40:41], v[16:17]
	v_pk_mul_f32 v[154:155], v[38:39], v[14:15]
	s_nop 0
	v_cvt_pk_bf16_f32 v154, v154, v155
	v_cvt_pk_bf16_f32 v155, v156, v157
	v_cvt_pk_bf16_f32 v157, v168, v169
	v_add_co_u32_e32 v168, vcc, s86, v166
	v_cvt_pk_bf16_f32 v156, v170, v171
	s_nop 0
	v_addc_co_u32_e32 v169, vcc, 0, v167, vcc
	global_store_dwordx4 v[168:169], v[154:157], off sc1
	v_pk_mul_f32 v[168:169], v[20:21], v[4:5]
	v_pk_mul_f32 v[170:171], v[18:19], v[2:3]
	v_pk_mul_f32 v[156:157], v[24:25], v[8:9]
	v_pk_mul_f32 v[154:155], v[22:23], v[6:7]
	v_add_co_u32_e32 v166, vcc, 0x58000, v166
	v_cvt_pk_bf16_f32 v154, v154, v155
	v_cvt_pk_bf16_f32 v155, v156, v157
	v_cvt_pk_bf16_f32 v156, v170, v171
	v_cvt_pk_bf16_f32 v157, v168, v169
	v_addc_co_u32_e32 v167, vcc, 0, v167, vcc
	global_store_dwordx4 v[166:167], v[154:157], off sc1

.LBB0_177:
	s_andn2_b64 vcc, exec, s[18:19]
	s_cbranch_vccnz .LBB0_179
	v_mul_f32_e32 v138, 0xbfb8aa3b, v126
	v_ashrrev_i32_e32 v153, 31, v152
	v_exp_f32_e32 v151, v138
	v_lshlrev_b64 v[154:155], 10, v[152:153]
	v_mul_f32_e32 v153, 0xbfb8aa3b, v127
	v_exp_f32_e32 v153, v153
	v_mul_f32_e32 v156, 0xbfb8aa3b, v128
	v_exp_f32_e32 v166, v156
	v_add_f32_e32 v151, 1.0, v151
	v_rcp_f32_e32 v156, v151
	v_add_f32_e32 v151, 1.0, v153
	v_mul_f32_e32 v153, 0xbfb8aa3b, v129
	v_rcp_f32_e32 v157, v151
	v_add_f32_e32 v151, 1.0, v166
	v_exp_f32_e32 v153, v153
	v_mul_f32_e32 v166, 0xbfb8aa3b, v122
	v_exp_f32_e32 v168, v166
	v_rcp_f32_e32 v166, v151
	v_add_f32_e32 v151, 1.0, v153
	v_rcp_f32_e32 v167, v151
	v_add_f32_e32 v151, 1.0, v168
	v_rcp_f32_e32 v168, v151
	v_mul_f32_e32 v151, 0xbfb8aa3b, v123
	v_mul_f32_e32 v153, 0xbfb8aa3b, v124
	v_exp_f32_e32 v151, v151
	v_exp_f32_e32 v153, v153
	v_mul_f32_e32 v169, 0xbfb8aa3b, v125
	v_exp_f32_e32 v169, v169
	v_add_f32_e32 v151, 1.0, v151
	v_add_f32_e32 v153, 1.0, v153
	v_rcp_f32_e32 v170, v153
	v_add_f32_e32 v153, 1.0, v169
	v_rcp_f32_e32 v169, v151
	v_mul_f32_e32 v151, 0xbfb8aa3b, v110
	v_exp_f32_e32 v151, v151
	v_lshl_add_u32 v138, s88, 8, v161
	v_rcp_f32_e32 v171, v153
	v_pk_mul_f32 v[156:157], v[126:127], v[156:157]
	v_pk_mul_f32 v[172:173], v[128:129], v[166:167]
	v_cvt_pk_bf16_f32 v166, v156, v157
	v_lshlrev_b64 v[156:157], 1, v[138:139]
	v_add_f32_e32 v138, 1.0, v151
	v_mul_f32_e32 v151, 0xbfb8aa3b, v111
	v_exp_f32_e32 v151, v151
	v_mul_f32_e32 v153, 0xbfb8aa3b, v112
	v_exp_f32_e32 v153, v153
	v_pk_mul_f32 v[170:171], v[124:125], v[170:171]
	v_pk_mul_f32 v[168:169], v[122:123], v[168:169]
	v_lshl_add_u64 v[154:155], s[8:9], 0, v[154:155]
	v_cvt_pk_bf16_f32 v167, v172, v173
	v_cvt_pk_bf16_f32 v168, v168, v169
	v_cvt_pk_bf16_f32 v169, v170, v171
	v_lshl_add_u64 v[154:155], v[154:155], 0, v[156:157]
	global_store_dwordx4 v[154:155], v[166:169], off sc1
	s_mov_b64 s[18:19], 0x20000
	s_nop 0
	v_rcp_f32_e32 v166, v138
	v_add_f32_e32 v138, 1.0, v151
	v_mul_f32_e32 v151, 0xbfb8aa3b, v113
	v_rcp_f32_e32 v167, v138
	v_add_f32_e32 v138, 1.0, v153
	v_exp_f32_e32 v151, v151
	v_mul_f32_e32 v153, 0xbfb8aa3b, v106
	v_exp_f32_e32 v153, v153
	v_rcp_f32_e32 v168, v138
	v_add_f32_e32 v138, 1.0, v151
	v_rcp_f32_e32 v169, v138
	v_add_f32_e32 v138, 1.0, v153
	v_mul_f32_e32 v151, 0xbfb8aa3b, v108
	v_rcp_f32_e32 v170, v138
	v_mul_f32_e32 v138, 0xbfb8aa3b, v107
	v_exp_f32_e32 v151, v151
	v_mul_f32_e32 v153, 0xbfb8aa3b, v109
	v_exp_f32_e32 v138, v138
	v_exp_f32_e32 v153, v153
	v_add_f32_e32 v151, 1.0, v151
	v_rcp_f32_e32 v172, v151
	v_add_f32_e32 v138, 1.0, v138
	v_add_f32_e32 v151, 1.0, v153
	v_rcp_f32_e32 v173, v151
	v_rcp_f32_e32 v171, v138
	v_mul_f32_e32 v138, 0xbfb8aa3b, v118
	v_exp_f32_e32 v138, v138
	v_mul_f32_e32 v151, 0xbfb8aa3b, v119
	v_pk_mul_f32 v[168:169], v[112:113], v[168:169]
	v_pk_mul_f32 v[166:167], v[110:111], v[166:167]
	v_pk_mul_f32 v[172:173], v[108:109], v[172:173]
	v_pk_mul_f32 v[170:171], v[106:107], v[170:171]
	v_exp_f32_e32 v151, v151
	v_mul_f32_e32 v153, 0xbfb8aa3b, v120
	v_cvt_pk_bf16_f32 v166, v166, v167
	v_cvt_pk_bf16_f32 v167, v168, v169
	v_cvt_pk_bf16_f32 v168, v170, v171
	v_cvt_pk_bf16_f32 v169, v172, v173
	v_exp_f32_e32 v153, v153
	global_store_dwordx4 v[154:155], v[166:169], off offset:256 sc1
	v_add_f32_e32 v138, 1.0, v138
	s_nop 0
	v_or_b32_e32 v166, 16, v152
	v_ashrrev_i32_e32 v167, 31, v166
	v_lshlrev_b64 v[170:171], 10, v[166:167]
	v_rcp_f32_e32 v166, v138
	v_add_f32_e32 v138, 1.0, v151
	v_mul_f32_e32 v151, 0xbfb8aa3b, v121
	v_rcp_f32_e32 v167, v138
	v_add_f32_e32 v138, 1.0, v153
	v_exp_f32_e32 v151, v151
	v_mul_f32_e32 v153, 0xbfb8aa3b, v114
	v_exp_f32_e32 v153, v153
	v_rcp_f32_e32 v168, v138
	v_add_f32_e32 v138, 1.0, v151
	v_rcp_f32_e32 v169, v138
	v_add_f32_e32 v138, 1.0, v153
	v_mul_f32_e32 v151, 0xbfb8aa3b, v116
	v_rcp_f32_e32 v172, v138
	v_mul_f32_e32 v138, 0xbfb8aa3b, v115
	v_exp_f32_e32 v151, v151
	v_mul_f32_e32 v153, 0xbfb8aa3b, v117
	v_exp_f32_e32 v138, v138
	v_exp_f32_e32 v153, v153
	v_add_f32_e32 v151, 1.0, v151
	v_rcp_f32_e32 v174, v151
	v_add_f32_e32 v138, 1.0, v138
	v_add_f32_e32 v151, 1.0, v153
	v_rcp_f32_e32 v175, v151
	v_rcp_f32_e32 v173, v138
	v_mul_f32_e32 v138, 0xbfb8aa3b, v94
	v_exp_f32_e32 v138, v138
	v_mul_f32_e32 v151, 0xbfb8aa3b, v95
	v_exp_f32_e32 v151, v151
	v_mul_f32_e32 v153, 0xbfb8aa3b, v96
	v_exp_f32_e32 v153, v153
	v_pk_mul_f32 v[168:169], v[120:121], v[168:169]
	v_pk_mul_f32 v[166:167], v[118:119], v[166:167]
	v_pk_mul_f32 v[174:175], v[116:117], v[174:175]
	v_pk_mul_f32 v[172:173], v[114:115], v[172:173]
	v_lshl_add_u64 v[170:171], s[8:9], 0, v[170:171]
	v_cvt_pk_bf16_f32 v166, v166, v167
	v_cvt_pk_bf16_f32 v167, v168, v169
	v_cvt_pk_bf16_f32 v168, v172, v173
	v_cvt_pk_bf16_f32 v169, v174, v175
	v_lshl_add_u64 v[170:171], v[170:171], 0, v[156:157]
	v_add_f32_e32 v138, 1.0, v138
	global_store_dwordx4 v[170:171], v[166:169], off sc1
	s_nop 1
	v_rcp_f32_e32 v166, v138
	v_add_f32_e32 v138, 1.0, v151
	v_mul_f32_e32 v151, 0xbfb8aa3b, v97
	v_rcp_f32_e32 v167, v138
	v_add_f32_e32 v138, 1.0, v153
	v_exp_f32_e32 v151, v151
	v_mul_f32_e32 v153, 0xbfb8aa3b, v90
	v_exp_f32_e32 v153, v153
	v_rcp_f32_e32 v168, v138
	v_add_f32_e32 v138, 1.0, v151
	v_rcp_f32_e32 v169, v138
	v_add_f32_e32 v138, 1.0, v153
	v_mul_f32_e32 v151, 0xbfb8aa3b, v92
	v_rcp_f32_e32 v172, v138
	v_mul_f32_e32 v138, 0xbfb8aa3b, v91
	v_exp_f32_e32 v151, v151
	v_mul_f32_e32 v153, 0xbfb8aa3b, v93
	v_exp_f32_e32 v138, v138
	v_exp_f32_e32 v153, v153
	v_add_f32_e32 v151, 1.0, v151
	v_rcp_f32_e32 v174, v151
	v_add_f32_e32 v138, 1.0, v138
	v_add_f32_e32 v151, 1.0, v153
	v_rcp_f32_e32 v175, v151
	v_rcp_f32_e32 v173, v138
	v_mul_f32_e32 v138, 0xbfb8aa3b, v102
	v_exp_f32_e32 v138, v138
	v_mul_f32_e32 v151, 0xbfb8aa3b, v103
	v_pk_mul_f32 v[168:169], v[96:97], v[168:169]
	v_pk_mul_f32 v[166:167], v[94:95], v[166:167]
	v_pk_mul_f32 v[174:175], v[92:93], v[174:175]
	v_pk_mul_f32 v[172:173], v[90:91], v[172:173]
	v_exp_f32_e32 v151, v151
	v_mul_f32_e32 v153, 0xbfb8aa3b, v104
	v_cvt_pk_bf16_f32 v166, v166, v167
	v_cvt_pk_bf16_f32 v167, v168, v169
	v_cvt_pk_bf16_f32 v168, v172, v173
	v_cvt_pk_bf16_f32 v169, v174, v175
	v_exp_f32_e32 v153, v153
	global_store_dwordx4 v[170:171], v[166:169], off offset:256 sc1
	v_add_f32_e32 v138, 1.0, v138
	s_nop 0
	v_or_b32_e32 v166, 32, v152
	v_ashrrev_i32_e32 v167, 31, v166
	v_lshlrev_b64 v[170:171], 10, v[166:167]
	v_rcp_f32_e32 v166, v138
	v_add_f32_e32 v138, 1.0, v151
	v_mul_f32_e32 v151, 0xbfb8aa3b, v105
	v_rcp_f32_e32 v167, v138
	v_add_f32_e32 v138, 1.0, v153
	v_exp_f32_e32 v151, v151
	v_mul_f32_e32 v153, 0xbfb8aa3b, v98
	v_exp_f32_e32 v153, v153
	v_rcp_f32_e32 v168, v138
	v_add_f32_e32 v138, 1.0, v151
	v_rcp_f32_e32 v169, v138
	v_add_f32_e32 v138, 1.0, v153
	v_mul_f32_e32 v151, 0xbfb8aa3b, v100
	v_rcp_f32_e32 v172, v138
	v_mul_f32_e32 v138, 0xbfb8aa3b, v99
	v_exp_f32_e32 v151, v151
	v_mul_f32_e32 v153, 0xbfb8aa3b, v101
	v_exp_f32_e32 v138, v138
	v_exp_f32_e32 v153, v153
	v_add_f32_e32 v151, 1.0, v151
	v_rcp_f32_e32 v174, v151
	v_add_f32_e32 v138, 1.0, v138
	v_add_f32_e32 v151, 1.0, v153
	v_rcp_f32_e32 v175, v151
	v_rcp_f32_e32 v173, v138
	v_mul_f32_e32 v138, 0xbfb8aa3b, v78
	v_exp_f32_e32 v138, v138
	v_mul_f32_e32 v151, 0xbfb8aa3b, v79
	v_exp_f32_e32 v151, v151
	v_mul_f32_e32 v153, 0xbfb8aa3b, v80
	v_exp_f32_e32 v153, v153
	v_pk_mul_f32 v[168:169], v[104:105], v[168:169]
	v_pk_mul_f32 v[166:167], v[102:103], v[166:167]
	v_pk_mul_f32 v[174:175], v[100:101], v[174:175]
	v_pk_mul_f32 v[172:173], v[98:99], v[172:173]
	v_lshl_add_u64 v[170:171], s[8:9], 0, v[170:171]
	v_cvt_pk_bf16_f32 v166, v166, v167
	v_cvt_pk_bf16_f32 v167, v168, v169
	v_cvt_pk_bf16_f32 v168, v172, v173
	v_cvt_pk_bf16_f32 v169, v174, v175
	v_lshl_add_u64 v[170:171], v[170:171], 0, v[156:157]
	v_add_f32_e32 v138, 1.0, v138
	global_store_dwordx4 v[170:171], v[166:169], off sc1
	s_nop 1
	v_rcp_f32_e32 v166, v138
	v_add_f32_e32 v138, 1.0, v151
	v_mul_f32_e32 v151, 0xbfb8aa3b, v81
	v_rcp_f32_e32 v167, v138
	v_add_f32_e32 v138, 1.0, v153
	v_exp_f32_e32 v151, v151
	v_mul_f32_e32 v153, 0xbfb8aa3b, v74
	v_exp_f32_e32 v153, v153
	v_rcp_f32_e32 v168, v138
	v_add_f32_e32 v138, 1.0, v151
	v_rcp_f32_e32 v169, v138
	v_add_f32_e32 v138, 1.0, v153
	v_mul_f32_e32 v151, 0xbfb8aa3b, v76
	v_rcp_f32_e32 v172, v138
	v_mul_f32_e32 v138, 0xbfb8aa3b, v75
	v_exp_f32_e32 v151, v151
	v_mul_f32_e32 v153, 0xbfb8aa3b, v77
	v_exp_f32_e32 v138, v138
	v_exp_f32_e32 v153, v153
	v_add_f32_e32 v151, 1.0, v151
	v_rcp_f32_e32 v174, v151
	v_add_f32_e32 v138, 1.0, v138
	v_add_f32_e32 v151, 1.0, v153
	v_rcp_f32_e32 v175, v151
	v_rcp_f32_e32 v173, v138
	v_mul_f32_e32 v138, 0xbfb8aa3b, v86
	v_exp_f32_e32 v138, v138
	v_mul_f32_e32 v151, 0xbfb8aa3b, v87
	v_pk_mul_f32 v[168:169], v[80:81], v[168:169]
	v_pk_mul_f32 v[166:167], v[78:79], v[166:167]
	v_pk_mul_f32 v[174:175], v[76:77], v[174:175]
	v_pk_mul_f32 v[172:173], v[74:75], v[172:173]
	v_exp_f32_e32 v151, v151
	v_mul_f32_e32 v153, 0xbfb8aa3b, v88
	v_cvt_pk_bf16_f32 v166, v166, v167
	v_cvt_pk_bf16_f32 v167, v168, v169
	v_cvt_pk_bf16_f32 v168, v172, v173
	v_cvt_pk_bf16_f32 v169, v174, v175
	v_exp_f32_e32 v153, v153
	global_store_dwordx4 v[170:171], v[166:169], off offset:256 sc1
	v_add_f32_e32 v138, 1.0, v138
	s_nop 0
	v_or_b32_e32 v166, 48, v152
	v_ashrrev_i32_e32 v167, 31, v166
	v_lshlrev_b64 v[170:171], 10, v[166:167]
	v_rcp_f32_e32 v166, v138
	v_add_f32_e32 v138, 1.0, v151
	v_mul_f32_e32 v151, 0xbfb8aa3b, v89
	v_rcp_f32_e32 v167, v138
	v_add_f32_e32 v138, 1.0, v153
	v_exp_f32_e32 v151, v151
	v_mul_f32_e32 v153, 0xbfb8aa3b, v82
	v_exp_f32_e32 v153, v153
	v_rcp_f32_e32 v168, v138
	v_add_f32_e32 v138, 1.0, v151
	v_rcp_f32_e32 v169, v138
	v_add_f32_e32 v138, 1.0, v153
	v_mul_f32_e32 v151, 0xbfb8aa3b, v84
	v_rcp_f32_e32 v172, v138
	v_mul_f32_e32 v138, 0xbfb8aa3b, v83
	v_exp_f32_e32 v151, v151
	v_mul_f32_e32 v153, 0xbfb8aa3b, v85
	v_exp_f32_e32 v138, v138
	v_exp_f32_e32 v153, v153
	v_add_f32_e32 v151, 1.0, v151
	v_rcp_f32_e32 v174, v151
	v_add_f32_e32 v138, 1.0, v138
	v_add_f32_e32 v151, 1.0, v153
	v_rcp_f32_e32 v175, v151
	v_rcp_f32_e32 v173, v138
	v_mul_f32_e32 v138, 0xbfb8aa3b, v70
	v_exp_f32_e32 v138, v138
	v_mul_f32_e32 v151, 0xbfb8aa3b, v71
	v_exp_f32_e32 v151, v151
	v_mul_f32_e32 v153, 0xbfb8aa3b, v72
	v_exp_f32_e32 v153, v153
	v_pk_mul_f32 v[168:169], v[88:89], v[168:169]
	v_pk_mul_f32 v[166:167], v[86:87], v[166:167]
	v_pk_mul_f32 v[174:175], v[84:85], v[174:175]
	v_pk_mul_f32 v[172:173], v[82:83], v[172:173]
	v_lshl_add_u64 v[170:171], s[8:9], 0, v[170:171]
	v_cvt_pk_bf16_f32 v166, v166, v167
	v_cvt_pk_bf16_f32 v167, v168, v169
	v_cvt_pk_bf16_f32 v168, v172, v173
	v_cvt_pk_bf16_f32 v169, v174, v175
	v_lshl_add_u64 v[156:157], v[170:171], 0, v[156:157]
	v_add_f32_e32 v138, 1.0, v138
	global_store_dwordx4 v[156:157], v[166:169], off sc1
	s_nop 1
	v_rcp_f32_e32 v166, v138
	v_add_f32_e32 v138, 1.0, v151
	v_mul_f32_e32 v151, 0xbfb8aa3b, v73
	v_rcp_f32_e32 v167, v138
	v_add_f32_e32 v138, 1.0, v153
	v_exp_f32_e32 v151, v151
	v_mul_f32_e32 v153, 0xbfb8aa3b, v66
	v_exp_f32_e32 v153, v153
	v_rcp_f32_e32 v168, v138
	v_add_f32_e32 v138, 1.0, v151
	v_rcp_f32_e32 v169, v138
	v_add_f32_e32 v138, 1.0, v153
	v_mul_f32_e32 v151, 0xbfb8aa3b, v68
	v_rcp_f32_e32 v170, v138
	v_mul_f32_e32 v138, 0xbfb8aa3b, v67
	v_exp_f32_e32 v151, v151
	v_mul_f32_e32 v153, 0xbfb8aa3b, v69
	v_exp_f32_e32 v138, v138
	v_exp_f32_e32 v153, v153
	v_add_f32_e32 v151, 1.0, v151
	v_rcp_f32_e32 v172, v151
	v_add_f32_e32 v138, 1.0, v138
	v_add_f32_e32 v151, 1.0, v153
	v_rcp_f32_e32 v173, v151
	v_rcp_f32_e32 v171, v138
	v_mul_f32_e32 v138, 0xbfb8aa3b, v62
	v_exp_f32_e32 v138, v138
	v_mul_f32_e32 v151, 0xbfb8aa3b, v63
	v_exp_f32_e32 v151, v151
	v_mul_f32_e32 v153, 0xbfb8aa3b, v64
	v_exp_f32_e32 v153, v153
	v_pk_mul_f32 v[168:169], v[72:73], v[168:169]
	v_pk_mul_f32 v[166:167], v[70:71], v[166:167]
	v_pk_mul_f32 v[172:173], v[68:69], v[172:173]
	v_pk_mul_f32 v[170:171], v[66:67], v[170:171]
	v_cvt_pk_bf16_f32 v166, v166, v167
	v_cvt_pk_bf16_f32 v167, v168, v169
	v_cvt_pk_bf16_f32 v168, v170, v171
	v_cvt_pk_bf16_f32 v169, v172, v173
	v_add_f32_e32 v138, 1.0, v138
	global_store_dwordx4 v[156:157], v[166:169], off offset:256 sc1
	v_rcp_f32_e32 v156, v138
	v_add_f32_e32 v138, 1.0, v151
	v_mul_f32_e32 v151, 0xbfb8aa3b, v65
	v_rcp_f32_e32 v157, v138
	v_add_f32_e32 v138, 1.0, v153
	v_exp_f32_e32 v151, v151
	v_mul_f32_e32 v153, 0xbfb8aa3b, v58
	v_exp_f32_e32 v153, v153
	v_rcp_f32_e32 v166, v138
	v_add_f32_e32 v138, 1.0, v151
	v_rcp_f32_e32 v167, v138
	v_add_f32_e32 v138, 1.0, v153
	v_mul_f32_e32 v151, 0xbfb8aa3b, v60
	v_rcp_f32_e32 v168, v138
	v_mul_f32_e32 v138, 0xbfb8aa3b, v59
	v_exp_f32_e32 v151, v151
	v_mul_f32_e32 v153, 0xbfb8aa3b, v61
	v_exp_f32_e32 v138, v138
	v_exp_f32_e32 v153, v153
	v_add_f32_e32 v151, 1.0, v151
	v_rcp_f32_e32 v170, v151
	v_add_f32_e32 v138, 1.0, v138
	v_add_f32_e32 v151, 1.0, v153
	v_rcp_f32_e32 v171, v151
	v_rcp_f32_e32 v169, v138
	v_mul_f32_e32 v138, 0xbfb8aa3b, v46
	v_exp_f32_e32 v138, v138
	v_mul_f32_e32 v151, 0xbfb8aa3b, v47
	v_pk_mul_f32 v[156:157], v[62:63], v[156:157]
	v_exp_f32_e32 v151, v151
	v_mul_f32_e32 v153, 0xbfb8aa3b, v48
	v_pk_mul_f32 v[172:173], v[64:65], v[166:167]
	v_pk_mul_f32 v[170:171], v[60:61], v[170:171]
	v_pk_mul_f32 v[168:169], v[58:59], v[168:169]
	v_cvt_pk_bf16_f32 v166, v156, v157
	v_lshl_add_u64 v[156:157], v[154:155], 0, s[18:19]
	s_mov_b32 s18, 0x20000
	v_exp_f32_e32 v153, v153
	v_cvt_pk_bf16_f32 v168, v168, v169
	v_cvt_pk_bf16_f32 v169, v170, v171
	v_add_co_u32_e32 v170, vcc, s18, v154
	v_cvt_pk_bf16_f32 v167, v172, v173
	s_nop 0
	v_addc_co_u32_e32 v171, vcc, 0, v155, vcc
	v_add_f32_e32 v138, 1.0, v138
	global_store_dwordx4 v[170:171], v[166:169], off sc1
	s_mov_b64 s[18:19], 0x24000
	s_nop 0
	v_rcp_f32_e32 v166, v138
	v_add_f32_e32 v138, 1.0, v151
	v_mul_f32_e32 v151, 0xbfb8aa3b, v49
	v_rcp_f32_e32 v167, v138
	v_add_f32_e32 v138, 1.0, v153
	v_exp_f32_e32 v151, v151
	v_mul_f32_e32 v153, 0xbfb8aa3b, v42
	v_exp_f32_e32 v153, v153
	v_rcp_f32_e32 v168, v138
	v_add_f32_e32 v138, 1.0, v151
	v_rcp_f32_e32 v169, v138
	v_add_f32_e32 v138, 1.0, v153
	v_mul_f32_e32 v151, 0xbfb8aa3b, v44
	v_rcp_f32_e32 v170, v138
	v_mul_f32_e32 v138, 0xbfb8aa3b, v43
	v_exp_f32_e32 v151, v151
	v_mul_f32_e32 v153, 0xbfb8aa3b, v45
	v_exp_f32_e32 v138, v138
	v_exp_f32_e32 v153, v153
	v_add_f32_e32 v151, 1.0, v151
	v_rcp_f32_e32 v172, v151
	v_add_f32_e32 v138, 1.0, v138
	v_add_f32_e32 v151, 1.0, v153
	v_rcp_f32_e32 v173, v151
	v_rcp_f32_e32 v171, v138
	v_mul_f32_e32 v138, 0xbfb8aa3b, v54
	v_exp_f32_e32 v138, v138
	v_mul_f32_e32 v151, 0xbfb8aa3b, v55
	v_exp_f32_e32 v151, v151
	v_mul_f32_e32 v153, 0xbfb8aa3b, v56
	v_exp_f32_e32 v153, v153
	v_pk_mul_f32 v[168:169], v[48:49], v[168:169]
	v_pk_mul_f32 v[166:167], v[46:47], v[166:167]
	v_pk_mul_f32 v[172:173], v[44:45], v[172:173]
	v_pk_mul_f32 v[170:171], v[42:43], v[170:171]
	v_cvt_pk_bf16_f32 v166, v166, v167
	v_cvt_pk_bf16_f32 v167, v168, v169
	v_cvt_pk_bf16_f32 v168, v170, v171
	v_cvt_pk_bf16_f32 v169, v172, v173
	v_add_f32_e32 v138, 1.0, v138
	global_store_dwordx4 v[156:157], v[166:169], off offset:256 sc1
	v_rcp_f32_e32 v156, v138
	v_add_f32_e32 v138, 1.0, v151
	v_mul_f32_e32 v151, 0xbfb8aa3b, v57
	v_rcp_f32_e32 v157, v138
	v_add_f32_e32 v138, 1.0, v153
	v_exp_f32_e32 v151, v151
	v_mul_f32_e32 v153, 0xbfb8aa3b, v50
	v_exp_f32_e32 v153, v153
	v_rcp_f32_e32 v166, v138
	v_add_f32_e32 v138, 1.0, v151
	v_rcp_f32_e32 v167, v138
	v_add_f32_e32 v138, 1.0, v153
	v_mul_f32_e32 v151, 0xbfb8aa3b, v52
	v_rcp_f32_e32 v168, v138
	v_mul_f32_e32 v138, 0xbfb8aa3b, v51
	v_exp_f32_e32 v151, v151
	v_mul_f32_e32 v153, 0xbfb8aa3b, v53
	v_exp_f32_e32 v138, v138
	v_exp_f32_e32 v153, v153
	v_add_f32_e32 v151, 1.0, v151
	v_rcp_f32_e32 v170, v151
	v_add_f32_e32 v138, 1.0, v138
	v_add_f32_e32 v151, 1.0, v153
	v_rcp_f32_e32 v171, v151
	v_rcp_f32_e32 v169, v138
	v_mul_f32_e32 v138, 0xbfb8aa3b, v30
	v_exp_f32_e32 v138, v138
	v_mul_f32_e32 v151, 0xbfb8aa3b, v31
	v_pk_mul_f32 v[156:157], v[54:55], v[156:157]
	v_exp_f32_e32 v151, v151
	v_mul_f32_e32 v153, 0xbfb8aa3b, v32
	v_pk_mul_f32 v[172:173], v[56:57], v[166:167]
	v_pk_mul_f32 v[170:171], v[52:53], v[170:171]
	v_pk_mul_f32 v[168:169], v[50:51], v[168:169]
	v_cvt_pk_bf16_f32 v166, v156, v157
	v_lshl_add_u64 v[156:157], v[154:155], 0, s[18:19]
	s_mov_b32 s18, 0x24000
	v_exp_f32_e32 v153, v153
	v_cvt_pk_bf16_f32 v168, v168, v169
	v_cvt_pk_bf16_f32 v169, v170, v171
	v_add_co_u32_e32 v170, vcc, s18, v154
	v_cvt_pk_bf16_f32 v167, v172, v173
	s_nop 0
	v_addc_co_u32_e32 v171, vcc, 0, v155, vcc
	v_add_f32_e32 v138, 1.0, v138
	global_store_dwordx4 v[170:171], v[166:169], off sc1
	s_mov_b64 s[18:19], 0x28000
	s_nop 0
	v_rcp_f32_e32 v166, v138
	v_add_f32_e32 v138, 1.0, v151
	v_mul_f32_e32 v151, 0xbfb8aa3b, v33
	v_rcp_f32_e32 v167, v138
	v_add_f32_e32 v138, 1.0, v153
	v_exp_f32_e32 v151, v151
	v_mul_f32_e32 v153, 0xbfb8aa3b, v26
	v_exp_f32_e32 v153, v153
	v_rcp_f32_e32 v168, v138
	v_add_f32_e32 v138, 1.0, v151
	v_rcp_f32_e32 v169, v138
	v_add_f32_e32 v138, 1.0, v153
	v_mul_f32_e32 v151, 0xbfb8aa3b, v28
	v_rcp_f32_e32 v170, v138
	v_mul_f32_e32 v138, 0xbfb8aa3b, v27
	v_exp_f32_e32 v151, v151
	v_mul_f32_e32 v153, 0xbfb8aa3b, v29
	v_exp_f32_e32 v138, v138
	v_exp_f32_e32 v153, v153
	v_add_f32_e32 v151, 1.0, v151
	v_rcp_f32_e32 v172, v151
	v_add_f32_e32 v138, 1.0, v138
	v_add_f32_e32 v151, 1.0, v153
	v_rcp_f32_e32 v173, v151
	v_rcp_f32_e32 v171, v138
	v_mul_f32_e32 v138, 0xbfb8aa3b, v38
	v_exp_f32_e32 v138, v138
	v_mul_f32_e32 v151, 0xbfb8aa3b, v39
	v_exp_f32_e32 v151, v151
	v_mul_f32_e32 v153, 0xbfb8aa3b, v40
	v_exp_f32_e32 v153, v153
	v_pk_mul_f32 v[168:169], v[32:33], v[168:169]
	v_pk_mul_f32 v[166:167], v[30:31], v[166:167]
	v_pk_mul_f32 v[172:173], v[28:29], v[172:173]
	v_pk_mul_f32 v[170:171], v[26:27], v[170:171]
	v_cvt_pk_bf16_f32 v166, v166, v167
	v_cvt_pk_bf16_f32 v167, v168, v169
	v_cvt_pk_bf16_f32 v168, v170, v171
	v_cvt_pk_bf16_f32 v169, v172, v173
	v_add_f32_e32 v138, 1.0, v138
	global_store_dwordx4 v[156:157], v[166:169], off offset:256 sc1
	v_rcp_f32_e32 v156, v138
	v_add_f32_e32 v138, 1.0, v151
	v_mul_f32_e32 v151, 0xbfb8aa3b, v41
	v_rcp_f32_e32 v157, v138
	v_add_f32_e32 v138, 1.0, v153
	v_exp_f32_e32 v151, v151
	v_mul_f32_e32 v153, 0xbfb8aa3b, v34
	v_exp_f32_e32 v153, v153
	v_rcp_f32_e32 v166, v138
	v_add_f32_e32 v138, 1.0, v151
	v_rcp_f32_e32 v167, v138
	v_add_f32_e32 v138, 1.0, v153
	v_mul_f32_e32 v151, 0xbfb8aa3b, v36
	v_rcp_f32_e32 v168, v138
	v_mul_f32_e32 v138, 0xbfb8aa3b, v35
	v_exp_f32_e32 v151, v151
	v_mul_f32_e32 v153, 0xbfb8aa3b, v37
	v_exp_f32_e32 v138, v138
	v_exp_f32_e32 v153, v153
	v_add_f32_e32 v151, 1.0, v151
	v_rcp_f32_e32 v170, v151
	v_add_f32_e32 v138, 1.0, v138
	v_add_f32_e32 v151, 1.0, v153
	v_rcp_f32_e32 v171, v151
	v_rcp_f32_e32 v169, v138
	v_mul_f32_e32 v138, 0xbfb8aa3b, v14
	v_exp_f32_e32 v138, v138
	v_mul_f32_e32 v151, 0xbfb8aa3b, v15
	v_pk_mul_f32 v[156:157], v[38:39], v[156:157]
	v_exp_f32_e32 v151, v151
	v_mul_f32_e32 v153, 0xbfb8aa3b, v16
	v_pk_mul_f32 v[172:173], v[40:41], v[166:167]
	v_pk_mul_f32 v[170:171], v[36:37], v[170:171]
	v_pk_mul_f32 v[168:169], v[34:35], v[168:169]
	v_cvt_pk_bf16_f32 v166, v156, v157
	v_lshl_add_u64 v[156:157], v[154:155], 0, s[18:19]
	s_mov_b32 s18, 0x28000
	v_exp_f32_e32 v153, v153
	v_cvt_pk_bf16_f32 v168, v168, v169
	v_cvt_pk_bf16_f32 v169, v170, v171
	v_add_co_u32_e32 v170, vcc, s18, v154
	v_cvt_pk_bf16_f32 v167, v172, v173
	s_nop 0
	v_addc_co_u32_e32 v171, vcc, 0, v155, vcc
	v_add_f32_e32 v138, 1.0, v138
	global_store_dwordx4 v[170:171], v[166:169], off sc1
	s_mov_b64 s[18:19], 0x2c000
	s_nop 0
	v_rcp_f32_e32 v166, v138
	v_add_f32_e32 v138, 1.0, v151
	v_mul_f32_e32 v151, 0xbfb8aa3b, v17
	v_rcp_f32_e32 v167, v138
	v_add_f32_e32 v138, 1.0, v153
	v_exp_f32_e32 v151, v151
	v_mul_f32_e32 v153, 0xbfb8aa3b, v10
	v_exp_f32_e32 v153, v153
	v_rcp_f32_e32 v168, v138
	v_add_f32_e32 v138, 1.0, v151
	v_rcp_f32_e32 v169, v138
	v_add_f32_e32 v138, 1.0, v153
	v_mul_f32_e32 v151, 0xbfb8aa3b, v12
	v_rcp_f32_e32 v170, v138
	v_mul_f32_e32 v138, 0xbfb8aa3b, v11
	v_exp_f32_e32 v151, v151
	v_mul_f32_e32 v153, 0xbfb8aa3b, v13
	v_exp_f32_e32 v138, v138
	v_exp_f32_e32 v153, v153
	v_add_f32_e32 v151, 1.0, v151
	v_rcp_f32_e32 v172, v151
	v_add_f32_e32 v138, 1.0, v138
	v_add_f32_e32 v151, 1.0, v153
	v_rcp_f32_e32 v173, v151
	v_rcp_f32_e32 v171, v138
	v_mul_f32_e32 v138, 0xbfb8aa3b, v22
	v_exp_f32_e32 v138, v138
	v_mul_f32_e32 v151, 0xbfb8aa3b, v23
	v_exp_f32_e32 v151, v151
	v_mul_f32_e32 v153, 0xbfb8aa3b, v24
	v_exp_f32_e32 v153, v153
	v_pk_mul_f32 v[168:169], v[16:17], v[168:169]
	v_pk_mul_f32 v[166:167], v[14:15], v[166:167]
	v_pk_mul_f32 v[172:173], v[12:13], v[172:173]
	v_pk_mul_f32 v[170:171], v[10:11], v[170:171]
	v_cvt_pk_bf16_f32 v166, v166, v167
	v_cvt_pk_bf16_f32 v167, v168, v169
	v_cvt_pk_bf16_f32 v168, v170, v171
	v_cvt_pk_bf16_f32 v169, v172, v173
	v_add_f32_e32 v138, 1.0, v138
	global_store_dwordx4 v[156:157], v[166:169], off offset:256 sc1
	v_rcp_f32_e32 v156, v138
	v_add_f32_e32 v138, 1.0, v151
	v_mul_f32_e32 v151, 0xbfb8aa3b, v25
	v_rcp_f32_e32 v157, v138
	v_add_f32_e32 v138, 1.0, v153
	v_exp_f32_e32 v151, v151
	v_mul_f32_e32 v153, 0xbfb8aa3b, v18
	v_exp_f32_e32 v153, v153
	v_rcp_f32_e32 v166, v138
	v_add_f32_e32 v138, 1.0, v151
	v_rcp_f32_e32 v167, v138
	v_add_f32_e32 v138, 1.0, v153
	v_mul_f32_e32 v151, 0xbfb8aa3b, v20
	v_rcp_f32_e32 v168, v138
	v_mul_f32_e32 v138, 0xbfb8aa3b, v19
	v_exp_f32_e32 v151, v151
	v_mul_f32_e32 v153, 0xbfb8aa3b, v21
	v_exp_f32_e32 v138, v138
	v_exp_f32_e32 v153, v153
	v_add_f32_e32 v151, 1.0, v151
	v_rcp_f32_e32 v170, v151
	v_add_f32_e32 v138, 1.0, v138
	v_add_f32_e32 v151, 1.0, v153
	v_rcp_f32_e32 v171, v151
	v_rcp_f32_e32 v169, v138
	v_mul_f32_e32 v138, 0xbfb8aa3b, v6
	v_exp_f32_e32 v138, v138
	v_mul_f32_e32 v151, 0xbfb8aa3b, v7
	v_pk_mul_f32 v[170:171], v[20:21], v[170:171]
	v_pk_mul_f32 v[168:169], v[18:19], v[168:169]
	v_exp_f32_e32 v151, v151
	v_mul_f32_e32 v153, 0xbfb8aa3b, v8
	v_cvt_pk_bf16_f32 v168, v168, v169
	v_cvt_pk_bf16_f32 v169, v170, v171
	v_lshl_add_u64 v[170:171], v[154:155], 0, s[18:19]
	s_mov_b32 s18, 0x2c000
	v_exp_f32_e32 v153, v153
	v_pk_mul_f32 v[172:173], v[24:25], v[166:167]
	v_pk_mul_f32 v[156:157], v[22:23], v[156:157]
	v_add_co_u32_e32 v154, vcc, s18, v154
	v_cvt_pk_bf16_f32 v166, v156, v157
	v_cvt_pk_bf16_f32 v167, v172, v173
	v_addc_co_u32_e32 v155, vcc, 0, v155, vcc
	v_add_f32_e32 v138, 1.0, v138
	global_store_dwordx4 v[154:155], v[166:169], off sc1
	v_rcp_f32_e32 v154, v138
	v_add_f32_e32 v138, 1.0, v151
	v_mul_f32_e32 v151, 0xbfb8aa3b, v9
	v_rcp_f32_e32 v155, v138
	v_add_f32_e32 v138, 1.0, v153
	v_exp_f32_e32 v151, v151
	v_mul_f32_e32 v153, 0xbfb8aa3b, v2
	v_exp_f32_e32 v153, v153
	v_rcp_f32_e32 v156, v138
	v_add_f32_e32 v138, 1.0, v151
	v_rcp_f32_e32 v157, v138
	v_add_f32_e32 v138, 1.0, v153
	v_mul_f32_e32 v151, 0xbfb8aa3b, v4
	v_rcp_f32_e32 v166, v138
	v_mul_f32_e32 v138, 0xbfb8aa3b, v3
	v_exp_f32_e32 v151, v151
	v_mul_f32_e32 v153, 0xbfb8aa3b, v5
	v_exp_f32_e32 v138, v138
	v_exp_f32_e32 v153, v153
	v_add_f32_e32 v151, 1.0, v151
	v_rcp_f32_e32 v168, v151
	v_add_f32_e32 v138, 1.0, v138
	v_add_f32_e32 v151, 1.0, v153
	v_rcp_f32_e32 v169, v151
	v_rcp_f32_e32 v167, v138
	v_pk_mul_f32 v[156:157], v[8:9], v[156:157]
	v_pk_mul_f32 v[154:155], v[6:7], v[154:155]
	v_pk_mul_f32 v[168:169], v[4:5], v[168:169]
	v_pk_mul_f32 v[166:167], v[2:3], v[166:167]
	v_cvt_pk_bf16_f32 v154, v154, v155
	v_cvt_pk_bf16_f32 v155, v156, v157
	v_cvt_pk_bf16_f32 v156, v166, v167
	v_cvt_pk_bf16_f32 v157, v168, v169
	global_store_dwordx4 v[170:171], v[154:157], off offset:256 sc1

.LBB0_182:
	s_ashr_i32 s21, s17, 5
	v_lshl_or_b32 v153, s88, 13, v162
	v_cvt_pk_bf16_f32 v126, v126, v127
	v_cvt_pk_bf16_f32 v127, v128, v129
	v_cvt_pk_bf16_f32 v128, v122, v123
	v_add_u32_e32 v122, s21, v153
	v_cvt_pk_bf16_f32 v129, v124, v125
	v_mad_i64_i32 v[122:123], s[18:19], v122, s87, v[140:141]
	global_store_dwordx4 v[122:123], v[126:129], off sc1
	v_cvt_pk_bf16_f32 v110, v110, v111
	v_cvt_pk_bf16_f32 v111, v112, v113
	v_or_b32_e32 v126, 0x1000, v153
	v_cvt_pk_bf16_f32 v112, v106, v107
	v_add_u32_e32 v106, s21, v126
	v_mad_i64_i32 v[124:125], s[18:19], v106, s87, v[140:141]
	v_cvt_pk_bf16_f32 v94, v94, v95
	v_cvt_pk_bf16_f32 v95, v96, v97
	v_cvt_pk_bf16_f32 v96, v90, v91
	v_cvt_pk_bf16_f32 v97, v92, v93
	s_or_b32 s21, s21, 1
	global_store_dwordx4 v[124:125], v[94:97], off offset:512 sc1
	v_cvt_pk_bf16_f32 v90, v102, v103
	v_cvt_pk_bf16_f32 v91, v104, v105
	v_add_u32_e32 v94, s21, v153
	v_cvt_pk_bf16_f32 v92, v98, v99
	v_cvt_pk_bf16_f32 v93, v100, v101
	v_mad_i64_i32 v[94:95], s[18:19], v94, s87, v[140:141]
	global_store_dwordx4 v[94:95], v[90:93], off sc1
	v_cvt_pk_bf16_f32 v78, v78, v79
	v_cvt_pk_bf16_f32 v79, v80, v81
	v_cvt_pk_bf16_f32 v80, v74, v75
	v_add_u32_e32 v74, s21, v126
	v_or_b32_e32 v90, 48, v152
	v_cvt_pk_bf16_f32 v81, v76, v77
	v_mad_i64_i32 v[74:75], s[18:19], v74, s87, v[140:141]
	v_ashrrev_i32_e32 v91, 5, v90
	global_store_dwordx4 v[74:75], v[78:81], off sc1
	v_cvt_pk_bf16_f32 v70, v70, v71
	v_cvt_pk_bf16_f32 v71, v72, v73
	v_add_u32_e32 v80, v91, v153
	v_mov_b64_e32 v[78:79], s[28:29]
	v_cvt_pk_bf16_f32 v72, v66, v67
	v_add_u32_e32 v66, v91, v126
	v_mad_i64_i32 v[80:81], s[18:19], v80, s87, v[78:79]
	v_mad_i64_i32 v[66:67], s[18:19], v66, s87, v[78:79]
	v_cvt_pk_bf16_f32 v76, v82, v83
	v_lshlrev_b32_e32 v82, 5, v90
	s_add_i32 s18, s17, 0x80
	v_and_b32_e32 v138, 0x3e0, v82
	s_ashr_i32 s21, s18, 5
	v_lshl_add_u64 v[80:81], v[80:81], 0, v[138:139]
	v_mov_b32_e32 v151, v139
	v_lshl_add_u64 v[66:67], v[66:67], 0, v[138:139]
	v_cvt_pk_bf16_f32 v46, v46, v47
	v_cvt_pk_bf16_f32 v47, v48, v49
	v_cvt_pk_bf16_f32 v48, v42, v43
	v_add_u32_e32 v42, s21, v126
	v_cvt_pk_bf16_f32 v113, v108, v109
	v_cvt_pk_bf16_f32 v106, v118, v119
	v_cvt_pk_bf16_f32 v107, v120, v121
	v_cvt_pk_bf16_f32 v108, v114, v115
	v_cvt_pk_bf16_f32 v109, v116, v117
	v_cvt_pk_bf16_f32 v74, v86, v87
	v_cvt_pk_bf16_f32 v75, v88, v89
	v_cvt_pk_bf16_f32 v77, v84, v85
	v_lshl_add_u64 v[80:81], v[80:81], 0, v[150:151]
	v_cvt_pk_bf16_f32 v73, v68, v69
	v_lshl_add_u64 v[66:67], v[66:67], 0, v[150:151]
	v_cvt_pk_bf16_f32 v49, v44, v45
	v_mad_i64_i32 v[42:43], s[18:19], v42, s87, v[140:141]
	global_store_dwordx4 v[124:125], v[110:113], off sc1
	global_store_dwordx4 v[122:123], v[106:109], off offset:512 sc1
	global_store_dwordx4 v[80:81], v[74:77], off sc1
	global_store_dwordx4 v[66:67], v[70:73], off sc1
	global_store_dwordx4 v[42:43], v[46:49], off sc1
	v_cvt_pk_bf16_f32 v30, v30, v31
	v_cvt_pk_bf16_f32 v31, v32, v33
	v_add_u32_e32 v48, 0x90, v152
	v_ashrrev_i32_e32 v49, 5, v48
	v_add_u32_e32 v46, v49, v153
	v_lshlrev_b32_e32 v48, 5, v48
	v_cvt_pk_bf16_f32 v32, v26, v27
	v_add_u32_e32 v26, v49, v126
	s_addk_i32 s17, 0xa0
	v_mad_i64_i32 v[46:47], s[18:19], v46, s87, v[78:79]
	v_and_b32_e32 v138, 0x3e0, v48
	v_mad_i64_i32 v[26:27], s[18:19], v26, s87, v[78:79]
	s_ashr_i32 s17, s17, 5
	v_cvt_pk_bf16_f32 v62, v62, v63
	v_cvt_pk_bf16_f32 v63, v64, v65
	v_cvt_pk_bf16_f32 v64, v58, v59
	v_add_u32_e32 v58, s21, v153
	v_lshl_add_u64 v[46:47], v[46:47], 0, v[138:139]
	v_lshl_add_u64 v[26:27], v[26:27], 0, v[138:139]
	v_cvt_pk_bf16_f32 v14, v14, v15
	v_cvt_pk_bf16_f32 v15, v16, v17
	v_cvt_pk_bf16_f32 v16, v10, v11
	v_add_u32_e32 v10, s17, v126
	v_cvt_pk_bf16_f32 v65, v60, v61
	v_mad_i64_i32 v[58:59], s[18:19], v58, s87, v[140:141]
	v_cvt_pk_bf16_f32 v42, v54, v55
	v_cvt_pk_bf16_f32 v43, v56, v57
	v_cvt_pk_bf16_f32 v44, v50, v51
	v_cvt_pk_bf16_f32 v45, v52, v53
	v_lshl_add_u64 v[46:47], v[46:47], 0, v[150:151]
	v_cvt_pk_bf16_f32 v33, v28, v29
	v_lshl_add_u64 v[26:27], v[26:27], 0, v[150:151]
	v_cvt_pk_bf16_f32 v17, v12, v13
	v_mad_i64_i32 v[10:11], s[18:19], v10, s87, v[140:141]
	global_store_dwordx4 v[58:59], v[62:65], off sc1
	global_store_dwordx4 v[46:47], v[42:45], off sc1
	global_store_dwordx4 v[26:27], v[30:33], off sc1
	global_store_dwordx4 v[10:11], v[14:17], off sc1
	v_cvt_pk_bf16_f32 v6, v6, v7
	v_cvt_pk_bf16_f32 v7, v8, v9
	v_add_u32_e32 v16, 0xb0, v152
	v_ashrrev_i32_e32 v17, 5, v16
	v_add_u32_e32 v14, v17, v153
	v_lshlrev_b32_e32 v16, 5, v16
	v_cvt_pk_bf16_f32 v8, v2, v3
	v_add_u32_e32 v2, v17, v126
	v_mad_i64_i32 v[14:15], s[18:19], v14, s87, v[78:79]
	v_and_b32_e32 v138, 0x3e0, v16
	v_mad_i64_i32 v[2:3], s[18:19], v2, s87, v[78:79]
	v_add_u32_e32 v30, s17, v153
	v_lshl_add_u64 v[14:15], v[14:15], 0, v[138:139]
	v_lshl_add_u64 v[2:3], v[2:3], 0, v[138:139]
	v_cvt_pk_bf16_f32 v26, v38, v39
	v_cvt_pk_bf16_f32 v27, v40, v41
	v_cvt_pk_bf16_f32 v28, v34, v35
	v_cvt_pk_bf16_f32 v29, v36, v37
	v_mad_i64_i32 v[30:31], s[18:19], v30, s87, v[140:141]
	v_cvt_pk_bf16_f32 v10, v22, v23
	v_cvt_pk_bf16_f32 v11, v24, v25
	v_cvt_pk_bf16_f32 v12, v18, v19
	v_cvt_pk_bf16_f32 v13, v20, v21
	v_lshl_add_u64 v[14:15], v[14:15], 0, v[150:151]
	v_cvt_pk_bf16_f32 v9, v4, v5
	v_lshl_add_u64 v[2:3], v[2:3], 0, v[150:151]
	global_store_dwordx4 v[30:31], v[26:29], off sc1
	global_store_dwordx4 v[14:15], v[10:13], off sc1
	global_store_dwordx4 v[2:3], v[6:9], off sc1
	s_andn2_b64 vcc, exec, s[0:1]
	s_mov_b64 s[0:1], -1
	s_cbranch_vccnz .LBB0_159

.LBB0_272:
	s_or_b64 exec, exec, s[14:15]
	v_lshlrev_b64 v[58:59], 11, v[28:29]
	v_or_b32_e32 v58, v58, v26
	v_lshl_add_u64 v[50:51], s[34:35], 0, v[58:59]
	global_load_dwordx4 v[50:53], v[50:51], off nt
	v_lshl_add_u64 v[54:55], s[4:5], 0, v[58:59]
	global_load_dwordx4 v[54:57], v[54:55], off nt
	s_waitcnt vmcnt(0)
	v_pk_mul_f32 v[44:45], v[16:17], v[44:45]
	v_pk_mul_f32 v[42:43], v[14:15], v[42:43]
	v_pk_mul_f32 v[40:41], v[10:11], v[40:41]
	v_pk_mul_f32 v[38:39], v[12:13], v[38:39]
	v_or_b32_e32 v60, 1, v28
	v_pk_fma_f32 v[44:45], v[24:25], v[36:37], v[44:45]
	v_pk_fma_f32 v[42:43], v[22:23], v[32:33], v[42:43]
	v_pk_fma_f32 v[38:39], v[20:21], v[34:35], v[38:39]
	v_pk_fma_f32 v[40:41], v[18:19], v[30:31], v[40:41]
	v_ashrrev_i32_e32 v61, 31, v60
	v_lshlrev_b64 v[60:61], 11, v[60:61]
	v_lshl_add_u64 v[58:59], s[6:7], 0, v[58:59]
	v_or_b32_e32 v60, v60, v26
	v_lshl_add_u64 v[62:63], s[34:35], 0, v[60:61]
	v_add_u32_e32 v46, s16, v46
	v_cmp_lt_i32_e32 vcc, s17, v46
	s_or_b64 s[12:13], vcc, s[12:13]
	v_add_u32_e32 v47, s2, v47
	v_lshlrev_b32_e32 v64, 16, v50
	v_and_b32_e32 v65, 0xffff0000, v50
	v_lshlrev_b32_e32 v50, 16, v51
	v_and_b32_e32 v51, 0xffff0000, v51
	v_lshlrev_b32_e32 v66, 16, v52
	v_and_b32_e32 v67, 0xffff0000, v52
	v_lshlrev_b32_e32 v52, 16, v53
	v_and_b32_e32 v53, 0xffff0000, v53
	v_lshlrev_b32_e32 v68, 16, v54
	v_and_b32_e32 v69, 0xffff0000, v54
	v_lshlrev_b32_e32 v54, 16, v55
	v_and_b32_e32 v55, 0xffff0000, v55
	v_lshlrev_b32_e32 v70, 16, v56
	v_and_b32_e32 v71, 0xffff0000, v56
	v_lshlrev_b32_e32 v56, 16, v57
	v_and_b32_e32 v57, 0xffff0000, v57
	v_pk_fma_f32 v[42:43], v[6:7], v[64:65], v[42:43]
	v_pk_fma_f32 v[44:45], v[8:9], v[50:51], v[44:45]
	v_pk_fma_f32 v[40:41], v[2:3], v[66:67], v[40:41]
	v_pk_fma_f32 v[38:39], v[4:5], v[52:53], v[38:39]
	v_pk_mul_f32 v[44:45], v[44:45], v[54:55]
	v_pk_mul_f32 v[42:43], v[42:43], v[68:69]
	v_pk_mul_f32 v[54:55], v[38:39], v[56:57]
	v_pk_mul_f32 v[40:41], v[40:41], v[70:71]
	v_cvt_pk_bf16_f32 v38, v42, v43
	v_cvt_pk_bf16_f32 v39, v44, v45
	v_cvt_pk_bf16_f32 v40, v40, v41
	v_cvt_pk_bf16_f32 v41, v54, v55
	global_store_dwordx4 v[58:59], v[38:41], off
	global_load_dwordx4 v[38:41], v[62:63], off nt
	v_lshl_add_u64 v[42:43], s[4:5], 0, v[60:61]
	global_load_dwordx4 v[42:45], v[42:43], off nt
	v_lshl_add_u64 v[56:57], s[6:7], 0, v[60:61]
	v_pk_mul_f32 v[60:61], v[22:23], v[64:65]
	v_pk_mul_f32 v[62:63], v[24:25], v[50:51]
	v_pk_mul_f32 v[68:69], v[18:19], v[66:67]
	v_pk_mul_f32 v[70:71], v[20:21], v[52:53]
	v_or_b32_e32 v54, 2, v28
	v_pk_fma_f32 v[36:37], v[16:17], v[36:37], v[62:63]
	v_pk_fma_f32 v[32:33], v[14:15], v[32:33], v[60:61]
	v_pk_fma_f32 v[34:35], v[12:13], v[34:35], v[70:71]
	v_pk_fma_f32 v[30:31], v[10:11], v[30:31], v[68:69]
	v_ashrrev_i32_e32 v55, 31, v54
	v_lshlrev_b64 v[54:55], 11, v[54:55]
	v_or_b32_e32 v54, v54, v26
	v_lshl_add_u64 v[58:59], s[34:35], 0, v[54:55]
	s_waitcnt vmcnt(1)
	v_lshlrev_b32_e32 v60, 16, v38
	v_and_b32_e32 v61, 0xffff0000, v38
	v_lshlrev_b32_e32 v38, 16, v39
	v_and_b32_e32 v39, 0xffff0000, v39
	v_lshlrev_b32_e32 v62, 16, v40
	v_and_b32_e32 v63, 0xffff0000, v40
	v_lshlrev_b32_e32 v40, 16, v41
	v_and_b32_e32 v41, 0xffff0000, v41
	s_waitcnt vmcnt(0)
	v_lshlrev_b32_e32 v68, 16, v42
	v_and_b32_e32 v69, 0xffff0000, v42
	v_lshlrev_b32_e32 v42, 16, v43
	v_and_b32_e32 v43, 0xffff0000, v43
	v_lshlrev_b32_e32 v70, 16, v44
	v_and_b32_e32 v71, 0xffff0000, v44
	v_lshlrev_b32_e32 v44, 16, v45
	v_and_b32_e32 v45, 0xffff0000, v45
	v_pk_fma_f32 v[32:33], v[6:7], v[60:61], v[32:33]
	v_pk_fma_f32 v[36:37], v[8:9], v[38:39], v[36:37]
	v_pk_fma_f32 v[30:31], v[2:3], v[62:63], v[30:31]
	v_pk_fma_f32 v[34:35], v[4:5], v[40:41], v[34:35]
	v_pk_mul_f32 v[36:37], v[36:37], v[42:43]
	v_pk_mul_f32 v[32:33], v[32:33], v[68:69]
	v_pk_mul_f32 v[34:35], v[34:35], v[44:45]
	v_pk_mul_f32 v[42:43], v[30:31], v[70:71]
	v_cvt_pk_bf16_f32 v30, v32, v33
	v_cvt_pk_bf16_f32 v31, v36, v37
	v_cvt_pk_bf16_f32 v32, v42, v43
	v_cvt_pk_bf16_f32 v33, v34, v35
	global_store_dwordx4 v[56:57], v[30:33], off
	global_load_dwordx4 v[30:33], v[58:59], off nt
	v_lshl_add_u64 v[34:35], s[4:5], 0, v[54:55]
	global_load_dwordx4 v[34:37], v[34:35], off nt
	v_pk_mul_f32 v[56:57], v[22:23], v[60:61]
	v_pk_mul_f32 v[58:59], v[24:25], v[38:39]
	v_pk_mul_f32 v[68:69], v[18:19], v[62:63]
	v_pk_mul_f32 v[70:71], v[20:21], v[40:41]
	v_or_b32_e32 v42, 3, v28
	v_pk_fma_f32 v[50:51], v[16:17], v[50:51], v[58:59]
	v_pk_fma_f32 v[56:57], v[14:15], v[64:65], v[56:57]
	v_pk_fma_f32 v[52:53], v[12:13], v[52:53], v[70:71]
	v_pk_fma_f32 v[58:59], v[10:11], v[66:67], v[68:69]
	v_ashrrev_i32_e32 v43, 31, v42
	v_lshlrev_b64 v[42:43], 11, v[42:43]
	v_or_b32_e32 v42, v42, v26
	v_lshl_add_u64 v[44:45], s[6:7], 0, v[54:55]
	v_lshl_add_u64 v[54:55], s[34:35], 0, v[42:43]
	s_waitcnt vmcnt(1)
	v_lshlrev_b32_e32 v64, 16, v30
	v_and_b32_e32 v65, 0xffff0000, v30
	v_lshlrev_b32_e32 v66, 16, v31
	v_and_b32_e32 v67, 0xffff0000, v31
	v_lshlrev_b32_e32 v68, 16, v32
	v_and_b32_e32 v69, 0xffff0000, v32
	v_lshlrev_b32_e32 v70, 16, v33
	v_and_b32_e32 v71, 0xffff0000, v33
	s_waitcnt vmcnt(0)
	v_lshlrev_b32_e32 v30, 16, v34
	v_and_b32_e32 v31, 0xffff0000, v34
	v_lshlrev_b32_e32 v32, 16, v35
	v_and_b32_e32 v33, 0xffff0000, v35
	v_lshlrev_b32_e32 v34, 16, v36
	v_and_b32_e32 v35, 0xffff0000, v36
	v_lshlrev_b32_e32 v36, 16, v37
	v_and_b32_e32 v37, 0xffff0000, v37
	v_pk_fma_f32 v[56:57], v[6:7], v[64:65], v[56:57]
	v_pk_fma_f32 v[50:51], v[8:9], v[66:67], v[50:51]
	v_pk_fma_f32 v[58:59], v[2:3], v[68:69], v[58:59]
	v_pk_fma_f32 v[52:53], v[4:5], v[70:71], v[52:53]
	v_pk_mul_f32 v[32:33], v[50:51], v[32:33]
	v_pk_mul_f32 v[30:31], v[56:57], v[30:31]
	v_pk_mul_f32 v[36:37], v[52:53], v[36:37]
	v_pk_mul_f32 v[34:35], v[58:59], v[34:35]
	v_cvt_pk_bf16_f32 v30, v30, v31
	v_cvt_pk_bf16_f32 v31, v32, v33
	v_cvt_pk_bf16_f32 v32, v34, v35
	v_cvt_pk_bf16_f32 v33, v36, v37
	global_store_dwordx4 v[44:45], v[30:33], off
	global_load_dwordx4 v[30:33], v[54:55], off nt
	v_lshl_add_u64 v[34:35], s[4:5], 0, v[42:43]
	global_load_dwordx4 v[34:37], v[34:35], off nt
	v_pk_mul_f32 v[52:53], v[22:23], v[64:65]
	v_pk_mul_f32 v[54:55], v[24:25], v[66:67]
	v_pk_mul_f32 v[56:57], v[18:19], v[68:69]
	v_pk_mul_f32 v[58:59], v[20:21], v[70:71]
	v_or_b32_e32 v44, 4, v28
	v_pk_fma_f32 v[38:39], v[16:17], v[38:39], v[54:55]
	v_pk_fma_f32 v[52:53], v[14:15], v[60:61], v[52:53]
	v_pk_fma_f32 v[40:41], v[12:13], v[40:41], v[58:59]
	v_pk_fma_f32 v[54:55], v[10:11], v[62:63], v[56:57]
	v_ashrrev_i32_e32 v45, 31, v44
	v_lshlrev_b64 v[44:45], 11, v[44:45]
	v_or_b32_e32 v44, v44, v26
	v_lshl_add_u64 v[42:43], s[6:7], 0, v[42:43]
	v_lshl_add_u64 v[50:51], s[34:35], 0, v[44:45]
	s_waitcnt vmcnt(1)
	v_lshlrev_b32_e32 v56, 16, v30
	v_and_b32_e32 v57, 0xffff0000, v30
	v_lshlrev_b32_e32 v58, 16, v31
	v_and_b32_e32 v59, 0xffff0000, v31
	v_lshlrev_b32_e32 v60, 16, v32
	v_and_b32_e32 v61, 0xffff0000, v32
	v_lshlrev_b32_e32 v62, 16, v33
	v_and_b32_e32 v63, 0xffff0000, v33
	s_waitcnt vmcnt(0)
	v_lshlrev_b32_e32 v30, 16, v34
	v_and_b32_e32 v31, 0xffff0000, v34
	v_lshlrev_b32_e32 v32, 16, v35
	v_and_b32_e32 v33, 0xffff0000, v35
	v_lshlrev_b32_e32 v34, 16, v36
	v_and_b32_e32 v35, 0xffff0000, v36
	v_lshlrev_b32_e32 v36, 16, v37
	v_and_b32_e32 v37, 0xffff0000, v37
	v_pk_fma_f32 v[52:53], v[6:7], v[56:57], v[52:53]
	v_pk_fma_f32 v[38:39], v[8:9], v[58:59], v[38:39]
	v_pk_fma_f32 v[54:55], v[2:3], v[60:61], v[54:55]
	v_pk_fma_f32 v[40:41], v[4:5], v[62:63], v[40:41]
	v_pk_mul_f32 v[32:33], v[38:39], v[32:33]
	v_pk_mul_f32 v[30:31], v[52:53], v[30:31]
	v_pk_mul_f32 v[36:37], v[40:41], v[36:37]
	v_pk_mul_f32 v[34:35], v[54:55], v[34:35]
	v_cvt_pk_bf16_f32 v30, v30, v31
	v_cvt_pk_bf16_f32 v31, v32, v33
	v_cvt_pk_bf16_f32 v32, v34, v35
	v_cvt_pk_bf16_f32 v33, v36, v37
	global_store_dwordx4 v[42:43], v[30:33], off
	global_load_dwordx4 v[30:33], v[50:51], off nt
	v_lshl_add_u64 v[34:35], s[4:5], 0, v[44:45]
	global_load_dwordx4 v[34:37], v[34:35], off nt
	v_lshl_add_u64 v[40:41], s[6:7], 0, v[44:45]
	v_pk_mul_f32 v[44:45], v[22:23], v[56:57]
	v_pk_mul_f32 v[50:51], v[24:25], v[58:59]
	v_pk_mul_f32 v[52:53], v[18:19], v[60:61]
	v_pk_mul_f32 v[54:55], v[20:21], v[62:63]
	v_or_b32_e32 v38, 5, v28
	v_pk_fma_f32 v[50:51], v[16:17], v[66:67], v[50:51]
	v_pk_fma_f32 v[44:45], v[14:15], v[64:65], v[44:45]
	v_pk_fma_f32 v[54:55], v[12:13], v[70:71], v[54:55]
	v_pk_fma_f32 v[52:53], v[10:11], v[68:69], v[52:53]
	v_ashrrev_i32_e32 v39, 31, v38
	v_lshlrev_b64 v[38:39], 11, v[38:39]
	v_or_b32_e32 v38, v38, v26
	v_lshl_add_u64 v[42:43], s[34:35], 0, v[38:39]
	s_waitcnt vmcnt(1)
	v_lshlrev_b32_e32 v64, 16, v30
	v_and_b32_e32 v65, 0xffff0000, v30
	v_lshlrev_b32_e32 v66, 16, v31
	v_and_b32_e32 v67, 0xffff0000, v31
	v_lshlrev_b32_e32 v68, 16, v32
	v_and_b32_e32 v69, 0xffff0000, v32
	v_lshlrev_b32_e32 v70, 16, v33
	v_and_b32_e32 v71, 0xffff0000, v33
	s_waitcnt vmcnt(0)
	v_lshlrev_b32_e32 v30, 16, v34
	v_and_b32_e32 v31, 0xffff0000, v34
	v_lshlrev_b32_e32 v32, 16, v35
	v_and_b32_e32 v33, 0xffff0000, v35
	v_lshlrev_b32_e32 v34, 16, v36
	v_and_b32_e32 v35, 0xffff0000, v36
	v_lshlrev_b32_e32 v36, 16, v37
	v_and_b32_e32 v37, 0xffff0000, v37
	v_pk_fma_f32 v[44:45], v[6:7], v[64:65], v[44:45]
	v_pk_fma_f32 v[50:51], v[8:9], v[66:67], v[50:51]
	v_pk_fma_f32 v[52:53], v[2:3], v[68:69], v[52:53]
	v_pk_fma_f32 v[54:55], v[4:5], v[70:71], v[54:55]
	v_pk_mul_f32 v[32:33], v[50:51], v[32:33]
	v_pk_mul_f32 v[30:31], v[44:45], v[30:31]
	v_pk_mul_f32 v[36:37], v[54:55], v[36:37]
	v_pk_mul_f32 v[34:35], v[52:53], v[34:35]
	v_cvt_pk_bf16_f32 v30, v30, v31
	v_cvt_pk_bf16_f32 v31, v32, v33
	v_cvt_pk_bf16_f32 v32, v34, v35
	v_cvt_pk_bf16_f32 v33, v36, v37
	global_store_dwordx4 v[40:41], v[30:33], off
	global_load_dwordx4 v[30:33], v[42:43], off nt
	v_lshl_add_u64 v[34:35], s[4:5], 0, v[38:39]
	global_load_dwordx4 v[34:37], v[34:35], off nt
	v_pk_mul_f32 v[44:45], v[22:23], v[64:65]
	v_pk_mul_f32 v[50:51], v[24:25], v[66:67]
	v_pk_mul_f32 v[52:53], v[18:19], v[68:69]
	v_pk_mul_f32 v[54:55], v[20:21], v[70:71]
	v_or_b32_e32 v40, 6, v28
	v_pk_fma_f32 v[50:51], v[16:17], v[58:59], v[50:51]
	v_pk_fma_f32 v[44:45], v[14:15], v[56:57], v[44:45]
	v_pk_fma_f32 v[54:55], v[12:13], v[62:63], v[54:55]
	v_pk_fma_f32 v[52:53], v[10:11], v[60:61], v[52:53]
	v_ashrrev_i32_e32 v41, 31, v40
	v_lshlrev_b64 v[40:41], 11, v[40:41]
	v_or_b32_e32 v40, v40, v26
	v_lshl_add_u64 v[38:39], s[6:7], 0, v[38:39]
	v_lshl_add_u64 v[42:43], s[34:35], 0, v[40:41]
	s_waitcnt vmcnt(1)
	v_lshlrev_b32_e32 v56, 16, v30
	v_and_b32_e32 v57, 0xffff0000, v30
	v_lshlrev_b32_e32 v58, 16, v31
	v_and_b32_e32 v59, 0xffff0000, v31
	v_lshlrev_b32_e32 v60, 16, v32
	v_and_b32_e32 v61, 0xffff0000, v32
	v_lshlrev_b32_e32 v62, 16, v33
	v_and_b32_e32 v63, 0xffff0000, v33
	s_waitcnt vmcnt(0)
	v_lshlrev_b32_e32 v30, 16, v34
	v_and_b32_e32 v31, 0xffff0000, v34
	v_lshlrev_b32_e32 v32, 16, v35
	v_and_b32_e32 v33, 0xffff0000, v35
	v_lshlrev_b32_e32 v34, 16, v36
	v_and_b32_e32 v35, 0xffff0000, v36
	v_lshlrev_b32_e32 v36, 16, v37
	v_and_b32_e32 v37, 0xffff0000, v37
	v_pk_fma_f32 v[44:45], v[6:7], v[56:57], v[44:45]
	v_pk_fma_f32 v[50:51], v[8:9], v[58:59], v[50:51]
	v_pk_fma_f32 v[52:53], v[2:3], v[60:61], v[52:53]
	v_pk_fma_f32 v[54:55], v[4:5], v[62:63], v[54:55]
	v_pk_mul_f32 v[32:33], v[50:51], v[32:33]
	v_pk_mul_f32 v[30:31], v[44:45], v[30:31]
	v_pk_mul_f32 v[36:37], v[54:55], v[36:37]
	v_pk_mul_f32 v[34:35], v[52:53], v[34:35]
	v_cvt_pk_bf16_f32 v30, v30, v31
	v_cvt_pk_bf16_f32 v31, v32, v33
	v_cvt_pk_bf16_f32 v32, v34, v35
	v_cvt_pk_bf16_f32 v33, v36, v37
	global_store_dwordx4 v[38:39], v[30:33], off
	global_load_dwordx4 v[30:33], v[42:43], off nt
	v_lshl_add_u64 v[34:35], s[4:5], 0, v[40:41]
	global_load_dwordx4 v[34:37], v[34:35], off nt
	v_pk_mul_f32 v[44:45], v[22:23], v[56:57]
	v_pk_mul_f32 v[50:51], v[24:25], v[58:59]
	v_pk_mul_f32 v[52:53], v[18:19], v[60:61]
	v_pk_mul_f32 v[54:55], v[20:21], v[62:63]
	v_or_b32_e32 v38, 7, v28
	v_pk_fma_f32 v[50:51], v[16:17], v[66:67], v[50:51]
	v_pk_fma_f32 v[44:45], v[14:15], v[64:65], v[44:45]
	v_pk_fma_f32 v[54:55], v[12:13], v[70:71], v[54:55]
	v_pk_fma_f32 v[52:53], v[10:11], v[68:69], v[52:53]
	v_ashrrev_i32_e32 v39, 31, v38
	v_lshlrev_b64 v[38:39], 11, v[38:39]
	v_or_b32_e32 v38, v38, v26
	v_lshl_add_u64 v[40:41], s[6:7], 0, v[40:41]
	v_lshl_add_u64 v[42:43], s[34:35], 0, v[38:39]
	s_waitcnt vmcnt(1)
	v_lshlrev_b32_e32 v64, 16, v30
	v_and_b32_e32 v65, 0xffff0000, v30
	v_lshlrev_b32_e32 v66, 16, v31
	v_and_b32_e32 v67, 0xffff0000, v31
	v_lshlrev_b32_e32 v68, 16, v32
	v_and_b32_e32 v69, 0xffff0000, v32
	v_lshlrev_b32_e32 v70, 16, v33
	v_and_b32_e32 v71, 0xffff0000, v33
	s_waitcnt vmcnt(0)
	v_lshlrev_b32_e32 v30, 16, v34
	v_and_b32_e32 v31, 0xffff0000, v34
	v_lshlrev_b32_e32 v32, 16, v35
	v_and_b32_e32 v33, 0xffff0000, v35
	v_lshlrev_b32_e32 v34, 16, v36
	v_and_b32_e32 v35, 0xffff0000, v36
	v_lshlrev_b32_e32 v36, 16, v37
	v_and_b32_e32 v37, 0xffff0000, v37
	v_pk_fma_f32 v[44:45], v[6:7], v[64:65], v[44:45]
	v_pk_fma_f32 v[50:51], v[8:9], v[66:67], v[50:51]
	v_pk_fma_f32 v[52:53], v[2:3], v[68:69], v[52:53]
	v_pk_fma_f32 v[54:55], v[4:5], v[70:71], v[54:55]
	v_pk_mul_f32 v[32:33], v[50:51], v[32:33]
	v_pk_mul_f32 v[30:31], v[44:45], v[30:31]
	v_pk_mul_f32 v[36:37], v[54:55], v[36:37]
	v_pk_mul_f32 v[34:35], v[52:53], v[34:35]
	v_cvt_pk_bf16_f32 v30, v30, v31
	v_cvt_pk_bf16_f32 v31, v32, v33
	v_cvt_pk_bf16_f32 v32, v34, v35
	v_cvt_pk_bf16_f32 v33, v36, v37
	global_store_dwordx4 v[40:41], v[30:33], off
	global_load_dwordx4 v[30:33], v[42:43], off nt
	v_lshl_add_u64 v[34:35], s[4:5], 0, v[38:39]
	global_load_dwordx4 v[34:37], v[34:35], off nt
	v_pk_mul_f32 v[44:45], v[22:23], v[64:65]
	v_pk_mul_f32 v[50:51], v[24:25], v[66:67]
	v_pk_mul_f32 v[52:53], v[18:19], v[68:69]
	v_pk_mul_f32 v[54:55], v[20:21], v[70:71]
	v_or_b32_e32 v40, 8, v28
	v_pk_fma_f32 v[50:51], v[16:17], v[58:59], v[50:51]
	v_pk_fma_f32 v[44:45], v[14:15], v[56:57], v[44:45]
	v_pk_fma_f32 v[54:55], v[12:13], v[62:63], v[54:55]
	v_pk_fma_f32 v[52:53], v[10:11], v[60:61], v[52:53]
	v_ashrrev_i32_e32 v41, 31, v40
	v_lshlrev_b64 v[40:41], 11, v[40:41]
	v_or_b32_e32 v40, v40, v26
	v_lshl_add_u64 v[38:39], s[6:7], 0, v[38:39]
	v_lshl_add_u64 v[42:43], s[34:35], 0, v[40:41]
	s_waitcnt vmcnt(1)
	v_lshlrev_b32_e32 v56, 16, v30
	v_and_b32_e32 v57, 0xffff0000, v30
	v_lshlrev_b32_e32 v58, 16, v31
	v_and_b32_e32 v59, 0xffff0000, v31
	v_lshlrev_b32_e32 v60, 16, v32
	v_and_b32_e32 v61, 0xffff0000, v32
	v_lshlrev_b32_e32 v62, 16, v33
	v_and_b32_e32 v63, 0xffff0000, v33
	s_waitcnt vmcnt(0)
	v_lshlrev_b32_e32 v30, 16, v34
	v_and_b32_e32 v31, 0xffff0000, v34
	v_lshlrev_b32_e32 v32, 16, v35
	v_and_b32_e32 v33, 0xffff0000, v35
	v_lshlrev_b32_e32 v34, 16, v36
	v_and_b32_e32 v35, 0xffff0000, v36
	v_lshlrev_b32_e32 v36, 16, v37
	v_and_b32_e32 v37, 0xffff0000, v37
	v_pk_fma_f32 v[44:45], v[6:7], v[56:57], v[44:45]
	v_pk_fma_f32 v[50:51], v[8:9], v[58:59], v[50:51]
	v_pk_fma_f32 v[52:53], v[2:3], v[60:61], v[52:53]
	v_pk_fma_f32 v[54:55], v[4:5], v[62:63], v[54:55]
	v_pk_mul_f32 v[32:33], v[50:51], v[32:33]
	v_pk_mul_f32 v[30:31], v[44:45], v[30:31]
	v_pk_mul_f32 v[36:37], v[54:55], v[36:37]
	v_pk_mul_f32 v[34:35], v[52:53], v[34:35]
	v_cvt_pk_bf16_f32 v30, v30, v31
	v_cvt_pk_bf16_f32 v31, v32, v33
	v_cvt_pk_bf16_f32 v32, v34, v35
	v_cvt_pk_bf16_f32 v33, v36, v37
	global_store_dwordx4 v[38:39], v[30:33], off
	global_load_dwordx4 v[30:33], v[42:43], off nt
	v_lshl_add_u64 v[34:35], s[4:5], 0, v[40:41]
	global_load_dwordx4 v[34:37], v[34:35], off nt
	v_pk_mul_f32 v[44:45], v[22:23], v[56:57]
	v_pk_mul_f32 v[50:51], v[24:25], v[58:59]
	v_pk_mul_f32 v[52:53], v[18:19], v[60:61]
	v_pk_mul_f32 v[54:55], v[20:21], v[62:63]
	v_or_b32_e32 v38, 9, v28
	v_pk_fma_f32 v[50:51], v[16:17], v[66:67], v[50:51]
	v_pk_fma_f32 v[44:45], v[14:15], v[64:65], v[44:45]
	v_pk_fma_f32 v[54:55], v[12:13], v[70:71], v[54:55]
	v_pk_fma_f32 v[52:53], v[10:11], v[68:69], v[52:53]
	v_ashrrev_i32_e32 v39, 31, v38
	v_lshlrev_b64 v[38:39], 11, v[38:39]
	v_or_b32_e32 v38, v38, v26
	v_lshl_add_u64 v[40:41], s[6:7], 0, v[40:41]
	v_lshl_add_u64 v[42:43], s[34:35], 0, v[38:39]
	s_waitcnt vmcnt(1)
	v_lshlrev_b32_e32 v64, 16, v30
	v_and_b32_e32 v65, 0xffff0000, v30
	v_lshlrev_b32_e32 v66, 16, v31
	v_and_b32_e32 v67, 0xffff0000, v31
	v_lshlrev_b32_e32 v68, 16, v32
	v_and_b32_e32 v69, 0xffff0000, v32
	v_lshlrev_b32_e32 v70, 16, v33
	v_and_b32_e32 v71, 0xffff0000, v33
	s_waitcnt vmcnt(0)
	v_lshlrev_b32_e32 v30, 16, v34
	v_and_b32_e32 v31, 0xffff0000, v34
	v_lshlrev_b32_e32 v32, 16, v35
	v_and_b32_e32 v33, 0xffff0000, v35
	v_lshlrev_b32_e32 v34, 16, v36
	v_and_b32_e32 v35, 0xffff0000, v36
	v_lshlrev_b32_e32 v36, 16, v37
	v_and_b32_e32 v37, 0xffff0000, v37
	v_pk_fma_f32 v[44:45], v[6:7], v[64:65], v[44:45]
	v_pk_fma_f32 v[50:51], v[8:9], v[66:67], v[50:51]
	v_pk_fma_f32 v[52:53], v[2:3], v[68:69], v[52:53]
	v_pk_fma_f32 v[54:55], v[4:5], v[70:71], v[54:55]
	v_pk_mul_f32 v[32:33], v[50:51], v[32:33]
	v_pk_mul_f32 v[30:31], v[44:45], v[30:31]
	v_pk_mul_f32 v[36:37], v[54:55], v[36:37]
	v_pk_mul_f32 v[34:35], v[52:53], v[34:35]
	v_cvt_pk_bf16_f32 v30, v30, v31
	v_cvt_pk_bf16_f32 v31, v32, v33
	v_cvt_pk_bf16_f32 v32, v34, v35
	v_cvt_pk_bf16_f32 v33, v36, v37
	global_store_dwordx4 v[40:41], v[30:33], off
	global_load_dwordx4 v[30:33], v[42:43], off nt
	v_lshl_add_u64 v[34:35], s[4:5], 0, v[38:39]
	global_load_dwordx4 v[34:37], v[34:35], off nt
	v_pk_mul_f32 v[44:45], v[22:23], v[64:65]
	v_pk_mul_f32 v[50:51], v[24:25], v[66:67]
	v_pk_mul_f32 v[52:53], v[18:19], v[68:69]
	v_pk_mul_f32 v[54:55], v[20:21], v[70:71]
	v_or_b32_e32 v40, 10, v28
	v_pk_fma_f32 v[50:51], v[16:17], v[58:59], v[50:51]
	v_pk_fma_f32 v[44:45], v[14:15], v[56:57], v[44:45]
	v_pk_fma_f32 v[54:55], v[12:13], v[62:63], v[54:55]
	v_pk_fma_f32 v[52:53], v[10:11], v[60:61], v[52:53]
	v_ashrrev_i32_e32 v41, 31, v40
	v_lshlrev_b64 v[40:41], 11, v[40:41]
	v_or_b32_e32 v40, v40, v26
	v_lshl_add_u64 v[38:39], s[6:7], 0, v[38:39]
	v_lshl_add_u64 v[42:43], s[34:35], 0, v[40:41]
	s_waitcnt vmcnt(1)
	v_lshlrev_b32_e32 v56, 16, v30
	v_and_b32_e32 v57, 0xffff0000, v30
	v_lshlrev_b32_e32 v58, 16, v31
	v_and_b32_e32 v59, 0xffff0000, v31
	v_lshlrev_b32_e32 v60, 16, v32
	v_and_b32_e32 v61, 0xffff0000, v32
	v_lshlrev_b32_e32 v62, 16, v33
	v_and_b32_e32 v63, 0xffff0000, v33
	s_waitcnt vmcnt(0)
	v_lshlrev_b32_e32 v30, 16, v34
	v_and_b32_e32 v31, 0xffff0000, v34
	v_lshlrev_b32_e32 v32, 16, v35
	v_and_b32_e32 v33, 0xffff0000, v35
	v_lshlrev_b32_e32 v34, 16, v36
	v_and_b32_e32 v35, 0xffff0000, v36
	v_lshlrev_b32_e32 v36, 16, v37
	v_and_b32_e32 v37, 0xffff0000, v37
	v_pk_fma_f32 v[44:45], v[6:7], v[56:57], v[44:45]
	v_pk_fma_f32 v[50:51], v[8:9], v[58:59], v[50:51]
	v_pk_fma_f32 v[52:53], v[2:3], v[60:61], v[52:53]
	v_pk_fma_f32 v[54:55], v[4:5], v[62:63], v[54:55]
	v_pk_mul_f32 v[32:33], v[50:51], v[32:33]
	v_pk_mul_f32 v[30:31], v[44:45], v[30:31]
	v_pk_mul_f32 v[36:37], v[54:55], v[36:37]
	v_pk_mul_f32 v[34:35], v[52:53], v[34:35]
	v_cvt_pk_bf16_f32 v30, v30, v31
	v_cvt_pk_bf16_f32 v31, v32, v33
	v_cvt_pk_bf16_f32 v32, v34, v35
	v_cvt_pk_bf16_f32 v33, v36, v37
	global_store_dwordx4 v[38:39], v[30:33], off
	global_load_dwordx4 v[30:33], v[42:43], off nt
	v_lshl_add_u64 v[34:35], s[4:5], 0, v[40:41]
	global_load_dwordx4 v[34:37], v[34:35], off nt
	v_pk_mul_f32 v[44:45], v[22:23], v[56:57]
	v_pk_mul_f32 v[50:51], v[24:25], v[58:59]
	v_pk_mul_f32 v[52:53], v[18:19], v[60:61]
	v_pk_mul_f32 v[54:55], v[20:21], v[62:63]
	v_or_b32_e32 v38, 11, v28
	v_pk_fma_f32 v[50:51], v[16:17], v[66:67], v[50:51]
	v_pk_fma_f32 v[44:45], v[14:15], v[64:65], v[44:45]
	v_pk_fma_f32 v[54:55], v[12:13], v[70:71], v[54:55]
	v_pk_fma_f32 v[52:53], v[10:11], v[68:69], v[52:53]
	v_ashrrev_i32_e32 v39, 31, v38
	v_lshlrev_b64 v[38:39], 11, v[38:39]
	v_or_b32_e32 v38, v38, v26
	v_lshl_add_u64 v[40:41], s[6:7], 0, v[40:41]
	v_lshl_add_u64 v[42:43], s[34:35], 0, v[38:39]
	s_waitcnt vmcnt(1)
	v_lshlrev_b32_e32 v64, 16, v30
	v_and_b32_e32 v65, 0xffff0000, v30
	v_lshlrev_b32_e32 v66, 16, v31
	v_and_b32_e32 v67, 0xffff0000, v31
	v_lshlrev_b32_e32 v68, 16, v32
	v_and_b32_e32 v69, 0xffff0000, v32
	v_lshlrev_b32_e32 v70, 16, v33
	v_and_b32_e32 v71, 0xffff0000, v33
	s_waitcnt vmcnt(0)
	v_lshlrev_b32_e32 v30, 16, v34
	v_and_b32_e32 v31, 0xffff0000, v34
	v_lshlrev_b32_e32 v32, 16, v35
	v_and_b32_e32 v33, 0xffff0000, v35
	v_lshlrev_b32_e32 v34, 16, v36
	v_and_b32_e32 v35, 0xffff0000, v36
	v_lshlrev_b32_e32 v36, 16, v37
	v_and_b32_e32 v37, 0xffff0000, v37
	v_pk_fma_f32 v[44:45], v[6:7], v[64:65], v[44:45]
	v_pk_fma_f32 v[50:51], v[8:9], v[66:67], v[50:51]
	v_pk_fma_f32 v[52:53], v[2:3], v[68:69], v[52:53]
	v_pk_fma_f32 v[54:55], v[4:5], v[70:71], v[54:55]
	v_pk_mul_f32 v[32:33], v[50:51], v[32:33]
	v_pk_mul_f32 v[30:31], v[44:45], v[30:31]
	v_pk_mul_f32 v[36:37], v[54:55], v[36:37]
	v_pk_mul_f32 v[34:35], v[52:53], v[34:35]
	v_cvt_pk_bf16_f32 v30, v30, v31
	v_cvt_pk_bf16_f32 v31, v32, v33
	v_cvt_pk_bf16_f32 v32, v34, v35
	v_cvt_pk_bf16_f32 v33, v36, v37
	global_store_dwordx4 v[40:41], v[30:33], off
	global_load_dwordx4 v[30:33], v[42:43], off nt
	v_lshl_add_u64 v[34:35], s[4:5], 0, v[38:39]
	global_load_dwordx4 v[34:37], v[34:35], off nt
	v_pk_mul_f32 v[44:45], v[22:23], v[64:65]
	v_pk_mul_f32 v[50:51], v[24:25], v[66:67]
	v_pk_mul_f32 v[52:53], v[18:19], v[68:69]
	v_pk_mul_f32 v[54:55], v[20:21], v[70:71]
	v_or_b32_e32 v40, 12, v28
	v_pk_fma_f32 v[50:51], v[16:17], v[58:59], v[50:51]
	v_pk_fma_f32 v[44:45], v[14:15], v[56:57], v[44:45]
	v_pk_fma_f32 v[54:55], v[12:13], v[62:63], v[54:55]
	v_pk_fma_f32 v[52:53], v[10:11], v[60:61], v[52:53]
	v_ashrrev_i32_e32 v41, 31, v40
	v_lshlrev_b64 v[40:41], 11, v[40:41]
	v_or_b32_e32 v40, v40, v26
	v_lshl_add_u64 v[38:39], s[6:7], 0, v[38:39]
	v_lshl_add_u64 v[42:43], s[34:35], 0, v[40:41]
	s_waitcnt vmcnt(1)
	v_lshlrev_b32_e32 v56, 16, v30
	v_and_b32_e32 v57, 0xffff0000, v30
	v_lshlrev_b32_e32 v58, 16, v31
	v_and_b32_e32 v59, 0xffff0000, v31
	v_lshlrev_b32_e32 v60, 16, v32
	v_and_b32_e32 v61, 0xffff0000, v32
	v_lshlrev_b32_e32 v62, 16, v33
	v_and_b32_e32 v63, 0xffff0000, v33
	s_waitcnt vmcnt(0)
	v_lshlrev_b32_e32 v30, 16, v34
	v_and_b32_e32 v31, 0xffff0000, v34
	v_lshlrev_b32_e32 v32, 16, v35
	v_and_b32_e32 v33, 0xffff0000, v35
	v_lshlrev_b32_e32 v34, 16, v36
	v_and_b32_e32 v35, 0xffff0000, v36
	v_lshlrev_b32_e32 v36, 16, v37
	v_and_b32_e32 v37, 0xffff0000, v37
	v_pk_fma_f32 v[44:45], v[6:7], v[56:57], v[44:45]
	v_pk_fma_f32 v[50:51], v[8:9], v[58:59], v[50:51]
	v_pk_fma_f32 v[52:53], v[2:3], v[60:61], v[52:53]
	v_pk_fma_f32 v[54:55], v[4:5], v[62:63], v[54:55]
	v_pk_mul_f32 v[32:33], v[50:51], v[32:33]
	v_pk_mul_f32 v[30:31], v[44:45], v[30:31]
	v_pk_mul_f32 v[36:37], v[54:55], v[36:37]
	v_pk_mul_f32 v[34:35], v[52:53], v[34:35]
	v_cvt_pk_bf16_f32 v30, v30, v31
	v_cvt_pk_bf16_f32 v31, v32, v33
	v_cvt_pk_bf16_f32 v32, v34, v35
	v_cvt_pk_bf16_f32 v33, v36, v37
	global_store_dwordx4 v[38:39], v[30:33], off
	global_load_dwordx4 v[30:33], v[42:43], off nt
	v_lshl_add_u64 v[34:35], s[4:5], 0, v[40:41]
	global_load_dwordx4 v[34:37], v[34:35], off nt
	v_pk_mul_f32 v[44:45], v[22:23], v[56:57]
	v_pk_mul_f32 v[50:51], v[24:25], v[58:59]
	v_pk_mul_f32 v[52:53], v[18:19], v[60:61]
	v_pk_mul_f32 v[54:55], v[20:21], v[62:63]
	v_or_b32_e32 v38, 13, v28
	v_pk_fma_f32 v[50:51], v[16:17], v[66:67], v[50:51]
	v_pk_fma_f32 v[44:45], v[14:15], v[64:65], v[44:45]
	v_pk_fma_f32 v[54:55], v[12:13], v[70:71], v[54:55]
	v_pk_fma_f32 v[52:53], v[10:11], v[68:69], v[52:53]
	v_ashrrev_i32_e32 v39, 31, v38
	v_lshlrev_b64 v[38:39], 11, v[38:39]
	v_or_b32_e32 v38, v38, v26
	v_lshl_add_u64 v[40:41], s[6:7], 0, v[40:41]
	v_lshl_add_u64 v[42:43], s[34:35], 0, v[38:39]
	v_or_b32_e32 v28, 14, v28
	v_ashrrev_i32_e32 v29, 31, v28
	s_waitcnt vmcnt(1)
	v_lshlrev_b32_e32 v64, 16, v30
	v_and_b32_e32 v65, 0xffff0000, v30
	v_lshlrev_b32_e32 v66, 16, v31
	v_and_b32_e32 v67, 0xffff0000, v31
	v_lshlrev_b32_e32 v68, 16, v32
	v_and_b32_e32 v69, 0xffff0000, v32
	v_lshlrev_b32_e32 v70, 16, v33
	v_and_b32_e32 v71, 0xffff0000, v33
	s_waitcnt vmcnt(0)
	v_lshlrev_b32_e32 v30, 16, v34
	v_and_b32_e32 v31, 0xffff0000, v34
	v_lshlrev_b32_e32 v32, 16, v35
	v_and_b32_e32 v33, 0xffff0000, v35
	v_lshlrev_b32_e32 v34, 16, v36
	v_and_b32_e32 v35, 0xffff0000, v36
	v_lshlrev_b32_e32 v36, 16, v37
	v_and_b32_e32 v37, 0xffff0000, v37
	v_pk_fma_f32 v[44:45], v[6:7], v[64:65], v[44:45]
	v_pk_fma_f32 v[50:51], v[8:9], v[66:67], v[50:51]
	v_pk_fma_f32 v[52:53], v[2:3], v[68:69], v[52:53]
	v_pk_fma_f32 v[54:55], v[4:5], v[70:71], v[54:55]
	v_pk_mul_f32 v[32:33], v[50:51], v[32:33]
	v_pk_mul_f32 v[30:31], v[44:45], v[30:31]
	v_pk_mul_f32 v[36:37], v[54:55], v[36:37]
	v_pk_mul_f32 v[34:35], v[52:53], v[34:35]
	v_cvt_pk_bf16_f32 v30, v30, v31
	v_cvt_pk_bf16_f32 v31, v32, v33
	v_cvt_pk_bf16_f32 v32, v34, v35
	v_cvt_pk_bf16_f32 v33, v36, v37
	global_store_dwordx4 v[40:41], v[30:33], off
	global_load_dwordx4 v[30:33], v[42:43], off nt
	v_lshl_add_u64 v[34:35], s[4:5], 0, v[38:39]
	global_load_dwordx4 v[34:37], v[34:35], off nt
	v_lshlrev_b64 v[40:41], 11, v[28:29]
	v_pk_mul_f32 v[28:29], v[22:23], v[64:65]
	v_pk_mul_f32 v[44:45], v[24:25], v[66:67]
	v_pk_mul_f32 v[50:51], v[18:19], v[68:69]
	v_pk_mul_f32 v[52:53], v[20:21], v[70:71]
	v_pk_fma_f32 v[44:45], v[16:17], v[58:59], v[44:45]
	v_pk_fma_f32 v[28:29], v[14:15], v[56:57], v[28:29]
	v_pk_fma_f32 v[52:53], v[12:13], v[62:63], v[52:53]
	v_pk_fma_f32 v[50:51], v[10:11], v[60:61], v[50:51]
	v_or_b32_e32 v40, v40, v26
	v_lshl_add_u64 v[38:39], s[6:7], 0, v[38:39]
	v_lshl_add_u64 v[42:43], s[34:35], 0, v[40:41]
	s_waitcnt vmcnt(1)
	v_lshlrev_b32_e32 v54, 16, v30
	v_and_b32_e32 v55, 0xffff0000, v30
	v_lshlrev_b32_e32 v56, 16, v31
	v_and_b32_e32 v57, 0xffff0000, v31
	v_lshlrev_b32_e32 v58, 16, v32
	v_and_b32_e32 v59, 0xffff0000, v32
	v_lshlrev_b32_e32 v60, 16, v33
	v_and_b32_e32 v61, 0xffff0000, v33
	s_waitcnt vmcnt(0)
	v_lshlrev_b32_e32 v30, 16, v34
	v_and_b32_e32 v31, 0xffff0000, v34
	v_lshlrev_b32_e32 v32, 16, v35
	v_and_b32_e32 v33, 0xffff0000, v35
	v_lshlrev_b32_e32 v34, 16, v36
	v_and_b32_e32 v35, 0xffff0000, v36
	v_lshlrev_b32_e32 v36, 16, v37
	v_and_b32_e32 v37, 0xffff0000, v37
	v_pk_fma_f32 v[28:29], v[6:7], v[54:55], v[28:29]
	v_pk_fma_f32 v[44:45], v[8:9], v[56:57], v[44:45]
	v_pk_fma_f32 v[50:51], v[2:3], v[58:59], v[50:51]
	v_pk_fma_f32 v[52:53], v[4:5], v[60:61], v[52:53]
	v_pk_mul_f32 v[32:33], v[44:45], v[32:33]
	v_pk_mul_f32 v[28:29], v[28:29], v[30:31]
	v_pk_mul_f32 v[36:37], v[52:53], v[36:37]
	v_pk_mul_f32 v[30:31], v[50:51], v[34:35]
	v_cvt_pk_bf16_f32 v28, v28, v29
	v_cvt_pk_bf16_f32 v29, v32, v33
	v_cvt_pk_bf16_f32 v30, v30, v31
	v_cvt_pk_bf16_f32 v31, v36, v37
	global_store_dwordx4 v[38:39], v[28:31], off
	global_load_dwordx4 v[28:31], v[42:43], off nt
	v_lshl_add_u64 v[32:33], s[4:5], 0, v[40:41]
	global_load_dwordx4 v[32:35], v[32:33], off nt
	v_or_b32_e32 v36, 15, v48
	v_pk_mul_f32 v[42:43], v[22:23], v[54:55]
	v_pk_mul_f32 v[44:45], v[24:25], v[56:57]
	v_pk_mul_f32 v[48:49], v[18:19], v[58:59]
	v_pk_mul_f32 v[50:51], v[20:21], v[60:61]
	v_pk_fma_f32 v[44:45], v[16:17], v[66:67], v[44:45]
	v_pk_fma_f32 v[42:43], v[14:15], v[64:65], v[42:43]
	v_pk_fma_f32 v[50:51], v[12:13], v[70:71], v[50:51]
	v_pk_fma_f32 v[48:49], v[10:11], v[68:69], v[48:49]
	v_ashrrev_i32_e32 v37, 31, v36
	v_lshlrev_b64 v[36:37], 11, v[36:37]
	v_or_b32_e32 v36, v36, v26
	v_lshl_add_u64 v[38:39], s[6:7], 0, v[40:41]
	v_lshl_add_u64 v[40:41], s[34:35], 0, v[36:37]
	s_waitcnt vmcnt(1)
	v_lshlrev_b32_e32 v52, 16, v28
	v_and_b32_e32 v53, 0xffff0000, v28
	v_lshlrev_b32_e32 v62, 16, v29
	v_and_b32_e32 v63, 0xffff0000, v29
	v_lshlrev_b32_e32 v64, 16, v30
	v_and_b32_e32 v65, 0xffff0000, v30
	v_lshlrev_b32_e32 v66, 16, v31
	v_and_b32_e32 v67, 0xffff0000, v31
	s_waitcnt vmcnt(0)
	v_lshlrev_b32_e32 v28, 16, v32
	v_and_b32_e32 v29, 0xffff0000, v32
	v_lshlrev_b32_e32 v30, 16, v33
	v_and_b32_e32 v31, 0xffff0000, v33
	v_lshlrev_b32_e32 v32, 16, v34
	v_and_b32_e32 v33, 0xffff0000, v34
	v_lshlrev_b32_e32 v34, 16, v35
	v_and_b32_e32 v35, 0xffff0000, v35
	v_pk_fma_f32 v[42:43], v[6:7], v[52:53], v[42:43]
	v_pk_fma_f32 v[44:45], v[8:9], v[62:63], v[44:45]
	v_pk_fma_f32 v[48:49], v[2:3], v[64:65], v[48:49]
	v_pk_fma_f32 v[50:51], v[4:5], v[66:67], v[50:51]
	v_pk_mul_f32 v[30:31], v[44:45], v[30:31]
	v_pk_mul_f32 v[28:29], v[42:43], v[28:29]
	v_pk_mul_f32 v[34:35], v[50:51], v[34:35]
	v_pk_mul_f32 v[32:33], v[48:49], v[32:33]
	v_cvt_pk_bf16_f32 v28, v28, v29
	v_cvt_pk_bf16_f32 v29, v30, v31
	v_cvt_pk_bf16_f32 v30, v32, v33
	v_cvt_pk_bf16_f32 v31, v34, v35
	global_store_dwordx4 v[38:39], v[28:31], off
	global_load_dwordx4 v[28:31], v[40:41], off nt
	v_lshl_add_u64 v[32:33], s[4:5], 0, v[36:37]
	global_load_dwordx4 v[32:35], v[32:33], off nt
	v_pk_mul_f32 v[22:23], v[22:23], v[52:53]
	v_pk_mul_f32 v[24:25], v[24:25], v[62:63]
	v_pk_mul_f32 v[18:19], v[18:19], v[64:65]
	v_pk_mul_f32 v[20:21], v[20:21], v[66:67]
	v_pk_fma_f32 v[16:17], v[16:17], v[56:57], v[24:25]
	v_pk_fma_f32 v[14:15], v[14:15], v[54:55], v[22:23]
	v_pk_fma_f32 v[12:13], v[12:13], v[60:61], v[20:21]
	v_pk_fma_f32 v[10:11], v[10:11], v[58:59], v[18:19]
	v_lshl_add_u64 v[36:37], s[6:7], 0, v[36:37]
	s_waitcnt vmcnt(1)
	v_lshlrev_b32_e32 v18, 16, v28
	v_and_b32_e32 v19, 0xffff0000, v28
	v_lshlrev_b32_e32 v20, 16, v29
	v_and_b32_e32 v21, 0xffff0000, v29
	v_lshlrev_b32_e32 v22, 16, v30
	v_and_b32_e32 v23, 0xffff0000, v30
	v_lshlrev_b32_e32 v24, 16, v31
	v_and_b32_e32 v25, 0xffff0000, v31
	s_waitcnt vmcnt(0)
	v_lshlrev_b32_e32 v28, 16, v32
	v_and_b32_e32 v29, 0xffff0000, v32
	v_lshlrev_b32_e32 v30, 16, v33
	v_and_b32_e32 v31, 0xffff0000, v33
	v_lshlrev_b32_e32 v32, 16, v34
	v_and_b32_e32 v33, 0xffff0000, v34
	v_lshlrev_b32_e32 v34, 16, v35
	v_and_b32_e32 v35, 0xffff0000, v35
	v_pk_fma_f32 v[6:7], v[6:7], v[18:19], v[14:15]
	v_pk_fma_f32 v[8:9], v[8:9], v[20:21], v[16:17]
	v_pk_fma_f32 v[2:3], v[2:3], v[22:23], v[10:11]
	v_pk_fma_f32 v[4:5], v[4:5], v[24:25], v[12:13]
	v_pk_mul_f32 v[8:9], v[8:9], v[30:31]
	v_pk_mul_f32 v[6:7], v[6:7], v[28:29]
	v_pk_mul_f32 v[10:11], v[4:5], v[34:35]
	v_pk_mul_f32 v[4:5], v[2:3], v[32:33]
	v_cvt_pk_bf16_f32 v2, v6, v7
	v_cvt_pk_bf16_f32 v3, v8, v9
	v_cvt_pk_bf16_f32 v4, v4, v5
	v_cvt_pk_bf16_f32 v5, v10, v11
	global_store_dwordx4 v[36:37], v[2:5], off
	s_andn2_b64 exec, exec, s[12:13]
	s_cbranch_execz .LBB0_275
.LBB0_273:
	v_and_b32_e32 v26, 0x3f8, v47
	v_readlane_b32 s36, v254, 21
	v_lshlrev_b32_e32 v6, 2, v26
	v_readlane_b32 s50, v254, 35
	v_readlane_b32 s51, v254, 36
	s_nop 4
	global_load_dwordx4 v[10:13], v6, s[50:51] offset:16 nt
	global_load_dwordx4 v[14:17], v6, s[50:51] nt
	global_load_dwordx4 v[18:21], v6, s[8:9] offset:16 nt
	global_load_dwordx4 v[22:25], v6, s[8:9] nt
	global_load_dwordx4 v[2:5], v6, s[10:11] offset:16 nt
	s_nop 0
	global_load_dwordx4 v[6:9], v6, s[10:11] nt
	v_ashrrev_i32_e32 v48, 3, v46
	v_and_b32_e32 v28, -16, v48
	v_cmp_lt_i32_e32 vcc, 15, v48
	v_ashrrev_i32_e32 v29, 31, v28
	v_lshlrev_b32_e32 v26, 1, v26
	v_mov_b32_e32 v30, 0
	v_mov_b32_e32 v31, 0
	v_mov_b32_e32 v34, 0
	v_mov_b32_e32 v35, 0
	v_mov_b32_e32 v32, 0
	v_mov_b32_e32 v33, 0
	v_mov_b32_e32 v36, 0
	v_mov_b32_e32 v37, 0
	v_mov_b32_e32 v40, 0
	v_mov_b32_e32 v41, 0
	v_mov_b32_e32 v38, 0
	v_mov_b32_e32 v39, 0
	v_mov_b32_e32 v42, 0
	v_mov_b32_e32 v43, 0
	v_mov_b32_e32 v44, 0
	v_mov_b32_e32 v45, 0
	v_readlane_b32 s37, v254, 22
	v_readlane_b32 s38, v254, 23
	v_readlane_b32 s39, v254, 24
	v_readlane_b32 s40, v254, 25
	v_readlane_b32 s41, v254, 26
	v_readlane_b32 s42, v254, 27
	v_readlane_b32 s43, v254, 28
	v_readlane_b32 s44, v254, 29
	v_readlane_b32 s45, v254, 30
	v_readlane_b32 s46, v254, 31
	v_readlane_b32 s47, v254, 32
	v_readlane_b32 s48, v254, 33
	v_readlane_b32 s49, v254, 34
	s_and_saveexec_b64 s[14:15], vcc
	s_cbranch_execz .LBB0_272
	v_add_u32_e32 v34, -1, v28
	v_mov_b32_e32 v35, v27
	v_lshlrev_b64 v[30:31], 11, v[28:29]
	v_lshlrev_b64 v[34:35], 11, v[34:35]
	v_lshl_add_u64 v[30:31], s[34:35], 0, v[30:31]
	v_lshl_add_u64 v[34:35], s[34:35], 0, v[34:35]
	v_lshl_add_u64 v[30:31], v[30:31], 0, v[26:27]
	v_lshl_add_u64 v[34:35], v[34:35], 0, v[26:27]
	global_load_dwordx4 v[30:33], v[30:31], off offset:-4096 nt
	s_nop 0
	global_load_dwordx4 v[50:53], v[34:35], off nt
	s_waitcnt vmcnt(0)
	v_lshlrev_b32_e32 v42, 16, v30
	v_and_b32_e32 v43, 0xffff0000, v30
	v_lshlrev_b32_e32 v44, 16, v31
	v_and_b32_e32 v45, 0xffff0000, v31
	v_lshlrev_b32_e32 v40, 16, v32
	v_and_b32_e32 v41, 0xffff0000, v32
	v_lshlrev_b32_e32 v38, 16, v33
	v_and_b32_e32 v39, 0xffff0000, v33
	v_lshlrev_b32_e32 v32, 16, v50
	v_and_b32_e32 v33, 0xffff0000, v50
	v_lshlrev_b32_e32 v36, 16, v51
	v_and_b32_e32 v37, 0xffff0000, v51
	v_lshlrev_b32_e32 v30, 16, v52
	v_and_b32_e32 v31, 0xffff0000, v52
	v_lshlrev_b32_e32 v34, 16, v53
	v_and_b32_e32 v35, 0xffff0000, v53
	s_branch .LBB0_272

.LBB0_436:
	s_cmp_lt_i32 s96, s2
	s_cselect_b64 s[0:1], -1, 0
	s_xor_b64 s[6:7], s[4:5], -1
	s_and_b64 s[0:1], s[6:7], s[0:1]
	s_and_b64 vcc, exec, s[0:1]
	s_cbranch_vccnz .LBB0_539
.Lp4_pe:
	s_add_u32 s12, s78, 0x580000
	s_addc_u32 s13, s79, 0
	s_and_b64 s[0:1], s[4:5], exec
	s_cselect_b32 s0, 0, 0xffffff80
	s_add_i32 s2, s0, s3
	s_add_i32 s24, s0, s96
	v_and_b32_e32 v1, 0x3ff, v0
	v_bfe_u32 v142, v0, 5, 5
	v_readfirstlane_b32 s0, v1
	s_cmp_eq_u32 s98, 0
	s_cbranch_scc1 .LBB0_457
	s_cmpk_gt_u32 s24, 0xff
	v_lshlrev_b32_e32 v143, 4, v1
	s_cbranch_scc1 .LBB0_457
	v_lshrrev_b32_e32 v4, 1, v1
	v_and_b32_e32 v2, 4, v142
	v_bfe_u32 v3, v1, 2, 2
	v_and_b32_e32 v10, 24, v4
	v_or3_b32 v2, v2, v3, v10
	v_add_u32_e32 v3, 0x2000, v143
	v_and_b32_e32 v5, 32, v1
	v_lshrrev_b32_e32 v3, 7, v3
	s_movk_i32 s4, 0xe0
	v_bitop3_b32 v5, v143, v5, 48 bitop3:0x6c
	v_and_or_b32 v4, v3, s4, v2
	v_and_or_b32 v5, v1, 64, v5
	v_lshl_or_b32 v130, v4, 9, v5
	v_bfe_u32 v4, v1, 2, 4
	s_movk_i32 s4, 0xf0
	v_and_or_b32 v3, v3, s4, v4
	v_lshl_or_b32 v132, v3, 9, v5
	v_lshrrev_b32_e32 v3, 3, v1
	s_movk_i32 s4, 0x60
	s_add_u32 s25, s78, 0x3200000
	v_and_or_b32 v2, v3, s4, v2
	s_movk_i32 s4, 0x70
	s_addc_u32 s26, s79, 0
	v_lshl_or_b32 v134, v2, 9, v5
	v_and_or_b32 v2, v3, s4, v4
	s_lshl_b32 s4, s96, 3
	s_and_b32 s4, s4, 56
	s_bfe_u32 s5, s24, 0x30003
	s_lshr_b32 s8, s0, 6
	s_or_b32 s91, s4, s5
	s_bfe_u32 s6, s24, 0x50006
	s_lshr_b32 s1, s0, 8
	s_lshl_b32 s27, s8, 10
	s_lshl_b32 s7, s91, 17
	s_lshl_b32 s4, s6, 17
	s_add_u32 s22, s12, s4
	s_addc_u32 s23, s13, 0
	s_add_i32 s80, s27, 0
	s_add_i32 m0, s80, 0x10000
	v_lshl_or_b32 v136, v2, 9, v5
	global_load_lds_dwordx4 v134, s[22:23]
	s_add_i32 m0, s80, 0x12000
	s_add_u32 s4, s22, 0x10000
	global_load_lds_dwordx4 v130, s[22:23]
	s_addc_u32 s5, s23, 0
	s_add_i32 m0, s80, 0x14000
	v_mov_b32_e32 v135, 0
	global_load_lds_dwordx4 v134, s[4:5]
	s_add_i32 m0, s80, 0x16000
	s_add_u32 s28, s25, s7
	s_addc_u32 s29, s26, 0
	s_add_i32 s82, s80, 0x2000
	global_load_lds_dwordx4 v130, s[4:5]
	s_mov_b32 m0, s80
	s_add_u32 s4, s28, 0x10000
	global_load_lds_dwordx4 v136, s[28:29]
	s_mov_b32 m0, s82
	s_addc_u32 s5, s29, 0
	s_add_i32 s83, s80, 0x4000
	global_load_lds_dwordx4 v132, s[28:29]
	s_mov_b32 m0, s83
	s_add_i32 s84, s80, 0x6000
	global_load_lds_dwordx4 v136, s[4:5]
	s_mov_b32 m0, s84
	v_mov_b32_e32 v131, v135
	global_load_lds_dwordx4 v132, s[4:5]
	v_mov_b32_e32 v137, v135
	v_mov_b32_e32 v133, v135
	s_cmp_eq_u32 s1, 1
	s_mov_b64 s[36:37], s[92:93]
	v_lshl_add_u64 v[8:9], s[22:23], 0, v[134:135]
	v_lshl_add_u64 v[6:7], s[22:23], 0, v[130:131]
	v_lshl_add_u64 v[2:3], s[28:29], 0, v[136:137]
	s_cselect_b64 s[4:5], -1, 0
	s_cmp_lg_u32 s1, 1
	v_lshl_add_u64 v[4:5], s[28:29], 0, v[132:133]
	s_cbranch_scc1 .LBB0_440
	s_barrier

.LBB0_453:
	v_lshl_add_u32 v150, s91, 8, v144
	v_lshl_or_b32 v152, s92, 8, v146
	v_ashrrev_i32_e32 v151, 31, v150
	v_ashrrev_i32_e32 v153, 31, v152
	v_cvt_pk_bf16_f32 v126, v126, v127
	v_cvt_pk_bf16_f32 v127, v128, v129
	v_cvt_pk_bf16_f32 v128, v122, v123
	v_lshlrev_b64 v[122:123], 11, v[150:151]
	v_cvt_pk_bf16_f32 v129, v124, v125
	v_lshl_add_u64 v[122:123], s[6:7], 0, v[122:123]
	v_lshlrev_b64 v[124:125], 1, v[152:153]
	v_lshl_add_u64 v[122:123], v[122:123], 0, v[124:125]
	v_cvt_pk_bf16_f32 v110, v110, v111
	v_cvt_pk_bf16_f32 v111, v112, v113
	v_cvt_pk_bf16_f32 v112, v106, v107
	v_cvt_pk_bf16_f32 v113, v108, v109
	global_store_dwordx4 v[122:123], v[110:113], off offset:256 sc1
	v_cvt_pk_bf16_f32 v94, v94, v95
	v_cvt_pk_bf16_f32 v95, v96, v97
	v_or_b32_e32 v110, 16, v150
	v_ashrrev_i32_e32 v111, 31, v110
	v_lshlrev_b64 v[110:111], 11, v[110:111]
	v_lshl_add_u64 v[110:111], s[6:7], 0, v[110:111]
	v_lshl_add_u64 v[110:111], v[110:111], 0, v[124:125]
	v_cvt_pk_bf16_f32 v96, v90, v91
	v_cvt_pk_bf16_f32 v97, v92, v93
	s_mov_b64 s[10:11], 0x40000
	global_store_dwordx4 v[110:111], v[94:97], off offset:256 sc1
	v_cvt_pk_bf16_f32 v62, v62, v63
	v_cvt_pk_bf16_f32 v63, v64, v65
	v_or_b32_e32 v94, 32, v150
	v_cvt_pk_bf16_f32 v64, v58, v59
	v_lshl_add_u64 v[58:59], v[122:123], 0, s[10:11]
	s_mov_b32 s10, 0x40000
	v_ashrrev_i32_e32 v95, 31, v94
	v_cvt_pk_bf16_f32 v65, v60, v61
	v_add_co_u32_e32 v60, vcc, s10, v122
	v_cvt_pk_bf16_f32 v46, v46, v47
	v_cvt_pk_bf16_f32 v47, v48, v49
	v_cvt_pk_bf16_f32 v48, v42, v43
	v_cvt_pk_bf16_f32 v49, v44, v45
	s_mov_b64 s[10:11], 0x48000
	v_lshlrev_b64 v[94:95], 11, v[94:95]
	v_addc_co_u32_e32 v61, vcc, 0, v123, vcc
	global_store_dwordx4 v[58:59], v[46:49], off offset:256 sc1
	v_lshl_add_u64 v[94:95], s[6:7], 0, v[94:95]
	v_cvt_pk_bf16_f32 v30, v30, v31
	v_lshl_add_u64 v[46:47], v[122:123], 0, s[10:11]
	s_mov_b32 s10, 0x48000
	v_add_co_u32_e32 v48, vcc, s10, v122
	v_cvt_pk_bf16_f32 v31, v32, v33
	v_cvt_pk_bf16_f32 v32, v26, v27
	v_cvt_pk_bf16_f32 v33, v28, v29
	s_mov_b64 s[10:11], 0x50000
	v_lshl_add_u64 v[94:95], v[94:95], 0, v[124:125]
	v_cvt_pk_bf16_f32 v78, v78, v79
	v_cvt_pk_bf16_f32 v79, v80, v81
	v_cvt_pk_bf16_f32 v80, v74, v75
	v_cvt_pk_bf16_f32 v81, v76, v77
	v_addc_co_u32_e32 v49, vcc, 0, v123, vcc
	global_store_dwordx4 v[46:47], v[30:33], off offset:256 sc1
	global_store_dwordx4 v[94:95], v[78:81], off offset:256 sc1
	v_cvt_pk_bf16_f32 v14, v14, v15
	v_lshl_add_u64 v[30:31], v[122:123], 0, s[10:11]
	s_mov_b32 s10, 0x50000
	v_or_b32_e32 v78, 48, v150
	v_add_co_u32_e32 v32, vcc, s10, v122
	v_cvt_pk_bf16_f32 v15, v16, v17
	v_cvt_pk_bf16_f32 v16, v10, v11
	v_cvt_pk_bf16_f32 v17, v12, v13
	s_mov_b64 s[10:11], 0x58000
	v_ashrrev_i32_e32 v79, 31, v78
	v_addc_co_u32_e32 v33, vcc, 0, v123, vcc
	global_store_dwordx4 v[30:31], v[14:17], off offset:256 sc1
	v_lshlrev_b64 v[78:79], 11, v[78:79]
	v_lshl_add_u64 v[78:79], s[6:7], 0, v[78:79]
	v_lshl_add_u64 v[14:15], v[122:123], 0, s[10:11]
	s_mov_b32 s10, 0x58000
	v_add_co_u32_e32 v16, vcc, s10, v122
	v_cvt_pk_bf16_f32 v106, v118, v119
	s_nop 0
	v_addc_co_u32_e32 v17, vcc, 0, v123, vcc
	v_cvt_pk_bf16_f32 v107, v120, v121
	v_cvt_pk_bf16_f32 v108, v114, v115
	v_cvt_pk_bf16_f32 v109, v116, v117
	v_cvt_pk_bf16_f32 v90, v102, v103
	v_cvt_pk_bf16_f32 v91, v104, v105
	v_cvt_pk_bf16_f32 v92, v98, v99
	v_cvt_pk_bf16_f32 v93, v100, v101
	v_cvt_pk_bf16_f32 v74, v86, v87
	v_cvt_pk_bf16_f32 v75, v88, v89
	v_cvt_pk_bf16_f32 v76, v82, v83
	v_cvt_pk_bf16_f32 v77, v84, v85
	v_lshl_add_u64 v[78:79], v[78:79], 0, v[124:125]
	v_cvt_pk_bf16_f32 v70, v70, v71
	v_cvt_pk_bf16_f32 v71, v72, v73
	v_cvt_pk_bf16_f32 v72, v66, v67
	v_cvt_pk_bf16_f32 v73, v68, v69
	v_cvt_pk_bf16_f32 v42, v54, v55
	v_cvt_pk_bf16_f32 v43, v56, v57
	v_cvt_pk_bf16_f32 v44, v50, v51
	v_cvt_pk_bf16_f32 v45, v52, v53
	v_cvt_pk_bf16_f32 v26, v38, v39
	v_cvt_pk_bf16_f32 v27, v40, v41
	v_cvt_pk_bf16_f32 v28, v34, v35
	v_cvt_pk_bf16_f32 v29, v36, v37
	v_cvt_pk_bf16_f32 v10, v22, v23
	v_cvt_pk_bf16_f32 v11, v24, v25
	v_cvt_pk_bf16_f32 v12, v18, v19
	v_cvt_pk_bf16_f32 v13, v20, v21
	v_cvt_pk_bf16_f32 v6, v6, v7
	v_cvt_pk_bf16_f32 v7, v8, v9
	v_cvt_pk_bf16_f32 v8, v2, v3
	v_cvt_pk_bf16_f32 v9, v4, v5
	s_andn2_b64 vcc, exec, s[0:1]
	s_mov_b64 s[0:1], -1
	v_readlane_b32 s96, v254, 37
	global_store_dwordx4 v[122:123], v[126:129], off sc1
	global_store_dwordx4 v[110:111], v[106:109], off sc1
	global_store_dwordx4 v[94:95], v[90:93], off sc1
	global_store_dwordx4 v[78:79], v[74:77], off sc1
	global_store_dwordx4 v[78:79], v[70:73], off offset:256 sc1
	global_store_dwordx4 v[60:61], v[62:65], off sc1
	global_store_dwordx4 v[48:49], v[42:45], off sc1
	global_store_dwordx4 v[32:33], v[26:29], off sc1
	global_store_dwordx4 v[16:17], v[10:13], off sc1
	global_store_dwordx4 v[14:15], v[6:9], off offset:256 sc1
	s_cbranch_vccnz .LBB0_442
	s_andn2_b64 vcc, exec, s[4:5]
	s_cbranch_vccnz .LBB0_441
	s_barrier
	s_branch .LBB0_441

.LBB0_457:
	s_waitcnt vmcnt(0)
	s_barrier
	s_cmp_eq_u32 s98, 1
	s_cbranch_scc1 .Lp4_resume
	s_cmpk_gt_i32 s24, 0xef
	s_cbranch_scc1 .LBB0_539
	v_lshlrev_b32_e32 v3, 3, v1
	v_and_b32_e32 v4, 0xf8, v3
	v_mul_u32_u24_e32 v5, 0x41, v4
	v_lshlrev_b32_e32 v5, 2, v5
	v_lshlrev_b32_e32 v6, 2, v142
	v_add_u32_e32 v7, 0, v5
	v_add3_u32 v26, 0, v6, v5
	v_add_u32_e32 v27, v7, v6
	v_add_u32_e32 v6, 0x200, v1
	v_lshrrev_b32_e32 v28, 5, v6
	v_lshlrev_b32_e32 v6, 2, v28
	s_add_u32 s14, s78, 0x600000
	v_add3_u32 v29, 0, v6, v5
	v_add_u32_e32 v30, v7, v6
	v_add_u32_e32 v6, 0x600, v1
	s_addc_u32 s15, s79, 0
	v_lshrrev_b32_e32 v32, 5, v6
	s_add_u32 s16, s78, 0x380000
	v_lshlrev_b32_e32 v6, 2, v32
	s_addc_u32 s17, s79, 0
	v_add3_u32 v33, 0, v6, v5
	v_add_u32_e32 v34, v7, v6
	v_not_b32_e32 v6, v1
	s_add_u32 s20, s78, 0x180000
	v_lshlrev_b32_e32 v6, 2, v6
	s_addc_u32 s21, s79, 0
	v_and_b32_e32 v6, 0xf8, v6
	s_add_u32 s22, s78, 0x80000
	v_add_u32_e32 v37, 0, v6
	v_lshlrev_b32_e32 v6, 6, v1
	s_addc_u32 s23, s79, 0
	v_mov_b32_e32 v11, 0
	v_add_u32_e32 v35, 0, v3
	s_movk_i32 s4, 0x78
	v_and_b32_e32 v6, 64, v6
	v_and_b32_e32 v10, 0x3f0, v143
	s_add_u32 s28, s78, 0x800000
	v_mul_u32_u24_e32 v5, 0x78, v1
	v_mad_u32_u24 v8, v1, s4, v35
	v_add_u32_e32 v38, 0, v6
	v_lshl_add_u64 v[6:7], s[78:79], 0, v[10:11]
	s_mov_b64 s[4:5], 0x2a00000
	s_addc_u32 s29, s79, 0
	v_mul_u32_u24_e32 v9, 0x88, v1
	v_bfe_u32 v36, v1, 4, 2
	v_lshl_add_u64 v[12:13], v[6:7], 0, s[4:5]
	v_add3_u32 v3, v5, v3, 0
	s_movk_i32 s4, 0x4200
	s_add_u32 s34, s78, 0x1600000
	v_add_u32_e32 v39, 0x200, v3
	v_add3_u32 v40, v3, v9, s4
	v_lshl_add_u32 v3, v36, 9, 0
	v_lshrrev_b32_e32 v24, 6, v1
	s_addc_u32 s35, s79, 0
	v_add_u32_e32 v43, 0x2200, v3
	v_lshl_add_u32 v3, v228, 3, 0
	v_and_b32_e32 v2, 63, v1
	s_add_u32 s90, s78, 0xe800000
	v_add_u32_e32 v44, 0x200, v3
	v_lshl_add_u32 v3, v24, 3, 0
	s_mov_b32 s31, 0
	v_lshl_add_u32 v25, v2, 2, 0
	v_or_b32_e32 v31, 32, v142
	s_addc_u32 s91, s79, 0
	v_cmp_gt_u32_e64 s[0:1], 64, v1
	v_add_u32_e32 v41, 0x2200, v35
	v_add_u32_e32 v42, 0xfffffe00, v1
	v_add_u32_e32 v45, 0x4200, v3
	v_lshlrev_b32_e32 v14, 2, v2
	v_lshlrev_b32_e32 v16, 1, v4
	s_mov_b32 s25, 0x3fb8aa3b
	s_mov_b32 s60, 0xc2ce8ed0
	s_mov_b32 s61, 0x42b17218
	s_mov_b32 s62, 0xfe5163ab
	s_mov_b32 s63, 0x3c439041
	s_mov_b32 s81, 0xdb629599
	s_mov_b32 s82, 0xf534ddc0
	s_mov_b32 s83, 0xfc2757d1
	s_mov_b32 s84, 0x4e441529
	s_mov_b32 s85, 0xa2f9836e
	s_mov_b32 s86, 0x3fc90fda
	s_mov_b32 s87, 0xbfc90fda
	v_mov_b32_e32 v46, 0x3c0881c4
	v_mov_b32_e32 v47, 0xbab64f3b
	v_add_u32_e32 v48, v8, v9
	s_mov_b64 s[52:53], 0x800
	v_mov_b32_e32 v49, 0x7f800000
	v_not_b32_e32 v50, 63
	v_not_b32_e32 v51, 31
	v_mov_b32_e32 v52, 0x7fc00000
	s_mov_b32 s88, s96
	s_branch .LBB0_460

.LBB0_589:
	s_cmp_gt_i32 s26, 4
	s_cselect_b64 s[4:5], -1, 0
	s_xor_b64 s[0:1], s[0:1], -1
	s_or_b64 s[0:1], s[4:5], s[0:1]
	s_and_b64 vcc, exec, s[0:1]
	s_cbranch_vccnz .LBB0_771
	s_cmpk_lt_i32 s96, 0x80
	s_cbranch_scc1 .Lp4_resume
	s_cmp_eq_u32 s98, 1
	s_cbranch_scc1 .Lp4_resume
	s_mov_b32 s98, 1
	s_mov_b64 s[4:5], 0
	s_branch .Lp4_pe
.Lp4_resume:
	v_and_b32_e32 v231, 0x3ff, v0
	v_lshlrev_b32_e32 v1, 4, v231
	v_and_b32_e32 v2, 32, v0
	v_bitop3_b32 v229, v1, v2, 48 bitop3:0x6c
	v_lshrrev_b32_e32 v2, 5, v0
	v_lshrrev_b32_e32 v4, 1, v0
	v_and_b32_e32 v2, 4, v2
	v_bfe_u32 v3, v231, 2, 2
	v_and_b32_e32 v236, 24, v4
	v_bfe_u32 v232, v231, 2, 4
	v_and_b32_e32 v230, 64, v0
	v_or3_b32 v2, v2, v3, v236
	v_bfe_u32 v0, v0, 3, 7
	v_or_b32_e32 v233, 0x2000, v1
	v_and_or_b32 v240, v0, 48, v232
	v_and_or_b32 v241, v0, 32, v2
	v_lshrrev_b32_e32 v0, 7, v233
	s_movk_i32 s1, 0x70
	v_and_or_b32 v243, v0, s1, v232
	s_movk_i32 s1, 0x60
	v_and_or_b32 v242, v0, s1, v2
	v_lshlrev_b32_e32 v0, 6, v231
	s_add_u32 s4, s76, 0x1000000
	v_and_b32_e32 v234, 0x3c0, v0
	v_lshlrev_b32_e32 v0, 2, v231
	s_addc_u32 s40, s77, 0
	v_or_b32_e32 v239, v229, v230
	v_lshlrev_b32_e32 v237, 1, v236
	v_and_b32_e32 v235, 32, v0
	v_readfirstlane_b32 s0, v231
	v_lshl_or_b32 v208, v240, 10, v239
	v_lshl_or_b32 v210, v241, 10, v239
	v_lshl_or_b32 v212, v243, 10, v239
	v_lshl_or_b32 v214, v242, 10, v239
	s_cmpk_gt_u32 s96, 0x7f
	v_bitop3_b32 v238, v237, v235, v234 bitop3:0x36
	s_cbranch_scc1 .LBB0_610
	s_lshl_b32 s2, s96, 3
	s_and_b32 s2, s2, 56
	s_bfe_u32 s6, s96, 0x30003
	s_lshr_b32 s5, s0, 6
	s_or_b32 s2, s2, s6
	s_bfe_u32 s6, s96, 0x50006
	s_lshr_b32 s1, s0, 8
	s_lshl_b32 s33, s5, 10
	s_lshl_b32 s7, s2, 18
	s_lshl_b32 s8, s6, 18
	s_add_u32 s36, s78, s8
	s_addc_u32 s37, s79, 0
	s_add_i32 s41, s33, 0
	s_add_i32 m0, s41, 0x10000
	v_mov_b32_e32 v211, 0
	global_load_lds_dwordx4 v210, s[36:37]
	s_add_i32 m0, s41, 0x12000
	s_add_u32 s8, s36, 0x20000
	global_load_lds_dwordx4 v214, s[36:37]
	s_addc_u32 s9, s37, 0
	s_add_i32 m0, s41, 0x14000
	v_mov_b32_e32 v215, v211
	global_load_lds_dwordx4 v210, s[8:9]
	s_add_i32 m0, s41, 0x16000
	s_add_u32 s34, s76, s7
	s_addc_u32 s35, s77, 0
	s_add_i32 s42, s41, 0x2000
	global_load_lds_dwordx4 v214, s[8:9]
	s_mov_b32 m0, s41
	s_add_u32 s8, s34, 0x20000
	global_load_lds_dwordx4 v208, s[34:35]
	s_mov_b32 m0, s42
	s_addc_u32 s9, s35, 0
	s_add_i32 s43, s41, 0x4000
	global_load_lds_dwordx4 v212, s[34:35]
	s_mov_b32 m0, s43
	s_add_i32 s44, s41, 0x6000
	global_load_lds_dwordx4 v208, s[8:9]
	s_mov_b32 m0, s44
	v_mov_b32_e32 v209, v211
	global_load_lds_dwordx4 v212, s[8:9]
	v_mov_b32_e32 v213, v211
	s_cmp_eq_u32 s1, 1
	s_mov_b32 s45, 0
	v_lshl_add_u64 v[6:7], s[36:37], 0, v[210:211]
	v_lshl_add_u64 v[2:3], s[36:37], 0, v[214:215]
	s_mov_b64 s[8:9], 0x20000
	v_lshl_add_u64 v[0:1], s[34:35], 0, v[208:209]
	s_cselect_b64 s[10:11], -1, 0
	s_cmp_lg_u32 s1, 1
	v_lshl_add_u64 v[4:5], s[34:35], 0, v[212:213]
	s_cbranch_scc1 .LBB0_593
	s_barrier

	.amdhsa_kernel _Z10hybrid_fwd6Params
		.amdhsa_group_segment_fixed_size 0
		.amdhsa_private_segment_fixed_size 0
		.amdhsa_kernarg_size 456
		.amdhsa_user_sgpr_count 2
		.amdhsa_user_sgpr_dispatch_ptr 0
		.amdhsa_user_sgpr_queue_ptr 0
		.amdhsa_user_sgpr_kernarg_segment_ptr 1
		.amdhsa_user_sgpr_dispatch_id 0
		.amdhsa_user_sgpr_kernarg_preload_length 0
		.amdhsa_user_sgpr_kernarg_preload_offset 0
		.amdhsa_user_sgpr_private_segment_size 0
		.amdhsa_uses_dynamic_stack 0
		.amdhsa_enable_private_segment 0
		.amdhsa_system_sgpr_workgroup_id_x 1
		.amdhsa_system_sgpr_workgroup_id_y 0
		.amdhsa_system_sgpr_workgroup_id_z 0
		.amdhsa_system_sgpr_workgroup_info 0
		.amdhsa_system_vgpr_workitem_id 2
		.amdhsa_next_free_vgpr 255
		.amdhsa_next_free_sgpr 99
		.amdhsa_accum_offset 256
		.amdhsa_reserve_vcc 1
		.amdhsa_float_round_mode_32 0
		.amdhsa_float_round_mode_16_64 0
		.amdhsa_float_denorm_mode_32 3
		.amdhsa_float_denorm_mode_16_64 3
		.amdhsa_dx10_clamp 1
		.amdhsa_ieee_mode 1
		.amdhsa_fp16_overflow 0
		.amdhsa_tg_split 0
		.amdhsa_exception_fp_ieee_invalid_op 0
		.amdhsa_exception_fp_denorm_src 0
		.amdhsa_exception_fp_ieee_div_zero 0
		.amdhsa_exception_fp_ieee_overflow 0
		.amdhsa_exception_fp_ieee_underflow 0
		.amdhsa_exception_fp_ieee_inexact 0
		.amdhsa_exception_int_div_zero 0
	.end_amdhsa_kernel

amdhsa.kernels:
  - .agpr_count:     0
    .args:
      - .offset:         0
        .size:           200
        .value_kind:     by_value
      - .offset:         200
        .size:           4
        .value_kind:     hidden_block_count_x
      - .offset:         204
        .size:           4
        .value_kind:     hidden_block_count_y
      - .offset:         208
        .size:           4
        .value_kind:     hidden_block_count_z
      - .offset:         212
        .size:           2
        .value_kind:     hidden_group_size_x
      - .offset:         214
        .size:           2
        .value_kind:     hidden_group_size_y
      - .offset:         216
        .size:           2
        .value_kind:     hidden_group_size_z
      - .offset:         218
        .size:           2
        .value_kind:     hidden_remainder_x
      - .offset:         220
        .size:           2
        .value_kind:     hidden_remainder_y
      - .offset:         222
        .size:           2
        .value_kind:     hidden_remainder_z
      - .offset:         240
        .size:           8
        .value_kind:     hidden_global_offset_x
      - .offset:         248
        .size:           8
        .value_kind:     hidden_global_offset_y
      - .offset:         256
        .size:           8
        .value_kind:     hidden_global_offset_z
      - .offset:         264
        .size:           2
        .value_kind:     hidden_grid_dims
      - .offset:         288
        .size:           8
        .value_kind:     hidden_multigrid_sync_arg
      - .offset:         320
        .size:           4
        .value_kind:     hidden_dynamic_lds_size
    .group_segment_fixed_size: 0
    .kernarg_segment_align: 8
    .kernarg_segment_size: 456
    .language:       OpenCL C
    .language_version:
      - 2
      - 0
    .max_flat_workgroup_size: 512
    .name:           _Z10hybrid_fwd6Params
    .private_segment_fixed_size: 0
    .sgpr_count:     105
    .sgpr_spill_count: 55
    .symbol:         _Z10hybrid_fwd6Params.kd
    .uniform_work_group_size: 1
    .uses_dynamic_stack: false
    .vgpr_count:     255
    .vgpr_spill_count: 0
    .wavefront_size: 64
